# K-loop L-phase: LDS-DMA in saddr form (SGPR base + 32-bit VGPR offset), all 64-bit VALU address adds removed or moved to SALU, LDS base adds hoisted out of the loop
# speedup vs baseline: 1.0146x; 1.0069x over previous
;     __device__ bool next(int i, Unit& u) const { const bool ok = StaticOrder::next(i, u); u.pm = 0; u.pn = 0; return ok; }
; #define PG8_STAGE(bufoff, gbase, voff) do { _Pragma("unroll") for (int _i = 0; _i < 2; ++_i) \
;         __builtin_amdgcn_global_load_lds((const unsigned*)((const char*)(gbase) + (voff)[_i]), (PG8_LAS unsigned*)(lds + (bufoff) + ldsw + _i * 8192), 16, 0, 0); } while (0)
; #define PG8_LDA(dst, b, h) do { _Pragma("unroll") for (int m = 0; m < 4; ++m) _Pragma("unroll") for (int k = 0; k < 2; ++k) dst[m][k] = *(const PG8_LAS bf16x8*)(lds + PG8_SA(b, h) + aoff + m * 2048 + k * 1024); } while (0)
; #define PG8_LDB(dst, b, h) do { _Pragma("unroll") for (int n = 0; n < 2; ++n) _Pragma("unroll") for (int k = 0; k < 2; ++k) dst[n][k] = *(const PG8_LAS bf16x8*)(lds + PG8_SB(b, h) + boff + n * 2048 + k * 1024); } while (0)
; #define PG8_SCHED __builtin_amdgcn_sched_barrier(0)
; template <class Epi, class Sched, bool ALIGN_EPI = false, bool SP2 = false>
; __device__ __forceinline__ void gemm_phase(PG8_LAS unsigned char* lds, const Gemm g, const Sched& S, const Epi& E, const int wid) {
;     ...
;         const bool has_next = S.next(ui + 1, nxt);
;         const char* nA = has_next ? (const char*)g.A + (size_t)nxt.pm * tstep + (size_t)nxt.kb * kstep : cA; const char* nB = has_next ? (const char*)g.Bt + (size_t)nxt.pn * tstep + (size_t)nxt.kb * kstep : cB;
;         for (int t = 0; t < nt; t += 2) {
;             const bool last = (t == nt - 2);
;             const char* a1 = cA + (size_t)(t + 1) * kstep;
;             const char* a2 = last ? nA : cA + (size_t)(t + 2) * kstep; const char* b2 = last ? nB : cB + (size_t)(t + 2) * kstep;
;             const char* a3 = a2 + kstep; const char* b3 = b2 + kstep;
;             if (last && has_next) S.a_ready(nxt);
;             if constexpr (SP2) {
;             PG8_LDB(B0, 0, 0); PG8_LDB(B1, 0, 1); PG8_SCHED; PG8_LDA(At, 0, 0); PG8_STAGE(PG8_SA(1, 1), a1 + hstep, voffA);
;     ...
; #pragma unroll
;         for (int a = 0; a < 2; ++a)
; #pragma unroll
;             for (int b = 0; b < 2; ++b)
; #pragma unroll
;                 for (int m = 0; m < 4; ++m)
; #pragma unroll
;                     for (int n = 0; n < 2; ++n) acc[a][b][m][n] = (f32x4){0.f, 0.f, 0.f, 0.f};
;         cur = nxt; cA = nA; cB = nB; ++ui; nt = cur.kn;
.LBB0_248:
	v_lshl_add_u32 v244, s20, 8, v157
	v_ashrrev_i32_e32 v245, 31, v244
	v_lshl_add_u64 v[244:245], v[244:245], 3, s[4:5]
	global_load_dwordx2 v[230:231], v[244:245], off
	global_load_dwordx2 v[232:233], v[244:245], off offset:128
	global_load_dwordx2 v[234:235], v[244:245], off offset:256
	global_load_dwordx2 v[236:237], v[244:245], off offset:384
	global_load_dwordx2 v[238:239], v[244:245], off offset:1024
	global_load_dwordx2 v[240:241], v[244:245], off offset:1152
	global_load_dwordx2 v[242:243], v[244:245], off offset:1280
	global_load_dwordx2 v[244:245], v[244:245], off offset:1408
	s_ashr_i32 s15, s14, 31
	s_lshl_b64 s[16:17], s[14:15], 21
	s_add_u32 s16, s78, s16
	s_addc_u32 s17, s79, s17
	s_and_b64 s[18:19], s[0:1], exec
	s_cselect_b32 s15, s17, s23
	s_cselect_b32 s21, s16, s22
	s_ashr_i32 s13, s12, 31
	s_lshl_b64 s[18:19], s[12:13], 21
	s_add_u32 s18, s82, s18
	s_addc_u32 s19, s83, s19
	s_and_b64 s[26:27], s[0:1], exec
	s_cselect_b32 s13, s19, s25
	s_cselect_b32 s45, s18, s24
	s_add_u32 s22, s22, 0x100080
	s_addc_u32 s23, s23, 0
	s_add_u32 s46, s24, 0x100
	v_mov_b32_e32 v0, 0
	s_addc_u32 s47, s25, 0
	s_mov_b32 s48, -2
	v_mov_b32_e32 v1, v0
	v_mov_b32_e32 v2, v0
	v_mov_b32_e32 v3, v0
	v_mov_b32_e32 v4, v0
	v_mov_b32_e32 v5, v0
	v_mov_b32_e32 v6, v0
	v_mov_b32_e32 v7, v0
	s_waitcnt vmcnt(0)
	v_mov_b32_e32 v16, v0
	v_mov_b32_e32 v17, v0
	v_mov_b32_e32 v18, v0
	v_mov_b32_e32 v19, v0
	v_mov_b32_e32 v20, v0
	v_mov_b32_e32 v21, v0
	v_mov_b32_e32 v22, v0
	v_mov_b32_e32 v23, v0
	v_mov_b32_e32 v32, v0
	v_mov_b32_e32 v33, v0
	v_mov_b32_e32 v34, v0
	v_mov_b32_e32 v35, v0
	v_mov_b32_e32 v36, v0
	v_mov_b32_e32 v37, v0
	v_mov_b32_e32 v38, v0
	v_mov_b32_e32 v39, v0
	v_mov_b32_e32 v48, v0
	v_mov_b32_e32 v49, v0
	v_mov_b32_e32 v50, v0
	v_mov_b32_e32 v51, v0
	v_mov_b32_e32 v52, v0
	v_mov_b32_e32 v53, v0
	v_mov_b32_e32 v54, v0
	v_mov_b32_e32 v55, v0
	v_mov_b32_e32 v8, v0
	v_mov_b32_e32 v9, v0
	v_mov_b32_e32 v10, v0
	v_mov_b32_e32 v11, v0
	v_mov_b32_e32 v12, v0
	v_mov_b32_e32 v13, v0
	v_mov_b32_e32 v14, v0
	v_mov_b32_e32 v15, v0
	v_mov_b32_e32 v24, v0
	v_mov_b32_e32 v25, v0
	v_mov_b32_e32 v26, v0
	v_mov_b32_e32 v27, v0
	v_mov_b32_e32 v28, v0
	v_mov_b32_e32 v29, v0
	v_mov_b32_e32 v30, v0
	v_mov_b32_e32 v31, v0
	v_mov_b32_e32 v40, v0
	v_mov_b32_e32 v41, v0
	v_mov_b32_e32 v42, v0
	v_mov_b32_e32 v43, v0
	v_mov_b32_e32 v44, v0
	v_mov_b32_e32 v45, v0
	v_mov_b32_e32 v46, v0
	v_mov_b32_e32 v47, v0
	v_mov_b32_e32 v56, v0
	v_mov_b32_e32 v57, v0
	v_mov_b32_e32 v58, v0
	v_mov_b32_e32 v59, v0
	v_mov_b32_e32 v60, v0
	v_mov_b32_e32 v61, v0
	v_mov_b32_e32 v62, v0
	v_mov_b32_e32 v63, v0
	v_mov_b32_e32 v64, v0
	v_mov_b32_e32 v65, v0
	v_mov_b32_e32 v66, v0
	v_mov_b32_e32 v67, v0
	v_mov_b32_e32 v68, v0
	v_mov_b32_e32 v69, v0
	v_mov_b32_e32 v70, v0
	v_mov_b32_e32 v71, v0
	v_mov_b32_e32 v80, v0
	v_mov_b32_e32 v81, v0
	v_mov_b32_e32 v82, v0
	v_mov_b32_e32 v83, v0
	v_mov_b32_e32 v84, v0
	v_mov_b32_e32 v85, v0
	v_mov_b32_e32 v86, v0
	v_mov_b32_e32 v87, v0
	v_mov_b32_e32 v96, v0
	v_mov_b32_e32 v97, v0
	v_mov_b32_e32 v98, v0
	v_mov_b32_e32 v99, v0
	v_mov_b32_e32 v100, v0
	v_mov_b32_e32 v101, v0
	v_mov_b32_e32 v102, v0
	v_mov_b32_e32 v103, v0
	v_mov_b32_e32 v112, v0
	v_mov_b32_e32 v113, v0
	v_mov_b32_e32 v114, v0
	v_mov_b32_e32 v115, v0
	v_mov_b32_e32 v116, v0
	v_mov_b32_e32 v117, v0
	v_mov_b32_e32 v118, v0
	v_mov_b32_e32 v119, v0
	v_mov_b32_e32 v72, v0
	v_mov_b32_e32 v73, v0
	v_mov_b32_e32 v74, v0
	v_mov_b32_e32 v75, v0
	v_mov_b32_e32 v76, v0
	v_mov_b32_e32 v77, v0
	v_mov_b32_e32 v78, v0
	v_mov_b32_e32 v79, v0
	v_mov_b32_e32 v88, v0
	v_mov_b32_e32 v89, v0
	v_mov_b32_e32 v90, v0
	v_mov_b32_e32 v91, v0
	v_mov_b32_e32 v92, v0
	v_mov_b32_e32 v93, v0
	v_mov_b32_e32 v94, v0
	v_mov_b32_e32 v95, v0
	v_mov_b32_e32 v104, v0
	v_mov_b32_e32 v105, v0
	v_mov_b32_e32 v106, v0
	v_mov_b32_e32 v107, v0
	v_mov_b32_e32 v108, v0
	v_mov_b32_e32 v109, v0
	v_mov_b32_e32 v110, v0
	v_mov_b32_e32 v111, v0
	v_mov_b32_e32 v120, v0
	v_mov_b32_e32 v121, v0
	v_mov_b32_e32 v122, v0
	v_mov_b32_e32 v123, v0
	v_mov_b32_e32 v124, v0
	v_mov_b32_e32 v125, v0
	v_mov_b32_e32 v126, v0
	v_mov_b32_e32 v127, v0
	v_add_u32_e32 v246, 0x18000, v158
	v_add_u32_e32 v248, 0x1c000, v158
.LBB0_249:
	ds_read_b128 v[148:151], v160
	ds_read_b128 v[152:155], v160 offset:1024
	ds_read_b128 v[164:167], v160 offset:2048
	ds_read_b128 v[168:171], v160 offset:3072
	ds_read_b128 v[172:175], v161
	ds_read_b128 v[176:179], v161 offset:1024
	ds_read_b128 v[180:183], v161 offset:2048
	ds_read_b128 v[184:187], v161 offset:3072
	s_add_u32 s24, s22, 0xfff00080
	s_addc_u32 s25, s23, -1
	s_cmp_eq_u32 s48, 60
	s_cselect_b32 s27, s15, s25
	s_cselect_b32 s26, s21, s24
	s_cselect_b32 s25, s13, s47
	s_cselect_b32 s24, s45, s46
	s_add_i32 m0, s30, 0xc000
	ds_read_b128 v[188:191], v162
	ds_read_b128 v[192:195], v162 offset:1024
	ds_read_b128 v[196:199], v162 offset:2048
	ds_read_b128 v[200:203], v162 offset:3072
	ds_read_b128 v[204:207], v162 offset:4096
	ds_read_b128 v[208:211], v162 offset:5120
	ds_read_b128 v[212:215], v162 offset:6144
	ds_read_b128 v[216:219], v162 offset:7168
	global_load_lds_dwordx4 v140, s[22:23]
	s_add_i32 m0, s30, 0xe000
	s_nop 0
	global_load_lds_dwordx4 v142, s[22:23]
	s_waitcnt vmcnt(8)
	s_waitcnt lgkmcnt(0)
	s_setprio 1
	s_barrier
; #define PG8_STAGE(bufoff, gbase, voff) do { _Pragma("unroll") for (int _i = 0; _i < 2; ++_i) \
;         __builtin_amdgcn_global_load_lds((const unsigned*)((const char*)(gbase) + (voff)[_i]), (PG8_LAS unsigned*)(lds + (bufoff) + ldsw + _i * 8192), 16, 0, 0); } while (0)
; #define PG8_LDA(dst, b, h) do { _Pragma("unroll") for (int m = 0; m < 4; ++m) _Pragma("unroll") for (int k = 0; k < 2; ++k) dst[m][k] = *(const PG8_LAS bf16x8*)(lds + PG8_SA(b, h) + aoff + m * 2048 + k * 1024); } while (0)
; #define PG8_MMA(ai, bj, At, Bt) do { __builtin_amdgcn_s_setprio(1); _Pragma("unroll") for (int m = 0; m < 4; ++m) _Pragma("unroll") for (int n = 0; n < 2; ++n) _Pragma("unroll") for (int k = 0; k < 2; ++k) \
;         acc[ai][bj][m][n] = __builtin_amdgcn_mfma_f32_16x16x32_bf16(Bt[n][k], At[m][k], acc[ai][bj][m][n], 0, 0, 0); __builtin_amdgcn_s_setprio(0); } while (0)
; #define PG8_WAIT_V(n) asm volatile("s_waitcnt vmcnt(" #n ")" ::: "memory")
; #define PG8_WAIT_L(n) asm volatile("s_waitcnt lgkmcnt(" #n ")" ::: "memory")
; #define PG8_BAR __builtin_amdgcn_s_barrier()
; #define PG8_SCHED __builtin_amdgcn_sched_barrier(0)
; template <class Epi, class Sched, bool ALIGN_EPI = false, bool SP2 = false>
; __device__ __forceinline__ void gemm_phase(PG8_LAS unsigned char* lds, const Gemm g, const Sched& S, const Epi& E, const int wid) {
;     ...
;             PG8_WAIT_V(8); PG8_WAIT_L(0); PG8_BAR; PG8_MMA(0, 0, At, B0); PG8_MMA(0, 1, At, B1); PG8_BAR; PG8_SCHED;
;             PG8_LDA(At, 0, 1); PG8_STAGE(PG8_SB(0, 0), b2, voffB); PG8_STAGE(PG8_SB(0, 1), b2 + hstep, voffB); PG8_STAGE(PG8_SA(0, 0), a2, voffA);
;             PG8_WAIT_V(8); PG8_WAIT_L(0); PG8_BAR; PG8_MMA(1, 0, At, B0); PG8_MMA(1, 1, At, B1); PG8_BAR; PG8_SCHED;
	v_mfma_f32_16x16x32_bf16 v[124:127], v[148:151], v[188:191], v[124:127]
	v_mfma_f32_16x16x32_bf16 v[120:123], v[164:167], v[188:191], v[120:123]
	v_mfma_f32_16x16x32_bf16 v[108:111], v[148:151], v[196:199], v[108:111]
	v_mfma_f32_16x16x32_bf16 v[104:107], v[164:167], v[196:199], v[104:107]
	v_mfma_f32_16x16x32_bf16 v[92:95], v[148:151], v[204:207], v[92:95]
	v_mfma_f32_16x16x32_bf16 v[88:91], v[164:167], v[204:207], v[88:91]
	v_mfma_f32_16x16x32_bf16 v[76:79], v[148:151], v[212:215], v[76:79]
	v_mfma_f32_16x16x32_bf16 v[72:75], v[164:167], v[212:215], v[72:75]
	v_mfma_f32_16x16x32_bf16 v[124:127], v[152:155], v[192:195], v[124:127]
	v_mfma_f32_16x16x32_bf16 v[120:123], v[168:171], v[192:195], v[120:123]
	v_mfma_f32_16x16x32_bf16 v[108:111], v[152:155], v[200:203], v[108:111]
	v_mfma_f32_16x16x32_bf16 v[104:107], v[168:171], v[200:203], v[104:107]
	v_mfma_f32_16x16x32_bf16 v[92:95], v[152:155], v[208:211], v[92:95]
	v_mfma_f32_16x16x32_bf16 v[88:91], v[168:171], v[208:211], v[88:91]
	v_mfma_f32_16x16x32_bf16 v[76:79], v[152:155], v[216:219], v[76:79]
	v_mfma_f32_16x16x32_bf16 v[72:75], v[168:171], v[216:219], v[72:75]
	v_mfma_f32_16x16x32_bf16 v[116:119], v[172:175], v[188:191], v[116:119]
	v_mfma_f32_16x16x32_bf16 v[112:115], v[180:183], v[188:191], v[112:115]
	v_mfma_f32_16x16x32_bf16 v[100:103], v[172:175], v[196:199], v[100:103]
	v_mfma_f32_16x16x32_bf16 v[96:99], v[180:183], v[196:199], v[96:99]
	v_mfma_f32_16x16x32_bf16 v[84:87], v[172:175], v[204:207], v[84:87]
	v_mfma_f32_16x16x32_bf16 v[80:83], v[180:183], v[204:207], v[80:83]
	v_mfma_f32_16x16x32_bf16 v[68:71], v[172:175], v[212:215], v[68:71]
	v_mfma_f32_16x16x32_bf16 v[64:67], v[180:183], v[212:215], v[64:67]
	v_mfma_f32_16x16x32_bf16 v[116:119], v[176:179], v[192:195], v[116:119]
	v_mfma_f32_16x16x32_bf16 v[112:115], v[184:187], v[192:195], v[112:115]
	v_mfma_f32_16x16x32_bf16 v[100:103], v[176:179], v[200:203], v[100:103]
	v_mfma_f32_16x16x32_bf16 v[96:99], v[184:187], v[200:203], v[96:99]
	v_mfma_f32_16x16x32_bf16 v[84:87], v[176:179], v[208:211], v[84:87]
	v_mfma_f32_16x16x32_bf16 v[80:83], v[184:187], v[208:211], v[80:83]
	v_mfma_f32_16x16x32_bf16 v[68:71], v[176:179], v[216:219], v[68:71]
	v_mfma_f32_16x16x32_bf16 v[64:67], v[184:187], v[216:219], v[64:67]
	s_barrier
	s_setprio 0
	s_add_i32 s49, s40, s29
	s_mov_b32 m0, s49
	ds_read_b128 v[188:191], v162 offset:16384
	ds_read_b128 v[192:195], v162 offset:17408
	ds_read_b128 v[196:199], v162 offset:18432
	ds_read_b128 v[200:203], v162 offset:19456
	ds_read_b128 v[204:207], v162 offset:20480
	ds_read_b128 v[208:211], v162 offset:21504
	ds_read_b128 v[212:215], v162 offset:22528
	ds_read_b128 v[216:219], v162 offset:23552
	global_load_lds_dwordx4 v130, s[24:25]
	s_add_i32 m0, s49, 0x2000
	s_add_u32 s50, s24, 0x100000
	s_addc_u32 s51, s25, 0
	s_add_i32 s49, s41, s29
	global_load_lds_dwordx4 v134, s[24:25]
	s_mov_b32 m0, s49
	global_load_lds_dwordx4 v130, s[50:51]
	s_add_i32 m0, s49, 0x2000
	s_nop 0
	global_load_lds_dwordx4 v134, s[50:51]
	s_mov_b32 m0, s30
	s_nop 0
	global_load_lds_dwordx4 v128, s[26:27]
	s_mov_b32 m0, s31
	s_nop 0
	global_load_lds_dwordx4 v132, s[26:27]
	s_waitcnt vmcnt(8)
	s_waitcnt lgkmcnt(0)
	s_setprio 1
	s_barrier
	v_mfma_f32_16x16x32_bf16 v[60:63], v[148:151], v[188:191], v[60:63]
	v_mfma_f32_16x16x32_bf16 v[56:59], v[164:167], v[188:191], v[56:59]
	v_mfma_f32_16x16x32_bf16 v[44:47], v[148:151], v[196:199], v[44:47]
	v_mfma_f32_16x16x32_bf16 v[40:43], v[164:167], v[196:199], v[40:43]
	v_mfma_f32_16x16x32_bf16 v[28:31], v[148:151], v[204:207], v[28:31]
	v_mfma_f32_16x16x32_bf16 v[24:27], v[164:167], v[204:207], v[24:27]
	v_mfma_f32_16x16x32_bf16 v[12:15], v[148:151], v[212:215], v[12:15]
	v_mfma_f32_16x16x32_bf16 v[8:11], v[164:167], v[212:215], v[8:11]
	v_mfma_f32_16x16x32_bf16 v[60:63], v[152:155], v[192:195], v[60:63]
	v_mfma_f32_16x16x32_bf16 v[56:59], v[168:171], v[192:195], v[56:59]
	v_mfma_f32_16x16x32_bf16 v[44:47], v[152:155], v[200:203], v[44:47]
	v_mfma_f32_16x16x32_bf16 v[40:43], v[168:171], v[200:203], v[40:43]
	v_mfma_f32_16x16x32_bf16 v[28:31], v[152:155], v[208:211], v[28:31]
	v_mfma_f32_16x16x32_bf16 v[24:27], v[168:171], v[208:211], v[24:27]
	v_mfma_f32_16x16x32_bf16 v[12:15], v[152:155], v[216:219], v[12:15]
	v_mfma_f32_16x16x32_bf16 v[8:11], v[168:171], v[216:219], v[8:11]
	v_mfma_f32_16x16x32_bf16 v[52:55], v[172:175], v[188:191], v[52:55]
	v_mfma_f32_16x16x32_bf16 v[48:51], v[180:183], v[188:191], v[48:51]
	v_mfma_f32_16x16x32_bf16 v[36:39], v[172:175], v[196:199], v[36:39]
	v_mfma_f32_16x16x32_bf16 v[32:35], v[180:183], v[196:199], v[32:35]
	v_mfma_f32_16x16x32_bf16 v[20:23], v[172:175], v[204:207], v[20:23]
	v_mfma_f32_16x16x32_bf16 v[16:19], v[180:183], v[204:207], v[16:19]
	v_mfma_f32_16x16x32_bf16 v[4:7], v[172:175], v[212:215], v[4:7]
	v_mfma_f32_16x16x32_bf16 v[0:3], v[180:183], v[212:215], v[0:3]
	v_mfma_f32_16x16x32_bf16 v[52:55], v[176:179], v[192:195], v[52:55]
	v_mfma_f32_16x16x32_bf16 v[48:51], v[184:187], v[192:195], v[48:51]
	v_mfma_f32_16x16x32_bf16 v[36:39], v[176:179], v[200:203], v[36:39]
	v_mfma_f32_16x16x32_bf16 v[32:35], v[184:187], v[200:203], v[32:35]
	v_mfma_f32_16x16x32_bf16 v[20:23], v[176:179], v[208:211], v[20:23]
	v_mfma_f32_16x16x32_bf16 v[16:19], v[184:187], v[208:211], v[16:19]
	v_mfma_f32_16x16x32_bf16 v[4:7], v[176:179], v[216:219], v[4:7]
	v_mfma_f32_16x16x32_bf16 v[0:3], v[184:187], v[216:219], v[0:3]
	s_barrier
; #define PG8_STAGE(bufoff, gbase, voff) do { _Pragma("unroll") for (int _i = 0; _i < 2; ++_i) \
;         __builtin_amdgcn_global_load_lds((const unsigned*)((const char*)(gbase) + (voff)[_i]), (PG8_LAS unsigned*)(lds + (bufoff) + ldsw + _i * 8192), 16, 0, 0); } while (0)
; #define PG8_LDA(dst, b, h) do { _Pragma("unroll") for (int m = 0; m < 4; ++m) _Pragma("unroll") for (int k = 0; k < 2; ++k) dst[m][k] = *(const PG8_LAS bf16x8*)(lds + PG8_SA(b, h) + aoff + m * 2048 + k * 1024); } while (0)
; #define PG8_LDB(dst, b, h) do { _Pragma("unroll") for (int n = 0; n < 2; ++n) _Pragma("unroll") for (int k = 0; k < 2; ++k) dst[n][k] = *(const PG8_LAS bf16x8*)(lds + PG8_SB(b, h) + boff + n * 2048 + k * 1024); } while (0)
; #define PG8_MMA(ai, bj, At, Bt) do { __builtin_amdgcn_s_setprio(1); _Pragma("unroll") for (int m = 0; m < 4; ++m) _Pragma("unroll") for (int n = 0; n < 2; ++n) _Pragma("unroll") for (int k = 0; k < 2; ++k) \
;         acc[ai][bj][m][n] = __builtin_amdgcn_mfma_f32_16x16x32_bf16(Bt[n][k], At[m][k], acc[ai][bj][m][n], 0, 0, 0); __builtin_amdgcn_s_setprio(0); } while (0)
; #define PG8_WAIT_V(n) asm volatile("s_waitcnt vmcnt(" #n ")" ::: "memory")
; #define PG8_WAIT_L(n) asm volatile("s_waitcnt lgkmcnt(" #n ")" ::: "memory")
; #define PG8_BAR __builtin_amdgcn_s_barrier()
; #define PG8_SCHED __builtin_amdgcn_sched_barrier(0)
; template <class Epi, class Sched, bool ALIGN_EPI = false, bool SP2 = false>
; __device__ __forceinline__ void gemm_phase(PG8_LAS unsigned char* lds, const Gemm g, const Sched& S, const Epi& E, const int wid) {
;     ...
;         for (int t = 0; t < nt; t += 2) {
;             const bool last = (t == nt - 2);
;     ...
;             PG8_LDB(B0, 1, 0); PG8_LDB(B1, 1, 1); PG8_SCHED; PG8_LDA(At, 1, 0); PG8_STAGE(PG8_SA(0, 1), a2 + hstep, voffA);
;             PG8_WAIT_V(8); PG8_WAIT_L(0); PG8_BAR; PG8_MMA(0, 0, At, B0); PG8_MMA(0, 1, At, B1); PG8_BAR; PG8_SCHED;
;             PG8_LDA(At, 1, 1); PG8_STAGE(PG8_SB(1, 0), b3, voffB); PG8_STAGE(PG8_SB(1, 1), b3 + hstep, voffB); PG8_STAGE(PG8_SA(1, 0), a3, voffA);
;             PG8_WAIT_V(8); PG8_WAIT_L(0); PG8_BAR; PG8_MMA(1, 0, At, B0); PG8_MMA(1, 1, At, B1); PG8_BAR; PG8_SCHED;
	s_setprio 0
	s_add_i32 s49, 0, 0x18000
	s_add_i32 s50, 0, 0x1c000
	ds_read_b128 v[148:151], v246
	ds_read_b128 v[152:155], v246 offset:1024
	ds_read_b128 v[164:167], v246 offset:2048
	ds_read_b128 v[168:171], v246 offset:3072
	ds_read_b128 v[172:175], v248
	ds_read_b128 v[176:179], v248 offset:1024
	ds_read_b128 v[180:183], v248 offset:2048
	ds_read_b128 v[184:187], v248 offset:3072
	s_add_u32 s26, s26, 0x100000
	s_addc_u32 s27, s27, 0
	s_mov_b32 m0, s34
	ds_read_b128 v[188:191], v162 offset:32768
	ds_read_b128 v[192:195], v162 offset:33792
	ds_read_b128 v[196:199], v162 offset:34816
	ds_read_b128 v[200:203], v162 offset:35840
	ds_read_b128 v[204:207], v162 offset:36864
	ds_read_b128 v[208:211], v162 offset:37888
	ds_read_b128 v[212:215], v162 offset:38912
	ds_read_b128 v[216:219], v162 offset:39936
	global_load_lds_dwordx4 v128, s[26:27]
	s_mov_b32 m0, s35
	s_nop 0
	global_load_lds_dwordx4 v132, s[26:27]
	s_waitcnt vmcnt(8)
	s_waitcnt lgkmcnt(0)
	s_setprio 1
	s_barrier
	v_mfma_f32_16x16x32_bf16 v[124:127], v[148:151], v[188:191], v[124:127]
	v_mfma_f32_16x16x32_bf16 v[120:123], v[164:167], v[188:191], v[120:123]
	v_mfma_f32_16x16x32_bf16 v[108:111], v[148:151], v[196:199], v[108:111]
	v_mfma_f32_16x16x32_bf16 v[104:107], v[164:167], v[196:199], v[104:107]
	v_mfma_f32_16x16x32_bf16 v[92:95], v[148:151], v[204:207], v[92:95]
	v_mfma_f32_16x16x32_bf16 v[88:91], v[164:167], v[204:207], v[88:91]
	v_mfma_f32_16x16x32_bf16 v[76:79], v[148:151], v[212:215], v[76:79]
	v_mfma_f32_16x16x32_bf16 v[72:75], v[164:167], v[212:215], v[72:75]
	v_mfma_f32_16x16x32_bf16 v[124:127], v[152:155], v[192:195], v[124:127]
	v_mfma_f32_16x16x32_bf16 v[120:123], v[168:171], v[192:195], v[120:123]
	v_mfma_f32_16x16x32_bf16 v[108:111], v[152:155], v[200:203], v[108:111]
	v_mfma_f32_16x16x32_bf16 v[104:107], v[168:171], v[200:203], v[104:107]
	v_mfma_f32_16x16x32_bf16 v[92:95], v[152:155], v[208:211], v[92:95]
	v_mfma_f32_16x16x32_bf16 v[88:91], v[168:171], v[208:211], v[88:91]
	v_mfma_f32_16x16x32_bf16 v[76:79], v[152:155], v[216:219], v[76:79]
	v_mfma_f32_16x16x32_bf16 v[72:75], v[168:171], v[216:219], v[72:75]
	v_mfma_f32_16x16x32_bf16 v[116:119], v[172:175], v[188:191], v[116:119]
	v_mfma_f32_16x16x32_bf16 v[112:115], v[180:183], v[188:191], v[112:115]
	v_mfma_f32_16x16x32_bf16 v[100:103], v[172:175], v[196:199], v[100:103]
	v_mfma_f32_16x16x32_bf16 v[96:99], v[180:183], v[196:199], v[96:99]
	v_mfma_f32_16x16x32_bf16 v[84:87], v[172:175], v[204:207], v[84:87]
	v_mfma_f32_16x16x32_bf16 v[80:83], v[180:183], v[204:207], v[80:83]
	v_mfma_f32_16x16x32_bf16 v[68:71], v[172:175], v[212:215], v[68:71]
	v_mfma_f32_16x16x32_bf16 v[64:67], v[180:183], v[212:215], v[64:67]
	v_mfma_f32_16x16x32_bf16 v[116:119], v[176:179], v[192:195], v[116:119]
	v_mfma_f32_16x16x32_bf16 v[112:115], v[184:187], v[192:195], v[112:115]
	v_mfma_f32_16x16x32_bf16 v[100:103], v[176:179], v[200:203], v[100:103]
	v_mfma_f32_16x16x32_bf16 v[96:99], v[184:187], v[200:203], v[96:99]
	v_mfma_f32_16x16x32_bf16 v[84:87], v[176:179], v[208:211], v[84:87]
	v_mfma_f32_16x16x32_bf16 v[80:83], v[184:187], v[208:211], v[80:83]
	v_mfma_f32_16x16x32_bf16 v[68:71], v[176:179], v[216:219], v[68:71]
	v_mfma_f32_16x16x32_bf16 v[64:67], v[184:187], v[216:219], v[64:67]
	s_barrier
	s_setprio 0
	s_add_u32 s98, s24, 0x80
	s_addc_u32 s99, s25, 0
	s_add_u32 s100, s26, 0xfff00080
	s_addc_u32 s101, s27, -1
	s_add_i32 s26, s49, s29
	s_mov_b32 m0, s26
	ds_read_b128 v[188:191], v162 offset:49152
	ds_read_b128 v[192:195], v162 offset:50176
	ds_read_b128 v[196:199], v162 offset:51200
	ds_read_b128 v[200:203], v162 offset:52224
	ds_read_b128 v[204:207], v162 offset:53248
	ds_read_b128 v[208:211], v162 offset:54272
	ds_read_b128 v[212:215], v162 offset:55296
	ds_read_b128 v[216:219], v162 offset:56320
	global_load_lds_dwordx4 v130, s[98:99]
	s_add_i32 m0, s26, 0x2000
	s_add_u32 s24, s24, 0x100080
	s_addc_u32 s25, s25, 0
	s_add_i32 s26, s50, s29
	global_load_lds_dwordx4 v134, s[98:99]
	s_mov_b32 m0, s26
	s_nop 0
	global_load_lds_dwordx4 v130, s[24:25]
	s_add_i32 m0, s26, 0x2000
	s_nop 0
	global_load_lds_dwordx4 v134, s[24:25]
	s_mov_b32 m0, s37
	s_nop 0
	global_load_lds_dwordx4 v128, s[100:101]
	s_mov_b32 m0, s38
	s_nop 0
	global_load_lds_dwordx4 v132, s[100:101]
	s_waitcnt vmcnt(8)
	s_waitcnt lgkmcnt(0)
	s_setprio 1
	s_barrier
	v_mfma_f32_16x16x32_bf16 v[60:63], v[148:151], v[188:191], v[60:63]
	v_mfma_f32_16x16x32_bf16 v[56:59], v[164:167], v[188:191], v[56:59]
	v_mfma_f32_16x16x32_bf16 v[44:47], v[148:151], v[196:199], v[44:47]
	v_mfma_f32_16x16x32_bf16 v[40:43], v[164:167], v[196:199], v[40:43]
	v_mfma_f32_16x16x32_bf16 v[28:31], v[148:151], v[204:207], v[28:31]
	v_mfma_f32_16x16x32_bf16 v[24:27], v[164:167], v[204:207], v[24:27]
	v_mfma_f32_16x16x32_bf16 v[12:15], v[148:151], v[212:215], v[12:15]
	v_mfma_f32_16x16x32_bf16 v[8:11], v[164:167], v[212:215], v[8:11]
	v_mfma_f32_16x16x32_bf16 v[60:63], v[152:155], v[192:195], v[60:63]
	v_mfma_f32_16x16x32_bf16 v[56:59], v[168:171], v[192:195], v[56:59]
	v_mfma_f32_16x16x32_bf16 v[44:47], v[152:155], v[200:203], v[44:47]
	v_mfma_f32_16x16x32_bf16 v[40:43], v[168:171], v[200:203], v[40:43]
	v_mfma_f32_16x16x32_bf16 v[28:31], v[152:155], v[208:211], v[28:31]
	v_mfma_f32_16x16x32_bf16 v[24:27], v[168:171], v[208:211], v[24:27]
	v_mfma_f32_16x16x32_bf16 v[12:15], v[152:155], v[216:219], v[12:15]
	v_mfma_f32_16x16x32_bf16 v[8:11], v[168:171], v[216:219], v[8:11]
	v_mfma_f32_16x16x32_bf16 v[52:55], v[172:175], v[188:191], v[52:55]
	v_mfma_f32_16x16x32_bf16 v[48:51], v[180:183], v[188:191], v[48:51]
	v_mfma_f32_16x16x32_bf16 v[36:39], v[172:175], v[196:199], v[36:39]
	v_mfma_f32_16x16x32_bf16 v[32:35], v[180:183], v[196:199], v[32:35]
	v_mfma_f32_16x16x32_bf16 v[20:23], v[172:175], v[204:207], v[20:23]
	v_mfma_f32_16x16x32_bf16 v[16:19], v[180:183], v[204:207], v[16:19]
	v_mfma_f32_16x16x32_bf16 v[4:7], v[172:175], v[212:215], v[4:7]
	v_mfma_f32_16x16x32_bf16 v[0:3], v[180:183], v[212:215], v[0:3]
	v_mfma_f32_16x16x32_bf16 v[52:55], v[176:179], v[192:195], v[52:55]
	v_mfma_f32_16x16x32_bf16 v[48:51], v[184:187], v[192:195], v[48:51]
	v_mfma_f32_16x16x32_bf16 v[36:39], v[176:179], v[200:203], v[36:39]
	v_mfma_f32_16x16x32_bf16 v[32:35], v[184:187], v[200:203], v[32:35]
	v_mfma_f32_16x16x32_bf16 v[20:23], v[176:179], v[208:211], v[20:23]
	v_mfma_f32_16x16x32_bf16 v[16:19], v[184:187], v[208:211], v[16:19]
	v_mfma_f32_16x16x32_bf16 v[4:7], v[176:179], v[216:219], v[4:7]
	v_mfma_f32_16x16x32_bf16 v[0:3], v[184:187], v[216:219], v[0:3]
	s_barrier
	s_setprio 0
	s_add_i32 s48, s48, 2
	s_add_u32 s22, s22, 0x100
	s_addc_u32 s23, s23, 0
	s_add_u32 s46, s46, 0x100
	s_addc_u32 s47, s47, 0
	s_cmp_gt_u32 s48, 61
	s_cbranch_scc0 .LBB0_249
	s_and_b64 vcc, exec, s[8:9]
	s_cbranch_vccnz .LBB0_254
	v_lshl_add_u32 v148, s20, 8, v157
	s_cmp_gt_i32 s44, 39
	s_mov_b64 s[20:21], -1
	s_cbranch_scc1 .LBB0_255

; #define PG8_STAGE(bufoff, gbase, voff) do { _Pragma("unroll") for (int _i = 0; _i < 2; ++_i) \
;         __builtin_amdgcn_global_load_lds((const unsigned*)((const char*)(gbase) + (voff)[_i]), (PG8_LAS unsigned*)(lds + (bufoff) + ldsw + _i * 8192), 16, 0, 0); } while (0)
; #define PG8_LDA(dst, b, h) do { _Pragma("unroll") for (int m = 0; m < 4; ++m) _Pragma("unroll") for (int k = 0; k < 2; ++k) dst[m][k] = *(const PG8_LAS bf16x8*)(lds + PG8_SA(b, h) + aoff + m * 2048 + k * 1024); } while (0)
; #define PG8_LDB(dst, b, h) do { _Pragma("unroll") for (int n = 0; n < 2; ++n) _Pragma("unroll") for (int k = 0; k < 2; ++k) dst[n][k] = *(const PG8_LAS bf16x8*)(lds + PG8_SB(b, h) + boff + n * 2048 + k * 1024); } while (0)
; #define PG8_SCHED __builtin_amdgcn_sched_barrier(0)
; template <class Epi, class Sched, bool ALIGN_EPI = false, bool SP2 = false>
; __device__ __forceinline__ void gemm_phase(PG8_LAS unsigned char* lds, const Gemm g, const Sched& S, const Epi& E, const int wid) {
;     ...
;         const char* nA = has_next ? (const char*)g.A + (size_t)nxt.pm * tstep + (size_t)nxt.kb * kstep : cA; const char* nB = has_next ? (const char*)g.Bt + (size_t)nxt.pn * tstep + (size_t)nxt.kb * kstep : cB;
;         for (int t = 0; t < nt; t += 2) {
;             const bool last = (t == nt - 2);
;             const char* a1 = cA + (size_t)(t + 1) * kstep;
;             const char* a2 = last ? nA : cA + (size_t)(t + 2) * kstep; const char* b2 = last ? nB : cB + (size_t)(t + 2) * kstep;
;             const char* a3 = a2 + kstep; const char* b3 = b2 + kstep;
;             if (last && has_next) S.a_ready(nxt);
;             if constexpr (SP2) {
;             PG8_LDB(B0, 0, 0); PG8_LDB(B1, 0, 1); PG8_SCHED; PG8_LDA(At, 0, 0); PG8_STAGE(PG8_SA(1, 1), a1 + hstep, voffA);
.LBB0_842:
	s_ashr_i32 s15, s14, 31
	s_lshl_b64 s[18:19], s[14:15], 21
	s_add_u32 s13, s90, s18
	s_addc_u32 s15, s91, s19
	s_ashr_i32 s11, s10, 31
	s_lshl_b64 s[20:21], s[10:11], 7
	s_add_u32 s18, s13, s20
	s_addc_u32 s19, s15, s21
	s_and_b64 s[30:31], s[16:17], exec
	s_cselect_b32 s11, s19, s27
	s_cselect_b32 s15, s18, s26
	s_ashr_i32 s13, s12, 31
	s_lshl_b64 s[30:31], s[12:13], 21
	s_add_u32 s13, s34, s30
	s_addc_u32 s23, s35, s31
	s_add_u32 s20, s13, s20
	s_addc_u32 s21, s23, s21
	s_and_b64 s[30:31], s[16:17], exec
	s_cselect_b32 s13, s21, s29
	s_cselect_b32 s23, s20, s28
	s_add_i32 s25, s55, -2
	s_add_u32 s26, s26, 0x100080
	s_addc_u32 s27, s27, 0
	s_add_u32 s56, s28, 0x100
	s_waitcnt vmcnt(0)
	v_mov_b32_e32 v64, 0
	s_addc_u32 s57, s29, 0
	s_mov_b32 s28, 0
	v_mov_b32_e32 v65, v64
	v_mov_b32_e32 v66, v64
	v_mov_b32_e32 v67, v64
	v_mov_b32_e32 v68, v64
	v_mov_b32_e32 v69, v64
	v_mov_b32_e32 v70, v64
	v_mov_b32_e32 v71, v64
	v_mov_b32_e32 v80, v64
	v_mov_b32_e32 v81, v64
	v_mov_b32_e32 v82, v64
	v_mov_b32_e32 v83, v64
	v_mov_b32_e32 v84, v64
	v_mov_b32_e32 v85, v64
	v_mov_b32_e32 v86, v64
	v_mov_b32_e32 v87, v64
	v_mov_b32_e32 v96, v64
	v_mov_b32_e32 v97, v64
	v_mov_b32_e32 v98, v64
	v_mov_b32_e32 v99, v64
	v_mov_b32_e32 v100, v64
	v_mov_b32_e32 v101, v64
	v_mov_b32_e32 v102, v64
	v_mov_b32_e32 v103, v64
	v_mov_b32_e32 v112, v64
	v_mov_b32_e32 v113, v64
	v_mov_b32_e32 v114, v64
	v_mov_b32_e32 v115, v64
	v_mov_b32_e32 v116, v64
	v_mov_b32_e32 v117, v64
	v_mov_b32_e32 v118, v64
	v_mov_b32_e32 v119, v64
	v_mov_b32_e32 v72, v64
	v_mov_b32_e32 v73, v64
	v_mov_b32_e32 v74, v64
	v_mov_b32_e32 v75, v64
	v_mov_b32_e32 v76, v64
	v_mov_b32_e32 v77, v64
	v_mov_b32_e32 v78, v64
	v_mov_b32_e32 v79, v64
	v_mov_b32_e32 v88, v64
	v_mov_b32_e32 v89, v64
	v_mov_b32_e32 v90, v64
	v_mov_b32_e32 v91, v64
	v_mov_b32_e32 v92, v64
	v_mov_b32_e32 v93, v64
	v_mov_b32_e32 v94, v64
	v_mov_b32_e32 v95, v64
	v_mov_b32_e32 v104, v64
	v_mov_b32_e32 v105, v64
	v_mov_b32_e32 v106, v64
	v_mov_b32_e32 v107, v64
	v_mov_b32_e32 v108, v64
	v_mov_b32_e32 v109, v64
	v_mov_b32_e32 v110, v64
	v_mov_b32_e32 v111, v64
	v_mov_b32_e32 v120, v64
	v_mov_b32_e32 v121, v64
	v_mov_b32_e32 v122, v64
	v_mov_b32_e32 v123, v64
	v_mov_b32_e32 v124, v64
	v_mov_b32_e32 v125, v64
	v_mov_b32_e32 v126, v64
	v_mov_b32_e32 v127, v64
	v_mov_b32_e32 v0, v64
	v_mov_b32_e32 v1, v64
	v_mov_b32_e32 v2, v64
	v_mov_b32_e32 v3, v64
	v_mov_b32_e32 v4, v64
	v_mov_b32_e32 v5, v64
	v_mov_b32_e32 v6, v64
	v_mov_b32_e32 v7, v64
	v_mov_b32_e32 v16, v64
	v_mov_b32_e32 v17, v64
	v_mov_b32_e32 v18, v64
	v_mov_b32_e32 v19, v64
	v_mov_b32_e32 v20, v64
	v_mov_b32_e32 v21, v64
	v_mov_b32_e32 v22, v64
	v_mov_b32_e32 v23, v64
	v_mov_b32_e32 v32, v64
	v_mov_b32_e32 v33, v64
	v_mov_b32_e32 v34, v64
	v_mov_b32_e32 v35, v64
	v_mov_b32_e32 v36, v64
	v_mov_b32_e32 v37, v64
	v_mov_b32_e32 v38, v64
	v_mov_b32_e32 v39, v64
	v_mov_b32_e32 v48, v64
	v_mov_b32_e32 v49, v64
	v_mov_b32_e32 v50, v64
	v_mov_b32_e32 v51, v64
	v_mov_b32_e32 v52, v64
	v_mov_b32_e32 v53, v64
	v_mov_b32_e32 v54, v64
	v_mov_b32_e32 v55, v64
	v_mov_b32_e32 v8, v64
	v_mov_b32_e32 v9, v64
	v_mov_b32_e32 v10, v64
	v_mov_b32_e32 v11, v64
	v_mov_b32_e32 v12, v64
	v_mov_b32_e32 v13, v64
	v_mov_b32_e32 v14, v64
	v_mov_b32_e32 v15, v64
	v_mov_b32_e32 v24, v64
	v_mov_b32_e32 v25, v64
	v_mov_b32_e32 v26, v64
	v_mov_b32_e32 v27, v64
	v_mov_b32_e32 v28, v64
	v_mov_b32_e32 v29, v64
	v_mov_b32_e32 v30, v64
	v_mov_b32_e32 v31, v64
	v_mov_b32_e32 v40, v64
	v_mov_b32_e32 v41, v64
	v_mov_b32_e32 v42, v64
	v_mov_b32_e32 v43, v64
	v_mov_b32_e32 v44, v64
	v_mov_b32_e32 v45, v64
	v_mov_b32_e32 v46, v64
	v_mov_b32_e32 v47, v64
	v_mov_b32_e32 v56, v64
	v_mov_b32_e32 v57, v64
	v_mov_b32_e32 v58, v64
	v_mov_b32_e32 v59, v64
	v_mov_b32_e32 v60, v64
	v_mov_b32_e32 v61, v64
	v_mov_b32_e32 v62, v64
	v_mov_b32_e32 v63, v64
	v_add_u32_e32 v246, 0x18000, v179
	v_add_u32_e32 v248, 0x1c000, v179
.LBB0_843:
	ds_read_b128 v[128:131], v181
	ds_read_b128 v[132:135], v181 offset:1024
	ds_read_b128 v[136:139], v181 offset:2048
	ds_read_b128 v[140:143], v181 offset:3072
	ds_read_b128 v[166:169], v182
	ds_read_b128 v[170:173], v182 offset:1024
	ds_read_b128 v[184:187], v182 offset:2048
	ds_read_b128 v[188:191], v182 offset:3072
	s_add_i32 s58, s28, 2
	s_add_u32 s29, s26, 0xfff00080
	s_addc_u32 s30, s27, -1
	s_cmp_eq_u32 s25, s28
	s_cselect_b32 s28, s23, s56
	s_cselect_b32 s31, s11, s30
	s_cselect_b32 s30, s15, s29
	s_cselect_b32 s29, s13, s57
	s_add_i32 m0, s37, 0xc000
	ds_read_b128 v[192:195], v183
	ds_read_b128 v[196:199], v183 offset:1024
	ds_read_b128 v[200:203], v183 offset:2048
	ds_read_b128 v[204:207], v183 offset:3072
	ds_read_b128 v[208:211], v183 offset:4096
	ds_read_b128 v[212:215], v183 offset:5120
	ds_read_b128 v[216:219], v183 offset:6144
	ds_read_b128 v[220:223], v183 offset:7168
	global_load_lds_dwordx4 v160, s[26:27]
	s_add_i32 m0, s37, 0xe000
	s_nop 0
	global_load_lds_dwordx4 v162, s[26:27]
	s_waitcnt vmcnt(8)
	s_waitcnt lgkmcnt(0)
	s_setprio 1
	s_barrier
; #define PG8_STAGE(bufoff, gbase, voff) do { _Pragma("unroll") for (int _i = 0; _i < 2; ++_i) \
;         __builtin_amdgcn_global_load_lds((const unsigned*)((const char*)(gbase) + (voff)[_i]), (PG8_LAS unsigned*)(lds + (bufoff) + ldsw + _i * 8192), 16, 0, 0); } while (0)
; #define PG8_LDA(dst, b, h) do { _Pragma("unroll") for (int m = 0; m < 4; ++m) _Pragma("unroll") for (int k = 0; k < 2; ++k) dst[m][k] = *(const PG8_LAS bf16x8*)(lds + PG8_SA(b, h) + aoff + m * 2048 + k * 1024); } while (0)
; #define PG8_MMA(ai, bj, At, Bt) do { __builtin_amdgcn_s_setprio(1); _Pragma("unroll") for (int m = 0; m < 4; ++m) _Pragma("unroll") for (int n = 0; n < 2; ++n) _Pragma("unroll") for (int k = 0; k < 2; ++k) \
;         acc[ai][bj][m][n] = __builtin_amdgcn_mfma_f32_16x16x32_bf16(Bt[n][k], At[m][k], acc[ai][bj][m][n], 0, 0, 0); __builtin_amdgcn_s_setprio(0); } while (0)
; #define PG8_WAIT_V(n) asm volatile("s_waitcnt vmcnt(" #n ")" ::: "memory")
; #define PG8_WAIT_L(n) asm volatile("s_waitcnt lgkmcnt(" #n ")" ::: "memory")
; #define PG8_BAR __builtin_amdgcn_s_barrier()
; #define PG8_SCHED __builtin_amdgcn_sched_barrier(0)
; template <class Epi, class Sched, bool ALIGN_EPI = false, bool SP2 = false>
; __device__ __forceinline__ void gemm_phase(PG8_LAS unsigned char* lds, const Gemm g, const Sched& S, const Epi& E, const int wid) {
;     ...
;             PG8_WAIT_V(8); PG8_WAIT_L(0); PG8_BAR; PG8_MMA(0, 0, At, B0); PG8_MMA(0, 1, At, B1); PG8_BAR; PG8_SCHED;
;             PG8_LDA(At, 0, 1); PG8_STAGE(PG8_SB(0, 0), b2, voffB); PG8_STAGE(PG8_SB(0, 1), b2 + hstep, voffB); PG8_STAGE(PG8_SA(0, 0), a2, voffA);
;             PG8_WAIT_V(8); PG8_WAIT_L(0); PG8_BAR; PG8_MMA(1, 0, At, B0); PG8_MMA(1, 1, At, B1); PG8_BAR; PG8_SCHED;
	v_mfma_f32_16x16x32_bf16 v[60:63], v[128:131], v[192:195], v[60:63]
	v_mfma_f32_16x16x32_bf16 v[56:59], v[136:139], v[192:195], v[56:59]
	v_mfma_f32_16x16x32_bf16 v[44:47], v[128:131], v[200:203], v[44:47]
	v_mfma_f32_16x16x32_bf16 v[40:43], v[136:139], v[200:203], v[40:43]
	v_mfma_f32_16x16x32_bf16 v[28:31], v[128:131], v[208:211], v[28:31]
	v_mfma_f32_16x16x32_bf16 v[24:27], v[136:139], v[208:211], v[24:27]
	v_mfma_f32_16x16x32_bf16 v[12:15], v[128:131], v[216:219], v[12:15]
	v_mfma_f32_16x16x32_bf16 v[8:11], v[136:139], v[216:219], v[8:11]
	v_mfma_f32_16x16x32_bf16 v[60:63], v[132:135], v[196:199], v[60:63]
	v_mfma_f32_16x16x32_bf16 v[56:59], v[140:143], v[196:199], v[56:59]
	v_mfma_f32_16x16x32_bf16 v[44:47], v[132:135], v[204:207], v[44:47]
	v_mfma_f32_16x16x32_bf16 v[40:43], v[140:143], v[204:207], v[40:43]
	v_mfma_f32_16x16x32_bf16 v[28:31], v[132:135], v[212:215], v[28:31]
	v_mfma_f32_16x16x32_bf16 v[24:27], v[140:143], v[212:215], v[24:27]
	v_mfma_f32_16x16x32_bf16 v[12:15], v[132:135], v[220:223], v[12:15]
	v_mfma_f32_16x16x32_bf16 v[8:11], v[140:143], v[220:223], v[8:11]
	v_mfma_f32_16x16x32_bf16 v[52:55], v[166:169], v[192:195], v[52:55]
	v_mfma_f32_16x16x32_bf16 v[48:51], v[184:187], v[192:195], v[48:51]
	v_mfma_f32_16x16x32_bf16 v[36:39], v[166:169], v[200:203], v[36:39]
	v_mfma_f32_16x16x32_bf16 v[32:35], v[184:187], v[200:203], v[32:35]
	v_mfma_f32_16x16x32_bf16 v[20:23], v[166:169], v[208:211], v[20:23]
	v_mfma_f32_16x16x32_bf16 v[16:19], v[184:187], v[208:211], v[16:19]
	v_mfma_f32_16x16x32_bf16 v[4:7], v[166:169], v[216:219], v[4:7]
	v_mfma_f32_16x16x32_bf16 v[0:3], v[184:187], v[216:219], v[0:3]
	v_mfma_f32_16x16x32_bf16 v[52:55], v[170:173], v[196:199], v[52:55]
	v_mfma_f32_16x16x32_bf16 v[48:51], v[188:191], v[196:199], v[48:51]
	v_mfma_f32_16x16x32_bf16 v[36:39], v[170:173], v[204:207], v[36:39]
	v_mfma_f32_16x16x32_bf16 v[32:35], v[188:191], v[204:207], v[32:35]
	v_mfma_f32_16x16x32_bf16 v[20:23], v[170:173], v[212:215], v[20:23]
	v_mfma_f32_16x16x32_bf16 v[16:19], v[188:191], v[212:215], v[16:19]
	v_mfma_f32_16x16x32_bf16 v[4:7], v[170:173], v[220:223], v[4:7]
	v_mfma_f32_16x16x32_bf16 v[0:3], v[188:191], v[220:223], v[0:3]
	s_barrier
	s_setprio 0
	s_add_i32 s59, s48, s36
	s_mov_b32 m0, s59
	ds_read_b128 v[192:195], v183 offset:16384
	ds_read_b128 v[196:199], v183 offset:17408
	ds_read_b128 v[200:203], v183 offset:18432
	ds_read_b128 v[204:207], v183 offset:19456
	ds_read_b128 v[208:211], v183 offset:20480
	ds_read_b128 v[212:215], v183 offset:21504
	ds_read_b128 v[216:219], v183 offset:22528
	ds_read_b128 v[220:223], v183 offset:23552
	global_load_lds_dwordx4 v146, s[28:29]
	s_add_i32 m0, s59, 0x2000
	s_add_u32 s60, s28, 0x100000
	s_addc_u32 s61, s29, 0
	s_add_i32 s59, s49, s36
	global_load_lds_dwordx4 v150, s[28:29]
	s_mov_b32 m0, s59
	global_load_lds_dwordx4 v146, s[60:61]
	s_add_i32 m0, s59, 0x2000
	s_nop 0
	global_load_lds_dwordx4 v150, s[60:61]
	s_mov_b32 m0, s37
	s_nop 0
	global_load_lds_dwordx4 v144, s[30:31]
	s_mov_b32 m0, s38
	s_nop 0
	global_load_lds_dwordx4 v148, s[30:31]
	s_waitcnt vmcnt(8)
	s_waitcnt lgkmcnt(0)
	s_setprio 1
	s_barrier
	v_mfma_f32_16x16x32_bf16 v[124:127], v[128:131], v[192:195], v[124:127]
	v_mfma_f32_16x16x32_bf16 v[120:123], v[136:139], v[192:195], v[120:123]
	v_mfma_f32_16x16x32_bf16 v[108:111], v[128:131], v[200:203], v[108:111]
	v_mfma_f32_16x16x32_bf16 v[104:107], v[136:139], v[200:203], v[104:107]
	v_mfma_f32_16x16x32_bf16 v[92:95], v[128:131], v[208:211], v[92:95]
	v_mfma_f32_16x16x32_bf16 v[88:91], v[136:139], v[208:211], v[88:91]
	v_mfma_f32_16x16x32_bf16 v[76:79], v[128:131], v[216:219], v[76:79]
	v_mfma_f32_16x16x32_bf16 v[72:75], v[136:139], v[216:219], v[72:75]
	v_mfma_f32_16x16x32_bf16 v[124:127], v[132:135], v[196:199], v[124:127]
	v_mfma_f32_16x16x32_bf16 v[120:123], v[140:143], v[196:199], v[120:123]
	v_mfma_f32_16x16x32_bf16 v[108:111], v[132:135], v[204:207], v[108:111]
	v_mfma_f32_16x16x32_bf16 v[104:107], v[140:143], v[204:207], v[104:107]
	v_mfma_f32_16x16x32_bf16 v[92:95], v[132:135], v[212:215], v[92:95]
	v_mfma_f32_16x16x32_bf16 v[88:91], v[140:143], v[212:215], v[88:91]
	v_mfma_f32_16x16x32_bf16 v[76:79], v[132:135], v[220:223], v[76:79]
	v_mfma_f32_16x16x32_bf16 v[72:75], v[140:143], v[220:223], v[72:75]
	v_mfma_f32_16x16x32_bf16 v[116:119], v[166:169], v[192:195], v[116:119]
	v_mfma_f32_16x16x32_bf16 v[112:115], v[184:187], v[192:195], v[112:115]
	v_mfma_f32_16x16x32_bf16 v[100:103], v[166:169], v[200:203], v[100:103]
	v_mfma_f32_16x16x32_bf16 v[96:99], v[184:187], v[200:203], v[96:99]
	v_mfma_f32_16x16x32_bf16 v[84:87], v[166:169], v[208:211], v[84:87]
	v_mfma_f32_16x16x32_bf16 v[80:83], v[184:187], v[208:211], v[80:83]
	v_mfma_f32_16x16x32_bf16 v[68:71], v[166:169], v[216:219], v[68:71]
	v_mfma_f32_16x16x32_bf16 v[64:67], v[184:187], v[216:219], v[64:67]
	v_mfma_f32_16x16x32_bf16 v[116:119], v[170:173], v[196:199], v[116:119]
	v_mfma_f32_16x16x32_bf16 v[112:115], v[188:191], v[196:199], v[112:115]
	v_mfma_f32_16x16x32_bf16 v[100:103], v[170:173], v[204:207], v[100:103]
	v_mfma_f32_16x16x32_bf16 v[96:99], v[188:191], v[204:207], v[96:99]
	v_mfma_f32_16x16x32_bf16 v[84:87], v[170:173], v[212:215], v[84:87]
	v_mfma_f32_16x16x32_bf16 v[80:83], v[188:191], v[212:215], v[80:83]
	v_mfma_f32_16x16x32_bf16 v[68:71], v[170:173], v[220:223], v[68:71]
	v_mfma_f32_16x16x32_bf16 v[64:67], v[188:191], v[220:223], v[64:67]
	s_barrier
; #define PG8_STAGE(bufoff, gbase, voff) do { _Pragma("unroll") for (int _i = 0; _i < 2; ++_i) \
;         __builtin_amdgcn_global_load_lds((const unsigned*)((const char*)(gbase) + (voff)[_i]), (PG8_LAS unsigned*)(lds + (bufoff) + ldsw + _i * 8192), 16, 0, 0); } while (0)
; #define PG8_LDA(dst, b, h) do { _Pragma("unroll") for (int m = 0; m < 4; ++m) _Pragma("unroll") for (int k = 0; k < 2; ++k) dst[m][k] = *(const PG8_LAS bf16x8*)(lds + PG8_SA(b, h) + aoff + m * 2048 + k * 1024); } while (0)
; #define PG8_LDB(dst, b, h) do { _Pragma("unroll") for (int n = 0; n < 2; ++n) _Pragma("unroll") for (int k = 0; k < 2; ++k) dst[n][k] = *(const PG8_LAS bf16x8*)(lds + PG8_SB(b, h) + boff + n * 2048 + k * 1024); } while (0)
; #define PG8_MMA(ai, bj, At, Bt) do { __builtin_amdgcn_s_setprio(1); _Pragma("unroll") for (int m = 0; m < 4; ++m) _Pragma("unroll") for (int n = 0; n < 2; ++n) _Pragma("unroll") for (int k = 0; k < 2; ++k) \
;         acc[ai][bj][m][n] = __builtin_amdgcn_mfma_f32_16x16x32_bf16(Bt[n][k], At[m][k], acc[ai][bj][m][n], 0, 0, 0); __builtin_amdgcn_s_setprio(0); } while (0)
; #define PG8_WAIT_V(n) asm volatile("s_waitcnt vmcnt(" #n ")" ::: "memory")
; #define PG8_WAIT_L(n) asm volatile("s_waitcnt lgkmcnt(" #n ")" ::: "memory")
; #define PG8_BAR __builtin_amdgcn_s_barrier()
; #define PG8_SCHED __builtin_amdgcn_sched_barrier(0)
; template <class Epi, class Sched, bool ALIGN_EPI = false, bool SP2 = false>
; __device__ __forceinline__ void gemm_phase(PG8_LAS unsigned char* lds, const Gemm g, const Sched& S, const Epi& E, const int wid) {
;     ...
;         for (int t = 0; t < nt; t += 2) {
;     ...
;             PG8_LDB(B0, 1, 0); PG8_LDB(B1, 1, 1); PG8_SCHED; PG8_LDA(At, 1, 0); PG8_STAGE(PG8_SA(0, 1), a2 + hstep, voffA);
;             PG8_WAIT_V(8); PG8_WAIT_L(0); PG8_BAR; PG8_MMA(0, 0, At, B0); PG8_MMA(0, 1, At, B1); PG8_BAR; PG8_SCHED;
;             PG8_LDA(At, 1, 1); PG8_STAGE(PG8_SB(1, 0), b3, voffB); PG8_STAGE(PG8_SB(1, 1), b3 + hstep, voffB); PG8_STAGE(PG8_SA(1, 0), a3, voffA);
;             PG8_WAIT_V(8); PG8_WAIT_L(0); PG8_BAR; PG8_MMA(1, 0, At, B0); PG8_MMA(1, 1, At, B1); PG8_BAR; PG8_SCHED;
	s_setprio 0
	s_add_i32 s59, 0, 0x18000
	s_add_i32 s60, 0, 0x1c000
	ds_read_b128 v[128:131], v246
	ds_read_b128 v[132:135], v246 offset:1024
	ds_read_b128 v[136:139], v246 offset:2048
	ds_read_b128 v[140:143], v246 offset:3072
	ds_read_b128 v[166:169], v248
	ds_read_b128 v[170:173], v248 offset:1024
	ds_read_b128 v[184:187], v248 offset:2048
	ds_read_b128 v[188:191], v248 offset:3072
	s_add_u32 s30, s30, 0x100000
	s_addc_u32 s31, s31, 0
	s_mov_b32 m0, s39
	ds_read_b128 v[192:195], v183 offset:32768
	ds_read_b128 v[196:199], v183 offset:33792
	ds_read_b128 v[200:203], v183 offset:34816
	ds_read_b128 v[204:207], v183 offset:35840
	ds_read_b128 v[208:211], v183 offset:36864
	ds_read_b128 v[212:215], v183 offset:37888
	ds_read_b128 v[216:219], v183 offset:38912
	ds_read_b128 v[220:223], v183 offset:39936
	global_load_lds_dwordx4 v144, s[30:31]
	s_mov_b32 m0, s40
	s_nop 0
	global_load_lds_dwordx4 v148, s[30:31]
	s_waitcnt vmcnt(8)
	s_waitcnt lgkmcnt(0)
	s_setprio 1
	s_barrier
	v_mfma_f32_16x16x32_bf16 v[60:63], v[128:131], v[192:195], v[60:63]
	v_mfma_f32_16x16x32_bf16 v[56:59], v[136:139], v[192:195], v[56:59]
	v_mfma_f32_16x16x32_bf16 v[44:47], v[128:131], v[200:203], v[44:47]
	v_mfma_f32_16x16x32_bf16 v[40:43], v[136:139], v[200:203], v[40:43]
	v_mfma_f32_16x16x32_bf16 v[28:31], v[128:131], v[208:211], v[28:31]
	v_mfma_f32_16x16x32_bf16 v[24:27], v[136:139], v[208:211], v[24:27]
	v_mfma_f32_16x16x32_bf16 v[12:15], v[128:131], v[216:219], v[12:15]
	v_mfma_f32_16x16x32_bf16 v[8:11], v[136:139], v[216:219], v[8:11]
	v_mfma_f32_16x16x32_bf16 v[60:63], v[132:135], v[196:199], v[60:63]
	v_mfma_f32_16x16x32_bf16 v[56:59], v[140:143], v[196:199], v[56:59]
	v_mfma_f32_16x16x32_bf16 v[44:47], v[132:135], v[204:207], v[44:47]
	v_mfma_f32_16x16x32_bf16 v[40:43], v[140:143], v[204:207], v[40:43]
	v_mfma_f32_16x16x32_bf16 v[28:31], v[132:135], v[212:215], v[28:31]
	v_mfma_f32_16x16x32_bf16 v[24:27], v[140:143], v[212:215], v[24:27]
	v_mfma_f32_16x16x32_bf16 v[12:15], v[132:135], v[220:223], v[12:15]
	v_mfma_f32_16x16x32_bf16 v[8:11], v[140:143], v[220:223], v[8:11]
	v_mfma_f32_16x16x32_bf16 v[52:55], v[166:169], v[192:195], v[52:55]
	v_mfma_f32_16x16x32_bf16 v[48:51], v[184:187], v[192:195], v[48:51]
	v_mfma_f32_16x16x32_bf16 v[36:39], v[166:169], v[200:203], v[36:39]
	v_mfma_f32_16x16x32_bf16 v[32:35], v[184:187], v[200:203], v[32:35]
	v_mfma_f32_16x16x32_bf16 v[20:23], v[166:169], v[208:211], v[20:23]
	v_mfma_f32_16x16x32_bf16 v[16:19], v[184:187], v[208:211], v[16:19]
	v_mfma_f32_16x16x32_bf16 v[4:7], v[166:169], v[216:219], v[4:7]
	v_mfma_f32_16x16x32_bf16 v[0:3], v[184:187], v[216:219], v[0:3]
	v_mfma_f32_16x16x32_bf16 v[52:55], v[170:173], v[196:199], v[52:55]
	v_mfma_f32_16x16x32_bf16 v[48:51], v[188:191], v[196:199], v[48:51]
	v_mfma_f32_16x16x32_bf16 v[36:39], v[170:173], v[204:207], v[36:39]
	v_mfma_f32_16x16x32_bf16 v[32:35], v[188:191], v[204:207], v[32:35]
	v_mfma_f32_16x16x32_bf16 v[20:23], v[170:173], v[212:215], v[20:23]
	v_mfma_f32_16x16x32_bf16 v[16:19], v[188:191], v[212:215], v[16:19]
	v_mfma_f32_16x16x32_bf16 v[4:7], v[170:173], v[220:223], v[4:7]
	v_mfma_f32_16x16x32_bf16 v[0:3], v[188:191], v[220:223], v[0:3]
	s_barrier
	s_setprio 0
	s_add_u32 s98, s28, 0x80
	s_addc_u32 s99, s29, 0
	s_add_u32 s100, s30, 0xfff00080
	s_addc_u32 s101, s31, -1
	s_add_i32 s30, s59, s36
	s_mov_b32 m0, s30
	ds_read_b128 v[192:195], v183 offset:49152
	ds_read_b128 v[196:199], v183 offset:50176
	ds_read_b128 v[200:203], v183 offset:51200
	ds_read_b128 v[204:207], v183 offset:52224
	ds_read_b128 v[208:211], v183 offset:53248
	ds_read_b128 v[212:215], v183 offset:54272
	ds_read_b128 v[216:219], v183 offset:55296
	ds_read_b128 v[220:223], v183 offset:56320
	global_load_lds_dwordx4 v146, s[98:99]
	s_add_i32 m0, s30, 0x2000
	s_add_u32 s28, s28, 0x100080
	s_addc_u32 s29, s29, 0
	s_add_i32 s30, s60, s36
	global_load_lds_dwordx4 v150, s[98:99]
	s_mov_b32 m0, s30
	s_nop 0
	global_load_lds_dwordx4 v146, s[28:29]
	s_add_i32 m0, s30, 0x2000
	s_nop 0
	global_load_lds_dwordx4 v150, s[28:29]
	s_mov_b32 m0, s42
	s_nop 0
	global_load_lds_dwordx4 v144, s[100:101]
	s_mov_b32 m0, s43
	s_nop 0
	global_load_lds_dwordx4 v148, s[100:101]
	s_waitcnt vmcnt(8)
	s_waitcnt lgkmcnt(0)
	s_setprio 1
	s_barrier
	v_mfma_f32_16x16x32_bf16 v[124:127], v[128:131], v[192:195], v[124:127]
	v_mfma_f32_16x16x32_bf16 v[120:123], v[136:139], v[192:195], v[120:123]
	v_mfma_f32_16x16x32_bf16 v[108:111], v[128:131], v[200:203], v[108:111]
	v_mfma_f32_16x16x32_bf16 v[104:107], v[136:139], v[200:203], v[104:107]
	v_mfma_f32_16x16x32_bf16 v[92:95], v[128:131], v[208:211], v[92:95]
	v_mfma_f32_16x16x32_bf16 v[88:91], v[136:139], v[208:211], v[88:91]
	v_mfma_f32_16x16x32_bf16 v[76:79], v[128:131], v[216:219], v[76:79]
	v_mfma_f32_16x16x32_bf16 v[72:75], v[136:139], v[216:219], v[72:75]
	v_mfma_f32_16x16x32_bf16 v[124:127], v[132:135], v[196:199], v[124:127]
	v_mfma_f32_16x16x32_bf16 v[120:123], v[140:143], v[196:199], v[120:123]
	v_mfma_f32_16x16x32_bf16 v[108:111], v[132:135], v[204:207], v[108:111]
	v_mfma_f32_16x16x32_bf16 v[104:107], v[140:143], v[204:207], v[104:107]
	v_mfma_f32_16x16x32_bf16 v[92:95], v[132:135], v[212:215], v[92:95]
	v_mfma_f32_16x16x32_bf16 v[88:91], v[140:143], v[212:215], v[88:91]
	v_mfma_f32_16x16x32_bf16 v[76:79], v[132:135], v[220:223], v[76:79]
	v_mfma_f32_16x16x32_bf16 v[72:75], v[140:143], v[220:223], v[72:75]
	v_mfma_f32_16x16x32_bf16 v[116:119], v[166:169], v[192:195], v[116:119]
	v_mfma_f32_16x16x32_bf16 v[112:115], v[184:187], v[192:195], v[112:115]
	v_mfma_f32_16x16x32_bf16 v[100:103], v[166:169], v[200:203], v[100:103]
	v_mfma_f32_16x16x32_bf16 v[96:99], v[184:187], v[200:203], v[96:99]
	v_mfma_f32_16x16x32_bf16 v[84:87], v[166:169], v[208:211], v[84:87]
	v_mfma_f32_16x16x32_bf16 v[80:83], v[184:187], v[208:211], v[80:83]
	v_mfma_f32_16x16x32_bf16 v[68:71], v[166:169], v[216:219], v[68:71]
	v_mfma_f32_16x16x32_bf16 v[64:67], v[184:187], v[216:219], v[64:67]
	v_mfma_f32_16x16x32_bf16 v[116:119], v[170:173], v[196:199], v[116:119]
	v_mfma_f32_16x16x32_bf16 v[112:115], v[188:191], v[196:199], v[112:115]
	v_mfma_f32_16x16x32_bf16 v[100:103], v[170:173], v[204:207], v[100:103]
	v_mfma_f32_16x16x32_bf16 v[96:99], v[188:191], v[204:207], v[96:99]
	v_mfma_f32_16x16x32_bf16 v[84:87], v[170:173], v[212:215], v[84:87]
	v_mfma_f32_16x16x32_bf16 v[80:83], v[188:191], v[212:215], v[80:83]
	v_mfma_f32_16x16x32_bf16 v[68:71], v[170:173], v[220:223], v[68:71]
	v_mfma_f32_16x16x32_bf16 v[64:67], v[188:191], v[220:223], v[64:67]
	s_barrier
	s_setprio 0
	s_add_u32 s26, s26, 0x100
	s_addc_u32 s27, s27, 0
	s_add_u32 s56, s56, 0x100
	s_addc_u32 s57, s57, 0
	s_cmp_ge_i32 s58, s55
	s_mov_b32 s28, s58
	s_cbranch_scc0 .LBB0_843
	s_and_b64 vcc, exec, s[8:9]
	s_cbranch_vccz .LBB0_846
	s_barrier

;     __device__ bool next(int i, Unit& u) const { const bool ok = StaticOrder::next(i, u); u.pm = 0; u.pn = 0; return ok; }
; #define PG8_STAGE(bufoff, gbase, voff) do { _Pragma("unroll") for (int _i = 0; _i < 2; ++_i) \
;         __builtin_amdgcn_global_load_lds((const unsigned*)((const char*)(gbase) + (voff)[_i]), (PG8_LAS unsigned*)(lds + (bufoff) + ldsw + _i * 8192), 16, 0, 0); } while (0)
; #define PG8_LDA(dst, b, h) do { _Pragma("unroll") for (int m = 0; m < 4; ++m) _Pragma("unroll") for (int k = 0; k < 2; ++k) dst[m][k] = *(const PG8_LAS bf16x8*)(lds + PG8_SA(b, h) + aoff + m * 2048 + k * 1024); } while (0)
; #define PG8_LDB(dst, b, h) do { _Pragma("unroll") for (int n = 0; n < 2; ++n) _Pragma("unroll") for (int k = 0; k < 2; ++k) dst[n][k] = *(const PG8_LAS bf16x8*)(lds + PG8_SB(b, h) + boff + n * 2048 + k * 1024); } while (0)
; #define PG8_SCHED __builtin_amdgcn_sched_barrier(0)
; template <class Epi, class Sched, bool ALIGN_EPI = false, bool SP2 = false>
; __device__ __forceinline__ void gemm_phase(PG8_LAS unsigned char* lds, const Gemm g, const Sched& S, const Epi& E, const int wid) {
;     ...
;         const bool has_next = S.next(ui + 1, nxt);
;         const char* nA = has_next ? (const char*)g.A + (size_t)nxt.pm * tstep + (size_t)nxt.kb * kstep : cA; const char* nB = has_next ? (const char*)g.Bt + (size_t)nxt.pn * tstep + (size_t)nxt.kb * kstep : cB;
;         for (int t = 0; t < nt; t += 2) {
;             const bool last = (t == nt - 2);
;             const char* a1 = cA + (size_t)(t + 1) * kstep;
;             const char* a2 = last ? nA : cA + (size_t)(t + 2) * kstep; const char* b2 = last ? nB : cB + (size_t)(t + 2) * kstep;
;             const char* a3 = a2 + kstep; const char* b3 = b2 + kstep;
;             if (last && has_next) S.a_ready(nxt);
;             if constexpr (SP2) {
;             PG8_LDB(B0, 0, 0); PG8_LDB(B1, 0, 1); PG8_SCHED; PG8_LDA(At, 0, 0); PG8_STAGE(PG8_SA(1, 1), a1 + hstep, voffA);
;     ...
; #pragma unroll
;         for (int a = 0; a < 2; ++a)
; #pragma unroll
;             for (int b = 0; b < 2; ++b)
; #pragma unroll
;                 for (int m = 0; m < 4; ++m)
; #pragma unroll
;                     for (int n = 0; n < 2; ++n) acc[a][b][m][n] = (f32x4){0.f, 0.f, 0.f, 0.f};
;         cur = nxt; cA = nA; cB = nB; ++ui; nt = cur.kn;
.LBB0_962:
	v_lshl_add_u32 v244, s20, 8, v151
	v_ashrrev_i32_e32 v245, 31, v244
	v_lshl_add_u64 v[244:245], v[244:245], 3, s[2:3]
	global_load_dwordx2 v[228:229], v[244:245], off
	global_load_dwordx2 v[230:231], v[244:245], off offset:128
	global_load_dwordx2 v[232:233], v[244:245], off offset:256
	global_load_dwordx2 v[234:235], v[244:245], off offset:384
	global_load_dwordx2 v[236:237], v[244:245], off offset:1024
	global_load_dwordx2 v[238:239], v[244:245], off offset:1152
	global_load_dwordx2 v[240:241], v[244:245], off offset:1280
	global_load_dwordx2 v[242:243], v[244:245], off offset:1408
	s_ashr_i32 s15, s14, 31
	s_lshl_b64 s[16:17], s[14:15], 21
	s_add_u32 s16, s78, s16
	s_addc_u32 s17, s79, s17
	s_and_b64 s[18:19], s[0:1], exec
	s_cselect_b32 s15, s17, s23
	s_cselect_b32 s48, s16, s22
	s_ashr_i32 s13, s12, 31
	s_lshl_b64 s[18:19], s[12:13], 21
	s_add_u32 s18, s30, s18
	s_addc_u32 s19, s31, s19
	s_and_b64 s[26:27], s[0:1], exec
	s_cselect_b32 s13, s19, s25
	s_cselect_b32 s49, s18, s24
	s_add_u32 s22, s22, 0x100080
	s_addc_u32 s23, s23, 0
	s_add_u32 s50, s24, 0x100
	v_mov_b32_e32 v0, 0
	s_addc_u32 s51, s25, 0
	s_mov_b32 s52, -2
	v_mov_b32_e32 v1, v0
	v_mov_b32_e32 v2, v0
	v_mov_b32_e32 v3, v0
	v_mov_b32_e32 v4, v0
	v_mov_b32_e32 v5, v0
	v_mov_b32_e32 v6, v0
	v_mov_b32_e32 v7, v0
	v_mov_b32_e32 v16, v0
	v_mov_b32_e32 v17, v0
	v_mov_b32_e32 v18, v0
	v_mov_b32_e32 v19, v0
	v_mov_b32_e32 v20, v0
	v_mov_b32_e32 v21, v0
	v_mov_b32_e32 v22, v0
	v_mov_b32_e32 v23, v0
	v_mov_b32_e32 v32, v0
	v_mov_b32_e32 v33, v0
	v_mov_b32_e32 v34, v0
	v_mov_b32_e32 v35, v0
	v_mov_b32_e32 v36, v0
	v_mov_b32_e32 v37, v0
	v_mov_b32_e32 v38, v0
	v_mov_b32_e32 v39, v0
	v_mov_b32_e32 v48, v0
	v_mov_b32_e32 v49, v0
	v_mov_b32_e32 v50, v0
	v_mov_b32_e32 v51, v0
	v_mov_b32_e32 v52, v0
	v_mov_b32_e32 v53, v0
	v_mov_b32_e32 v54, v0
	v_mov_b32_e32 v55, v0
	v_mov_b32_e32 v8, v0
	v_mov_b32_e32 v9, v0
	v_mov_b32_e32 v10, v0
	v_mov_b32_e32 v11, v0
	v_mov_b32_e32 v12, v0
	v_mov_b32_e32 v13, v0
	v_mov_b32_e32 v14, v0
	v_mov_b32_e32 v15, v0
	v_mov_b32_e32 v24, v0
	v_mov_b32_e32 v25, v0
	v_mov_b32_e32 v26, v0
	v_mov_b32_e32 v27, v0
	v_mov_b32_e32 v28, v0
	v_mov_b32_e32 v29, v0
	v_mov_b32_e32 v30, v0
	v_mov_b32_e32 v31, v0
	v_mov_b32_e32 v40, v0
	v_mov_b32_e32 v41, v0
	v_mov_b32_e32 v42, v0
	v_mov_b32_e32 v43, v0
	v_mov_b32_e32 v44, v0
	v_mov_b32_e32 v45, v0
	v_mov_b32_e32 v46, v0
	v_mov_b32_e32 v47, v0
	v_mov_b32_e32 v56, v0
	v_mov_b32_e32 v57, v0
	v_mov_b32_e32 v58, v0
	v_mov_b32_e32 v59, v0
	v_mov_b32_e32 v60, v0
	v_mov_b32_e32 v61, v0
	v_mov_b32_e32 v62, v0
	v_mov_b32_e32 v63, v0
	v_mov_b32_e32 v64, v0
	v_mov_b32_e32 v65, v0
	v_mov_b32_e32 v66, v0
	v_mov_b32_e32 v67, v0
	v_mov_b32_e32 v68, v0
	v_mov_b32_e32 v69, v0
	v_mov_b32_e32 v70, v0
	v_mov_b32_e32 v71, v0
	v_mov_b32_e32 v80, v0
	v_mov_b32_e32 v81, v0
	v_mov_b32_e32 v82, v0
	v_mov_b32_e32 v83, v0
	v_mov_b32_e32 v84, v0
	v_mov_b32_e32 v85, v0
	v_mov_b32_e32 v86, v0
	v_mov_b32_e32 v87, v0
	v_mov_b32_e32 v96, v0
	v_mov_b32_e32 v97, v0
	v_mov_b32_e32 v98, v0
	v_mov_b32_e32 v99, v0
	v_mov_b32_e32 v100, v0
	v_mov_b32_e32 v101, v0
	v_mov_b32_e32 v102, v0
	v_mov_b32_e32 v103, v0
	v_mov_b32_e32 v112, v0
	v_mov_b32_e32 v113, v0
	v_mov_b32_e32 v114, v0
	v_mov_b32_e32 v115, v0
	v_mov_b32_e32 v116, v0
	v_mov_b32_e32 v117, v0
	v_mov_b32_e32 v118, v0
	v_mov_b32_e32 v119, v0
	v_mov_b32_e32 v72, v0
	v_mov_b32_e32 v73, v0
	v_mov_b32_e32 v74, v0
	v_mov_b32_e32 v75, v0
	v_mov_b32_e32 v76, v0
	v_mov_b32_e32 v77, v0
	v_mov_b32_e32 v78, v0
	v_mov_b32_e32 v79, v0
	v_mov_b32_e32 v88, v0
	v_mov_b32_e32 v89, v0
	v_mov_b32_e32 v90, v0
	v_mov_b32_e32 v91, v0
	v_mov_b32_e32 v92, v0
	v_mov_b32_e32 v93, v0
	v_mov_b32_e32 v94, v0
	v_mov_b32_e32 v95, v0
	v_mov_b32_e32 v104, v0
	v_mov_b32_e32 v105, v0
	v_mov_b32_e32 v106, v0
	v_mov_b32_e32 v107, v0
	v_mov_b32_e32 v108, v0
	v_mov_b32_e32 v109, v0
	v_mov_b32_e32 v110, v0
	v_mov_b32_e32 v111, v0
	v_mov_b32_e32 v120, v0
	v_mov_b32_e32 v121, v0
	v_mov_b32_e32 v122, v0
	v_mov_b32_e32 v123, v0
	v_mov_b32_e32 v124, v0
	v_mov_b32_e32 v125, v0
	v_mov_b32_e32 v126, v0
	v_mov_b32_e32 v127, v0
	v_add_u32_e32 v246, 0x18000, v152
	v_add_u32_e32 v248, 0x1c000, v152
.LBB0_963:
	ds_read_b128 v[146:149], v154
	ds_read_b128 v[158:161], v154 offset:1024
	ds_read_b128 v[162:165], v154 offset:2048
	ds_read_b128 v[166:169], v154 offset:3072
	ds_read_b128 v[170:173], v155
	ds_read_b128 v[174:177], v155 offset:1024
	ds_read_b128 v[178:181], v155 offset:2048
	ds_read_b128 v[182:185], v155 offset:3072
	s_add_u32 s24, s22, 0xfff00080
	s_addc_u32 s25, s23, -1
	s_cmp_eq_u32 s52, 60
	s_cselect_b32 s27, s15, s25
	s_cselect_b32 s26, s48, s24
	s_cselect_b32 s25, s13, s51
	s_cselect_b32 s24, s49, s50
	s_add_i32 m0, s21, 0xc000
	ds_read_b128 v[186:189], v156
	ds_read_b128 v[190:193], v156 offset:1024
	ds_read_b128 v[194:197], v156 offset:2048
	ds_read_b128 v[198:201], v156 offset:3072
	ds_read_b128 v[202:205], v156 offset:4096
	ds_read_b128 v[206:209], v156 offset:5120
	ds_read_b128 v[210:213], v156 offset:6144
	ds_read_b128 v[214:217], v156 offset:7168
	global_load_lds_dwordx4 v138, s[22:23]
	s_add_i32 m0, s21, 0xe000
	s_nop 0
	global_load_lds_dwordx4 v140, s[22:23]
	s_waitcnt vmcnt(8)
	s_waitcnt lgkmcnt(0)
	s_setprio 1
	s_barrier
; #define PG8_STAGE(bufoff, gbase, voff) do { _Pragma("unroll") for (int _i = 0; _i < 2; ++_i) \
;         __builtin_amdgcn_global_load_lds((const unsigned*)((const char*)(gbase) + (voff)[_i]), (PG8_LAS unsigned*)(lds + (bufoff) + ldsw + _i * 8192), 16, 0, 0); } while (0)
; #define PG8_LDA(dst, b, h) do { _Pragma("unroll") for (int m = 0; m < 4; ++m) _Pragma("unroll") for (int k = 0; k < 2; ++k) dst[m][k] = *(const PG8_LAS bf16x8*)(lds + PG8_SA(b, h) + aoff + m * 2048 + k * 1024); } while (0)
; #define PG8_MMA(ai, bj, At, Bt) do { __builtin_amdgcn_s_setprio(1); _Pragma("unroll") for (int m = 0; m < 4; ++m) _Pragma("unroll") for (int n = 0; n < 2; ++n) _Pragma("unroll") for (int k = 0; k < 2; ++k) \
;         acc[ai][bj][m][n] = __builtin_amdgcn_mfma_f32_16x16x32_bf16(Bt[n][k], At[m][k], acc[ai][bj][m][n], 0, 0, 0); __builtin_amdgcn_s_setprio(0); } while (0)
; #define PG8_WAIT_V(n) asm volatile("s_waitcnt vmcnt(" #n ")" ::: "memory")
; #define PG8_WAIT_L(n) asm volatile("s_waitcnt lgkmcnt(" #n ")" ::: "memory")
; #define PG8_BAR __builtin_amdgcn_s_barrier()
; #define PG8_SCHED __builtin_amdgcn_sched_barrier(0)
; template <class Epi, class Sched, bool ALIGN_EPI = false, bool SP2 = false>
; __device__ __forceinline__ void gemm_phase(PG8_LAS unsigned char* lds, const Gemm g, const Sched& S, const Epi& E, const int wid) {
;     ...
;             PG8_WAIT_V(8); PG8_WAIT_L(0); PG8_BAR; PG8_MMA(0, 0, At, B0); PG8_MMA(0, 1, At, B1); PG8_BAR; PG8_SCHED;
;             PG8_LDA(At, 0, 1); PG8_STAGE(PG8_SB(0, 0), b2, voffB); PG8_STAGE(PG8_SB(0, 1), b2 + hstep, voffB); PG8_STAGE(PG8_SA(0, 0), a2, voffA);
;             PG8_WAIT_V(8); PG8_WAIT_L(0); PG8_BAR; PG8_MMA(1, 0, At, B0); PG8_MMA(1, 1, At, B1); PG8_BAR; PG8_SCHED;
	v_mfma_f32_16x16x32_bf16 v[124:127], v[146:149], v[186:189], v[124:127]
	v_mfma_f32_16x16x32_bf16 v[120:123], v[162:165], v[186:189], v[120:123]
	v_mfma_f32_16x16x32_bf16 v[108:111], v[146:149], v[194:197], v[108:111]
	v_mfma_f32_16x16x32_bf16 v[104:107], v[162:165], v[194:197], v[104:107]
	v_mfma_f32_16x16x32_bf16 v[92:95], v[146:149], v[202:205], v[92:95]
	v_mfma_f32_16x16x32_bf16 v[88:91], v[162:165], v[202:205], v[88:91]
	v_mfma_f32_16x16x32_bf16 v[76:79], v[146:149], v[210:213], v[76:79]
	v_mfma_f32_16x16x32_bf16 v[72:75], v[162:165], v[210:213], v[72:75]
	v_mfma_f32_16x16x32_bf16 v[124:127], v[158:161], v[190:193], v[124:127]
	v_mfma_f32_16x16x32_bf16 v[120:123], v[166:169], v[190:193], v[120:123]
	v_mfma_f32_16x16x32_bf16 v[108:111], v[158:161], v[198:201], v[108:111]
	v_mfma_f32_16x16x32_bf16 v[104:107], v[166:169], v[198:201], v[104:107]
	v_mfma_f32_16x16x32_bf16 v[92:95], v[158:161], v[206:209], v[92:95]
	v_mfma_f32_16x16x32_bf16 v[88:91], v[166:169], v[206:209], v[88:91]
	v_mfma_f32_16x16x32_bf16 v[76:79], v[158:161], v[214:217], v[76:79]
	v_mfma_f32_16x16x32_bf16 v[72:75], v[166:169], v[214:217], v[72:75]
	v_mfma_f32_16x16x32_bf16 v[116:119], v[170:173], v[186:189], v[116:119]
	v_mfma_f32_16x16x32_bf16 v[112:115], v[178:181], v[186:189], v[112:115]
	v_mfma_f32_16x16x32_bf16 v[100:103], v[170:173], v[194:197], v[100:103]
	v_mfma_f32_16x16x32_bf16 v[96:99], v[178:181], v[194:197], v[96:99]
	v_mfma_f32_16x16x32_bf16 v[84:87], v[170:173], v[202:205], v[84:87]
	v_mfma_f32_16x16x32_bf16 v[80:83], v[178:181], v[202:205], v[80:83]
	v_mfma_f32_16x16x32_bf16 v[68:71], v[170:173], v[210:213], v[68:71]
	v_mfma_f32_16x16x32_bf16 v[64:67], v[178:181], v[210:213], v[64:67]
	v_mfma_f32_16x16x32_bf16 v[116:119], v[174:177], v[190:193], v[116:119]
	v_mfma_f32_16x16x32_bf16 v[112:115], v[182:185], v[190:193], v[112:115]
	v_mfma_f32_16x16x32_bf16 v[100:103], v[174:177], v[198:201], v[100:103]
	v_mfma_f32_16x16x32_bf16 v[96:99], v[182:185], v[198:201], v[96:99]
	v_mfma_f32_16x16x32_bf16 v[84:87], v[174:177], v[206:209], v[84:87]
	v_mfma_f32_16x16x32_bf16 v[80:83], v[182:185], v[206:209], v[80:83]
	v_mfma_f32_16x16x32_bf16 v[68:71], v[174:177], v[214:217], v[68:71]
	v_mfma_f32_16x16x32_bf16 v[64:67], v[182:185], v[214:217], v[64:67]
	s_barrier
	s_setprio 0
	s_add_i32 s53, s41, s29
	s_mov_b32 m0, s53
	ds_read_b128 v[186:189], v156 offset:16384
	ds_read_b128 v[190:193], v156 offset:17408
	ds_read_b128 v[194:197], v156 offset:18432
	ds_read_b128 v[198:201], v156 offset:19456
	ds_read_b128 v[202:205], v156 offset:20480
	ds_read_b128 v[206:209], v156 offset:21504
	ds_read_b128 v[210:213], v156 offset:22528
	ds_read_b128 v[214:217], v156 offset:23552
	global_load_lds_dwordx4 v130, s[24:25]
	s_add_i32 m0, s53, 0x2000
	s_add_u32 s54, s24, 0x100000
	s_addc_u32 s55, s25, 0
	s_add_i32 s53, s42, s29
	global_load_lds_dwordx4 v134, s[24:25]
	s_mov_b32 m0, s53
	global_load_lds_dwordx4 v130, s[54:55]
	s_add_i32 m0, s53, 0x2000
	s_nop 0
	global_load_lds_dwordx4 v134, s[54:55]
	s_mov_b32 m0, s21
	s_nop 0
	global_load_lds_dwordx4 v128, s[26:27]
	s_mov_b32 m0, s34
	s_nop 0
	global_load_lds_dwordx4 v132, s[26:27]
	s_waitcnt vmcnt(8)
	s_waitcnt lgkmcnt(0)
	s_setprio 1
	s_barrier
	v_mfma_f32_16x16x32_bf16 v[60:63], v[146:149], v[186:189], v[60:63]
	v_mfma_f32_16x16x32_bf16 v[56:59], v[162:165], v[186:189], v[56:59]
	v_mfma_f32_16x16x32_bf16 v[44:47], v[146:149], v[194:197], v[44:47]
	v_mfma_f32_16x16x32_bf16 v[40:43], v[162:165], v[194:197], v[40:43]
	v_mfma_f32_16x16x32_bf16 v[28:31], v[146:149], v[202:205], v[28:31]
	v_mfma_f32_16x16x32_bf16 v[24:27], v[162:165], v[202:205], v[24:27]
	v_mfma_f32_16x16x32_bf16 v[12:15], v[146:149], v[210:213], v[12:15]
	v_mfma_f32_16x16x32_bf16 v[8:11], v[162:165], v[210:213], v[8:11]
	v_mfma_f32_16x16x32_bf16 v[60:63], v[158:161], v[190:193], v[60:63]
	v_mfma_f32_16x16x32_bf16 v[56:59], v[166:169], v[190:193], v[56:59]
	v_mfma_f32_16x16x32_bf16 v[44:47], v[158:161], v[198:201], v[44:47]
	v_mfma_f32_16x16x32_bf16 v[40:43], v[166:169], v[198:201], v[40:43]
	v_mfma_f32_16x16x32_bf16 v[28:31], v[158:161], v[206:209], v[28:31]
	v_mfma_f32_16x16x32_bf16 v[24:27], v[166:169], v[206:209], v[24:27]
	v_mfma_f32_16x16x32_bf16 v[12:15], v[158:161], v[214:217], v[12:15]
	v_mfma_f32_16x16x32_bf16 v[8:11], v[166:169], v[214:217], v[8:11]
	v_mfma_f32_16x16x32_bf16 v[52:55], v[170:173], v[186:189], v[52:55]
	v_mfma_f32_16x16x32_bf16 v[48:51], v[178:181], v[186:189], v[48:51]
	v_mfma_f32_16x16x32_bf16 v[36:39], v[170:173], v[194:197], v[36:39]
	v_mfma_f32_16x16x32_bf16 v[32:35], v[178:181], v[194:197], v[32:35]
	v_mfma_f32_16x16x32_bf16 v[20:23], v[170:173], v[202:205], v[20:23]
	v_mfma_f32_16x16x32_bf16 v[16:19], v[178:181], v[202:205], v[16:19]
	v_mfma_f32_16x16x32_bf16 v[4:7], v[170:173], v[210:213], v[4:7]
	v_mfma_f32_16x16x32_bf16 v[0:3], v[178:181], v[210:213], v[0:3]
	v_mfma_f32_16x16x32_bf16 v[52:55], v[174:177], v[190:193], v[52:55]
	v_mfma_f32_16x16x32_bf16 v[48:51], v[182:185], v[190:193], v[48:51]
	v_mfma_f32_16x16x32_bf16 v[36:39], v[174:177], v[198:201], v[36:39]
	v_mfma_f32_16x16x32_bf16 v[32:35], v[182:185], v[198:201], v[32:35]
	v_mfma_f32_16x16x32_bf16 v[20:23], v[174:177], v[206:209], v[20:23]
	v_mfma_f32_16x16x32_bf16 v[16:19], v[182:185], v[206:209], v[16:19]
	v_mfma_f32_16x16x32_bf16 v[4:7], v[174:177], v[214:217], v[4:7]
	v_mfma_f32_16x16x32_bf16 v[0:3], v[182:185], v[214:217], v[0:3]
	s_barrier
; #define PG8_STAGE(bufoff, gbase, voff) do { _Pragma("unroll") for (int _i = 0; _i < 2; ++_i) \
;         __builtin_amdgcn_global_load_lds((const unsigned*)((const char*)(gbase) + (voff)[_i]), (PG8_LAS unsigned*)(lds + (bufoff) + ldsw + _i * 8192), 16, 0, 0); } while (0)
; #define PG8_LDA(dst, b, h) do { _Pragma("unroll") for (int m = 0; m < 4; ++m) _Pragma("unroll") for (int k = 0; k < 2; ++k) dst[m][k] = *(const PG8_LAS bf16x8*)(lds + PG8_SA(b, h) + aoff + m * 2048 + k * 1024); } while (0)
; #define PG8_LDB(dst, b, h) do { _Pragma("unroll") for (int n = 0; n < 2; ++n) _Pragma("unroll") for (int k = 0; k < 2; ++k) dst[n][k] = *(const PG8_LAS bf16x8*)(lds + PG8_SB(b, h) + boff + n * 2048 + k * 1024); } while (0)
; #define PG8_MMA(ai, bj, At, Bt) do { __builtin_amdgcn_s_setprio(1); _Pragma("unroll") for (int m = 0; m < 4; ++m) _Pragma("unroll") for (int n = 0; n < 2; ++n) _Pragma("unroll") for (int k = 0; k < 2; ++k) \
;         acc[ai][bj][m][n] = __builtin_amdgcn_mfma_f32_16x16x32_bf16(Bt[n][k], At[m][k], acc[ai][bj][m][n], 0, 0, 0); __builtin_amdgcn_s_setprio(0); } while (0)
; #define PG8_WAIT_V(n) asm volatile("s_waitcnt vmcnt(" #n ")" ::: "memory")
; #define PG8_WAIT_L(n) asm volatile("s_waitcnt lgkmcnt(" #n ")" ::: "memory")
; #define PG8_BAR __builtin_amdgcn_s_barrier()
; #define PG8_SCHED __builtin_amdgcn_sched_barrier(0)
; template <class Epi, class Sched, bool ALIGN_EPI = false, bool SP2 = false>
; __device__ __forceinline__ void gemm_phase(PG8_LAS unsigned char* lds, const Gemm g, const Sched& S, const Epi& E, const int wid) {
;     ...
;         for (int t = 0; t < nt; t += 2) {
;     ...
;             PG8_LDB(B0, 1, 0); PG8_LDB(B1, 1, 1); PG8_SCHED; PG8_LDA(At, 1, 0); PG8_STAGE(PG8_SA(0, 1), a2 + hstep, voffA);
;             PG8_WAIT_V(8); PG8_WAIT_L(0); PG8_BAR; PG8_MMA(0, 0, At, B0); PG8_MMA(0, 1, At, B1); PG8_BAR; PG8_SCHED;
;             PG8_LDA(At, 1, 1); PG8_STAGE(PG8_SB(1, 0), b3, voffB); PG8_STAGE(PG8_SB(1, 1), b3 + hstep, voffB); PG8_STAGE(PG8_SA(1, 0), a3, voffA);
;             PG8_WAIT_V(8); PG8_WAIT_L(0); PG8_BAR; PG8_MMA(1, 0, At, B0); PG8_MMA(1, 1, At, B1); PG8_BAR; PG8_SCHED;
	s_setprio 0
	s_add_i32 s53, 0, 0x18000
	s_add_i32 s54, 0, 0x1c000
	ds_read_b128 v[146:149], v246
	ds_read_b128 v[158:161], v246 offset:1024
	ds_read_b128 v[162:165], v246 offset:2048
	ds_read_b128 v[166:169], v246 offset:3072
	ds_read_b128 v[170:173], v248
	ds_read_b128 v[174:177], v248 offset:1024
	ds_read_b128 v[178:181], v248 offset:2048
	ds_read_b128 v[182:185], v248 offset:3072
	s_add_u32 s26, s26, 0x100000
	s_addc_u32 s27, s27, 0
	s_mov_b32 m0, s35
	ds_read_b128 v[186:189], v156 offset:32768
	ds_read_b128 v[190:193], v156 offset:33792
	ds_read_b128 v[194:197], v156 offset:34816
	ds_read_b128 v[198:201], v156 offset:35840
	ds_read_b128 v[202:205], v156 offset:36864
	ds_read_b128 v[206:209], v156 offset:37888
	ds_read_b128 v[210:213], v156 offset:38912
	ds_read_b128 v[214:217], v156 offset:39936
	global_load_lds_dwordx4 v128, s[26:27]
	s_mov_b32 m0, s36
	s_nop 0
	global_load_lds_dwordx4 v132, s[26:27]
	s_waitcnt vmcnt(8)
	s_waitcnt lgkmcnt(0)
	s_setprio 1
	s_barrier
	v_mfma_f32_16x16x32_bf16 v[124:127], v[146:149], v[186:189], v[124:127]
	v_mfma_f32_16x16x32_bf16 v[120:123], v[162:165], v[186:189], v[120:123]
	v_mfma_f32_16x16x32_bf16 v[108:111], v[146:149], v[194:197], v[108:111]
	v_mfma_f32_16x16x32_bf16 v[104:107], v[162:165], v[194:197], v[104:107]
	v_mfma_f32_16x16x32_bf16 v[92:95], v[146:149], v[202:205], v[92:95]
	v_mfma_f32_16x16x32_bf16 v[88:91], v[162:165], v[202:205], v[88:91]
	v_mfma_f32_16x16x32_bf16 v[76:79], v[146:149], v[210:213], v[76:79]
	v_mfma_f32_16x16x32_bf16 v[72:75], v[162:165], v[210:213], v[72:75]
	v_mfma_f32_16x16x32_bf16 v[124:127], v[158:161], v[190:193], v[124:127]
	v_mfma_f32_16x16x32_bf16 v[120:123], v[166:169], v[190:193], v[120:123]
	v_mfma_f32_16x16x32_bf16 v[108:111], v[158:161], v[198:201], v[108:111]
	v_mfma_f32_16x16x32_bf16 v[104:107], v[166:169], v[198:201], v[104:107]
	v_mfma_f32_16x16x32_bf16 v[92:95], v[158:161], v[206:209], v[92:95]
	v_mfma_f32_16x16x32_bf16 v[88:91], v[166:169], v[206:209], v[88:91]
	v_mfma_f32_16x16x32_bf16 v[76:79], v[158:161], v[214:217], v[76:79]
	v_mfma_f32_16x16x32_bf16 v[72:75], v[166:169], v[214:217], v[72:75]
	v_mfma_f32_16x16x32_bf16 v[116:119], v[170:173], v[186:189], v[116:119]
	v_mfma_f32_16x16x32_bf16 v[112:115], v[178:181], v[186:189], v[112:115]
	v_mfma_f32_16x16x32_bf16 v[100:103], v[170:173], v[194:197], v[100:103]
	v_mfma_f32_16x16x32_bf16 v[96:99], v[178:181], v[194:197], v[96:99]
	v_mfma_f32_16x16x32_bf16 v[84:87], v[170:173], v[202:205], v[84:87]
	v_mfma_f32_16x16x32_bf16 v[80:83], v[178:181], v[202:205], v[80:83]
	v_mfma_f32_16x16x32_bf16 v[68:71], v[170:173], v[210:213], v[68:71]
	v_mfma_f32_16x16x32_bf16 v[64:67], v[178:181], v[210:213], v[64:67]
	v_mfma_f32_16x16x32_bf16 v[116:119], v[174:177], v[190:193], v[116:119]
	v_mfma_f32_16x16x32_bf16 v[112:115], v[182:185], v[190:193], v[112:115]
	v_mfma_f32_16x16x32_bf16 v[100:103], v[174:177], v[198:201], v[100:103]
	v_mfma_f32_16x16x32_bf16 v[96:99], v[182:185], v[198:201], v[96:99]
	v_mfma_f32_16x16x32_bf16 v[84:87], v[174:177], v[206:209], v[84:87]
	v_mfma_f32_16x16x32_bf16 v[80:83], v[182:185], v[206:209], v[80:83]
	v_mfma_f32_16x16x32_bf16 v[68:71], v[174:177], v[214:217], v[68:71]
	v_mfma_f32_16x16x32_bf16 v[64:67], v[182:185], v[214:217], v[64:67]
	s_barrier
	s_setprio 0
	s_add_u32 s98, s24, 0x80
	s_addc_u32 s99, s25, 0
	s_add_u32 s100, s26, 0xfff00080
	s_addc_u32 s101, s27, -1
	s_add_i32 s26, s53, s29
	s_mov_b32 m0, s26
	ds_read_b128 v[186:189], v156 offset:49152
	ds_read_b128 v[190:193], v156 offset:50176
	ds_read_b128 v[194:197], v156 offset:51200
	ds_read_b128 v[198:201], v156 offset:52224
	ds_read_b128 v[202:205], v156 offset:53248
	ds_read_b128 v[206:209], v156 offset:54272
	ds_read_b128 v[210:213], v156 offset:55296
	ds_read_b128 v[214:217], v156 offset:56320
	global_load_lds_dwordx4 v130, s[98:99]
	s_add_i32 m0, s26, 0x2000
	s_add_u32 s24, s24, 0x100080
	s_addc_u32 s25, s25, 0
	s_add_i32 s26, s54, s29
	global_load_lds_dwordx4 v134, s[98:99]
	s_mov_b32 m0, s26
	s_nop 0
	global_load_lds_dwordx4 v130, s[24:25]
	s_add_i32 m0, s26, 0x2000
	s_nop 0
	global_load_lds_dwordx4 v134, s[24:25]
	s_mov_b32 m0, s38
	s_nop 0
	global_load_lds_dwordx4 v128, s[100:101]
	s_mov_b32 m0, s39
	s_nop 0
	global_load_lds_dwordx4 v132, s[100:101]
	s_waitcnt vmcnt(8)
	s_waitcnt lgkmcnt(0)
	s_setprio 1
	s_barrier
	v_mfma_f32_16x16x32_bf16 v[60:63], v[146:149], v[186:189], v[60:63]
	v_mfma_f32_16x16x32_bf16 v[56:59], v[162:165], v[186:189], v[56:59]
	v_mfma_f32_16x16x32_bf16 v[44:47], v[146:149], v[194:197], v[44:47]
	v_mfma_f32_16x16x32_bf16 v[40:43], v[162:165], v[194:197], v[40:43]
	v_mfma_f32_16x16x32_bf16 v[28:31], v[146:149], v[202:205], v[28:31]
	v_mfma_f32_16x16x32_bf16 v[24:27], v[162:165], v[202:205], v[24:27]
	v_mfma_f32_16x16x32_bf16 v[12:15], v[146:149], v[210:213], v[12:15]
	v_mfma_f32_16x16x32_bf16 v[8:11], v[162:165], v[210:213], v[8:11]
	v_mfma_f32_16x16x32_bf16 v[60:63], v[158:161], v[190:193], v[60:63]
	v_mfma_f32_16x16x32_bf16 v[56:59], v[166:169], v[190:193], v[56:59]
	v_mfma_f32_16x16x32_bf16 v[44:47], v[158:161], v[198:201], v[44:47]
	v_mfma_f32_16x16x32_bf16 v[40:43], v[166:169], v[198:201], v[40:43]
	v_mfma_f32_16x16x32_bf16 v[28:31], v[158:161], v[206:209], v[28:31]
	v_mfma_f32_16x16x32_bf16 v[24:27], v[166:169], v[206:209], v[24:27]
	v_mfma_f32_16x16x32_bf16 v[12:15], v[158:161], v[214:217], v[12:15]
	v_mfma_f32_16x16x32_bf16 v[8:11], v[166:169], v[214:217], v[8:11]
	v_mfma_f32_16x16x32_bf16 v[52:55], v[170:173], v[186:189], v[52:55]
	v_mfma_f32_16x16x32_bf16 v[48:51], v[178:181], v[186:189], v[48:51]
	v_mfma_f32_16x16x32_bf16 v[36:39], v[170:173], v[194:197], v[36:39]
	v_mfma_f32_16x16x32_bf16 v[32:35], v[178:181], v[194:197], v[32:35]
	v_mfma_f32_16x16x32_bf16 v[20:23], v[170:173], v[202:205], v[20:23]
	v_mfma_f32_16x16x32_bf16 v[16:19], v[178:181], v[202:205], v[16:19]
	v_mfma_f32_16x16x32_bf16 v[4:7], v[170:173], v[210:213], v[4:7]
	v_mfma_f32_16x16x32_bf16 v[0:3], v[178:181], v[210:213], v[0:3]
	v_mfma_f32_16x16x32_bf16 v[52:55], v[174:177], v[190:193], v[52:55]
	v_mfma_f32_16x16x32_bf16 v[48:51], v[182:185], v[190:193], v[48:51]
	v_mfma_f32_16x16x32_bf16 v[36:39], v[174:177], v[198:201], v[36:39]
	v_mfma_f32_16x16x32_bf16 v[32:35], v[182:185], v[198:201], v[32:35]
	v_mfma_f32_16x16x32_bf16 v[20:23], v[174:177], v[206:209], v[20:23]
	v_mfma_f32_16x16x32_bf16 v[16:19], v[182:185], v[206:209], v[16:19]
	v_mfma_f32_16x16x32_bf16 v[4:7], v[174:177], v[214:217], v[4:7]
	v_mfma_f32_16x16x32_bf16 v[0:3], v[182:185], v[214:217], v[0:3]
	s_barrier
	s_setprio 0
	s_add_i32 s52, s52, 2
	s_add_u32 s22, s22, 0x100
	s_addc_u32 s23, s23, 0
	s_add_u32 s50, s50, 0x100
	s_addc_u32 s51, s51, 0
	s_cmp_gt_u32 s52, 61
	s_cbranch_scc0 .LBB0_963
	s_and_b64 vcc, exec, s[10:11]
	s_cbranch_vccz .LBB0_966
	s_barrier

; #define PG8_STAGE(bufoff, gbase, voff) do { _Pragma("unroll") for (int _i = 0; _i < 2; ++_i) \
;         __builtin_amdgcn_global_load_lds((const unsigned*)((const char*)(gbase) + (voff)[_i]), (PG8_LAS unsigned*)(lds + (bufoff) + ldsw + _i * 8192), 16, 0, 0); } while (0)
; #define PG8_LDA(dst, b, h) do { _Pragma("unroll") for (int m = 0; m < 4; ++m) _Pragma("unroll") for (int k = 0; k < 2; ++k) dst[m][k] = *(const PG8_LAS bf16x8*)(lds + PG8_SA(b, h) + aoff + m * 2048 + k * 1024); } while (0)
; #define PG8_LDB(dst, b, h) do { _Pragma("unroll") for (int n = 0; n < 2; ++n) _Pragma("unroll") for (int k = 0; k < 2; ++k) dst[n][k] = *(const PG8_LAS bf16x8*)(lds + PG8_SB(b, h) + boff + n * 2048 + k * 1024); } while (0)
; #define PG8_MMA(ai, bj, At, Bt) do { __builtin_amdgcn_s_setprio(1); _Pragma("unroll") for (int m = 0; m < 4; ++m) _Pragma("unroll") for (int n = 0; n < 2; ++n) _Pragma("unroll") for (int k = 0; k < 2; ++k) \
;         acc[ai][bj][m][n] = __builtin_amdgcn_mfma_f32_16x16x32_bf16(Bt[n][k], At[m][k], acc[ai][bj][m][n], 0, 0, 0); __builtin_amdgcn_s_setprio(0); } while (0)
; #define PG8_WAIT_V(n) asm volatile("s_waitcnt vmcnt(" #n ")" ::: "memory")
; #define PG8_WAIT_L(n) asm volatile("s_waitcnt lgkmcnt(" #n ")" ::: "memory")
; template <class Epi, class Sched, bool ALIGN_EPI = false, bool SP2 = false>
; __device__ __forceinline__ void gemm_phase(PG8_LAS unsigned char* lds, const Gemm g, const Sched& S, const Epi& E, const int wid) {
;     ...
;         const char* nA = has_next ? (const char*)g.A + (size_t)nxt.pm * tstep + (size_t)nxt.kb * kstep : cA; const char* nB = has_next ? (const char*)g.Bt + (size_t)nxt.pn * tstep + (size_t)nxt.kb * kstep : cB;
;         for (int t = 0; t < nt; t += 2) {
;             const bool last = (t == nt - 2);
;             const char* a1 = cA + (size_t)(t + 1) * kstep;
;             const char* a2 = last ? nA : cA + (size_t)(t + 2) * kstep; const char* b2 = last ? nB : cB + (size_t)(t + 2) * kstep;
;             const char* a3 = a2 + kstep; const char* b3 = b2 + kstep;
;             if (last && has_next) S.a_ready(nxt);
;             if constexpr (SP2) {
;             PG8_LDB(B0, 0, 0); PG8_LDB(B1, 0, 1); PG8_SCHED; PG8_LDA(At, 0, 0); PG8_STAGE(PG8_SA(1, 1), a1 + hstep, voffA);
;             PG8_WAIT_V(8); PG8_WAIT_L(0); PG8_BAR; PG8_MMA(0, 0, At, B0); PG8_MMA(0, 1, At, B1); PG8_BAR; PG8_SCHED;
.LBB0_1137:
	s_add_i32 s13, s53, -2
	s_add_u32 s54, s20, 0x100
	s_waitcnt vmcnt(0)
	v_mov_b32_e32 v64, 0
	s_addc_u32 s55, s21, 0
	s_mov_b32 s22, 0
	v_mov_b32_e32 v65, v64
	v_mov_b32_e32 v66, v64
	v_mov_b32_e32 v67, v64
	v_mov_b32_e32 v68, v64
	v_mov_b32_e32 v69, v64
	v_mov_b32_e32 v70, v64
	v_mov_b32_e32 v71, v64
	v_mov_b32_e32 v80, v64
	v_mov_b32_e32 v81, v64
	v_mov_b32_e32 v82, v64
	v_mov_b32_e32 v83, v64
	v_mov_b32_e32 v84, v64
	v_mov_b32_e32 v85, v64
	v_mov_b32_e32 v86, v64
	v_mov_b32_e32 v87, v64
	v_mov_b32_e32 v96, v64
	v_mov_b32_e32 v97, v64
	v_mov_b32_e32 v98, v64
	v_mov_b32_e32 v99, v64
	v_mov_b32_e32 v100, v64
	v_mov_b32_e32 v101, v64
	v_mov_b32_e32 v102, v64
	v_mov_b32_e32 v103, v64
	v_mov_b32_e32 v112, v64
	v_mov_b32_e32 v113, v64
	v_mov_b32_e32 v114, v64
	v_mov_b32_e32 v115, v64
	v_mov_b32_e32 v116, v64
	v_mov_b32_e32 v117, v64
	v_mov_b32_e32 v118, v64
	v_mov_b32_e32 v119, v64
	v_mov_b32_e32 v72, v64
	v_mov_b32_e32 v73, v64
	v_mov_b32_e32 v74, v64
	v_mov_b32_e32 v75, v64
	v_mov_b32_e32 v76, v64
	v_mov_b32_e32 v77, v64
	v_mov_b32_e32 v78, v64
	v_mov_b32_e32 v79, v64
	v_mov_b32_e32 v88, v64
	v_mov_b32_e32 v89, v64
	v_mov_b32_e32 v90, v64
	v_mov_b32_e32 v91, v64
	v_mov_b32_e32 v92, v64
	v_mov_b32_e32 v93, v64
	v_mov_b32_e32 v94, v64
	v_mov_b32_e32 v95, v64
	v_mov_b32_e32 v104, v64
	v_mov_b32_e32 v105, v64
	v_mov_b32_e32 v106, v64
	v_mov_b32_e32 v107, v64
	v_mov_b32_e32 v108, v64
	v_mov_b32_e32 v109, v64
	v_mov_b32_e32 v110, v64
	v_mov_b32_e32 v111, v64
	v_mov_b32_e32 v120, v64
	v_mov_b32_e32 v121, v64
	v_mov_b32_e32 v122, v64
	v_mov_b32_e32 v123, v64
	v_mov_b32_e32 v124, v64
	v_mov_b32_e32 v125, v64
	v_mov_b32_e32 v126, v64
	v_mov_b32_e32 v127, v64
	v_mov_b32_e32 v0, v64
	v_mov_b32_e32 v1, v64
	v_mov_b32_e32 v2, v64
	v_mov_b32_e32 v3, v64
	v_mov_b32_e32 v4, v64
	v_mov_b32_e32 v5, v64
	v_mov_b32_e32 v6, v64
	v_mov_b32_e32 v7, v64
	v_mov_b32_e32 v16, v64
	v_mov_b32_e32 v17, v64
	v_mov_b32_e32 v18, v64
	v_mov_b32_e32 v19, v64
	v_mov_b32_e32 v20, v64
	v_mov_b32_e32 v21, v64
	v_mov_b32_e32 v22, v64
	v_mov_b32_e32 v23, v64
	v_mov_b32_e32 v32, v64
	v_mov_b32_e32 v33, v64
	v_mov_b32_e32 v34, v64
	v_mov_b32_e32 v35, v64
	v_mov_b32_e32 v36, v64
	v_mov_b32_e32 v37, v64
	v_mov_b32_e32 v38, v64
	v_mov_b32_e32 v39, v64
	v_mov_b32_e32 v48, v64
	v_mov_b32_e32 v49, v64
	v_mov_b32_e32 v50, v64
	v_mov_b32_e32 v51, v64
	v_mov_b32_e32 v52, v64
	v_mov_b32_e32 v53, v64
	v_mov_b32_e32 v54, v64
	v_mov_b32_e32 v55, v64
	v_mov_b32_e32 v8, v64
	v_mov_b32_e32 v9, v64
	v_mov_b32_e32 v10, v64
	v_mov_b32_e32 v11, v64
	v_mov_b32_e32 v12, v64
	v_mov_b32_e32 v13, v64
	v_mov_b32_e32 v14, v64
	v_mov_b32_e32 v15, v64
	v_mov_b32_e32 v24, v64
	v_mov_b32_e32 v25, v64
	v_mov_b32_e32 v26, v64
	v_mov_b32_e32 v27, v64
	v_mov_b32_e32 v28, v64
	v_mov_b32_e32 v29, v64
	v_mov_b32_e32 v30, v64
	v_mov_b32_e32 v31, v64
	v_mov_b32_e32 v40, v64
	v_mov_b32_e32 v41, v64
	v_mov_b32_e32 v42, v64
	v_mov_b32_e32 v43, v64
	v_mov_b32_e32 v44, v64
	v_mov_b32_e32 v45, v64
	v_mov_b32_e32 v46, v64
	v_mov_b32_e32 v47, v64
	v_mov_b32_e32 v56, v64
	v_mov_b32_e32 v57, v64
	v_mov_b32_e32 v58, v64
	v_mov_b32_e32 v59, v64
	v_mov_b32_e32 v60, v64
	v_mov_b32_e32 v61, v64
	v_mov_b32_e32 v62, v64
	v_mov_b32_e32 v63, v64
	v_add_u32_e32 v246, 0x18000, v195
	v_add_u32_e32 v248, 0x1c000, v195
.LBB0_1138:
	ds_read_b128 v[128:131], v197
	ds_read_b128 v[132:135], v197 offset:1024
	ds_read_b128 v[136:139], v197 offset:2048
	ds_read_b128 v[140:143], v197 offset:3072
	ds_read_b128 v[144:147], v198
	ds_read_b128 v[148:151], v198 offset:1024
	ds_read_b128 v[174:177], v198 offset:2048
	ds_read_b128 v[178:181], v198 offset:3072
	s_add_i32 s56, s22, 2
	s_add_u32 s20, s18, 0x100
	s_addc_u32 s21, s19, 0
	s_cmp_eq_u32 s13, s22
	s_cselect_b32 s22, s16, s54
	s_cselect_b32 s25, s15, s21
	s_cselect_b32 s24, s14, s20
	s_cselect_b32 s23, s17, s55
	s_add_i32 m0, s29, 0xc000
	ds_read_b128 v[182:185], v199
	ds_read_b128 v[186:189], v199 offset:1024
	ds_read_b128 v[200:203], v199 offset:2048
	ds_read_b128 v[204:207], v199 offset:3072
	ds_read_b128 v[208:211], v199 offset:4096
	ds_read_b128 v[212:215], v199 offset:5120
	ds_read_b128 v[216:219], v199 offset:6144
	ds_read_b128 v[220:223], v199 offset:7168
	global_load_lds_dwordx4 v168, s[18:19]
	s_add_i32 m0, s29, 0xe000
	s_nop 0
	global_load_lds_dwordx4 v170, s[18:19]
	s_waitcnt vmcnt(8)
	s_waitcnt lgkmcnt(0)
	s_setprio 1
	s_barrier
	v_mfma_f32_16x16x32_bf16 v[60:63], v[128:131], v[182:185], v[60:63]
	v_mfma_f32_16x16x32_bf16 v[56:59], v[136:139], v[182:185], v[56:59]
	v_mfma_f32_16x16x32_bf16 v[44:47], v[128:131], v[200:203], v[44:47]
	v_mfma_f32_16x16x32_bf16 v[40:43], v[136:139], v[200:203], v[40:43]
	v_mfma_f32_16x16x32_bf16 v[28:31], v[128:131], v[208:211], v[28:31]
	v_mfma_f32_16x16x32_bf16 v[24:27], v[136:139], v[208:211], v[24:27]
	v_mfma_f32_16x16x32_bf16 v[12:15], v[128:131], v[216:219], v[12:15]
	v_mfma_f32_16x16x32_bf16 v[8:11], v[136:139], v[216:219], v[8:11]
	v_mfma_f32_16x16x32_bf16 v[60:63], v[132:135], v[186:189], v[60:63]
	v_mfma_f32_16x16x32_bf16 v[56:59], v[140:143], v[186:189], v[56:59]
	v_mfma_f32_16x16x32_bf16 v[44:47], v[132:135], v[204:207], v[44:47]
	v_mfma_f32_16x16x32_bf16 v[40:43], v[140:143], v[204:207], v[40:43]
	v_mfma_f32_16x16x32_bf16 v[28:31], v[132:135], v[212:215], v[28:31]
	v_mfma_f32_16x16x32_bf16 v[24:27], v[140:143], v[212:215], v[24:27]
	v_mfma_f32_16x16x32_bf16 v[12:15], v[132:135], v[220:223], v[12:15]
	v_mfma_f32_16x16x32_bf16 v[8:11], v[140:143], v[220:223], v[8:11]
	v_mfma_f32_16x16x32_bf16 v[52:55], v[144:147], v[182:185], v[52:55]
	v_mfma_f32_16x16x32_bf16 v[48:51], v[174:177], v[182:185], v[48:51]
	v_mfma_f32_16x16x32_bf16 v[36:39], v[144:147], v[200:203], v[36:39]
	v_mfma_f32_16x16x32_bf16 v[32:35], v[174:177], v[200:203], v[32:35]
	v_mfma_f32_16x16x32_bf16 v[20:23], v[144:147], v[208:211], v[20:23]
	v_mfma_f32_16x16x32_bf16 v[16:19], v[174:177], v[208:211], v[16:19]
	v_mfma_f32_16x16x32_bf16 v[4:7], v[144:147], v[216:219], v[4:7]
	v_mfma_f32_16x16x32_bf16 v[0:3], v[174:177], v[216:219], v[0:3]
	v_mfma_f32_16x16x32_bf16 v[52:55], v[148:151], v[186:189], v[52:55]
	v_mfma_f32_16x16x32_bf16 v[48:51], v[178:181], v[186:189], v[48:51]
	v_mfma_f32_16x16x32_bf16 v[36:39], v[148:151], v[204:207], v[36:39]
	v_mfma_f32_16x16x32_bf16 v[32:35], v[178:181], v[204:207], v[32:35]
	v_mfma_f32_16x16x32_bf16 v[20:23], v[148:151], v[212:215], v[20:23]
	v_mfma_f32_16x16x32_bf16 v[16:19], v[178:181], v[212:215], v[16:19]
	v_mfma_f32_16x16x32_bf16 v[4:7], v[148:151], v[220:223], v[4:7]
	v_mfma_f32_16x16x32_bf16 v[0:3], v[178:181], v[220:223], v[0:3]
	s_barrier
; #define PG8_STAGE(bufoff, gbase, voff) do { _Pragma("unroll") for (int _i = 0; _i < 2; ++_i) \
;         __builtin_amdgcn_global_load_lds((const unsigned*)((const char*)(gbase) + (voff)[_i]), (PG8_LAS unsigned*)(lds + (bufoff) + ldsw + _i * 8192), 16, 0, 0); } while (0)
; #define PG8_LDA(dst, b, h) do { _Pragma("unroll") for (int m = 0; m < 4; ++m) _Pragma("unroll") for (int k = 0; k < 2; ++k) dst[m][k] = *(const PG8_LAS bf16x8*)(lds + PG8_SA(b, h) + aoff + m * 2048 + k * 1024); } while (0)
; #define PG8_LDB(dst, b, h) do { _Pragma("unroll") for (int n = 0; n < 2; ++n) _Pragma("unroll") for (int k = 0; k < 2; ++k) dst[n][k] = *(const PG8_LAS bf16x8*)(lds + PG8_SB(b, h) + boff + n * 2048 + k * 1024); } while (0)
; #define PG8_MMA(ai, bj, At, Bt) do { __builtin_amdgcn_s_setprio(1); _Pragma("unroll") for (int m = 0; m < 4; ++m) _Pragma("unroll") for (int n = 0; n < 2; ++n) _Pragma("unroll") for (int k = 0; k < 2; ++k) \
;         acc[ai][bj][m][n] = __builtin_amdgcn_mfma_f32_16x16x32_bf16(Bt[n][k], At[m][k], acc[ai][bj][m][n], 0, 0, 0); __builtin_amdgcn_s_setprio(0); } while (0)
; #define PG8_WAIT_V(n) asm volatile("s_waitcnt vmcnt(" #n ")" ::: "memory")
; #define PG8_WAIT_L(n) asm volatile("s_waitcnt lgkmcnt(" #n ")" ::: "memory")
; #define PG8_BAR __builtin_amdgcn_s_barrier()
; #define PG8_SCHED __builtin_amdgcn_sched_barrier(0)
; template <class Epi, class Sched, bool ALIGN_EPI = false, bool SP2 = false>
; __device__ __forceinline__ void gemm_phase(PG8_LAS unsigned char* lds, const Gemm g, const Sched& S, const Epi& E, const int wid) {
;     ...
;             PG8_LDA(At, 0, 1); PG8_STAGE(PG8_SB(0, 0), b2, voffB); PG8_STAGE(PG8_SB(0, 1), b2 + hstep, voffB); PG8_STAGE(PG8_SA(0, 0), a2, voffA);
;             PG8_WAIT_V(8); PG8_WAIT_L(0); PG8_BAR; PG8_MMA(1, 0, At, B0); PG8_MMA(1, 1, At, B1); PG8_BAR; PG8_SCHED;
;             PG8_LDB(B0, 1, 0); PG8_LDB(B1, 1, 1); PG8_SCHED; PG8_LDA(At, 1, 0); PG8_STAGE(PG8_SA(0, 1), a2 + hstep, voffA);
	s_setprio 0
	s_add_i32 s18, s40, s28
	s_mov_b32 m0, s18
	ds_read_b128 v[182:185], v199 offset:16384
	ds_read_b128 v[186:189], v199 offset:17408
	ds_read_b128 v[200:203], v199 offset:18432
	ds_read_b128 v[204:207], v199 offset:19456
	ds_read_b128 v[208:211], v199 offset:20480
	ds_read_b128 v[212:215], v199 offset:21504
	ds_read_b128 v[216:219], v199 offset:22528
	ds_read_b128 v[220:223], v199 offset:23552
	global_load_lds_dwordx4 v154, s[22:23]
	s_add_i32 m0, s18, 0x2000
	s_add_u32 s18, s22, 0x2b0000
	s_addc_u32 s19, s23, 0
	s_add_i32 s57, s41, s28
	global_load_lds_dwordx4 v158, s[22:23]
	s_mov_b32 m0, s57
	global_load_lds_dwordx4 v154, s[18:19]
	s_add_i32 m0, s57, 0x2000
	s_nop 0
	global_load_lds_dwordx4 v158, s[18:19]
	s_mov_b32 m0, s29
	s_nop 0
	global_load_lds_dwordx4 v152, s[24:25]
	s_mov_b32 m0, s30
	s_nop 0
	global_load_lds_dwordx4 v156, s[24:25]
	s_waitcnt vmcnt(8)
	s_waitcnt lgkmcnt(0)
	s_setprio 1
	s_barrier
	v_mfma_f32_16x16x32_bf16 v[124:127], v[128:131], v[182:185], v[124:127]
	v_mfma_f32_16x16x32_bf16 v[120:123], v[136:139], v[182:185], v[120:123]
	v_mfma_f32_16x16x32_bf16 v[108:111], v[128:131], v[200:203], v[108:111]
	v_mfma_f32_16x16x32_bf16 v[104:107], v[136:139], v[200:203], v[104:107]
	v_mfma_f32_16x16x32_bf16 v[92:95], v[128:131], v[208:211], v[92:95]
	v_mfma_f32_16x16x32_bf16 v[88:91], v[136:139], v[208:211], v[88:91]
	v_mfma_f32_16x16x32_bf16 v[76:79], v[128:131], v[216:219], v[76:79]
	v_mfma_f32_16x16x32_bf16 v[72:75], v[136:139], v[216:219], v[72:75]
	v_mfma_f32_16x16x32_bf16 v[124:127], v[132:135], v[186:189], v[124:127]
	v_mfma_f32_16x16x32_bf16 v[120:123], v[140:143], v[186:189], v[120:123]
	v_mfma_f32_16x16x32_bf16 v[108:111], v[132:135], v[204:207], v[108:111]
	v_mfma_f32_16x16x32_bf16 v[104:107], v[140:143], v[204:207], v[104:107]
	v_mfma_f32_16x16x32_bf16 v[92:95], v[132:135], v[212:215], v[92:95]
	v_mfma_f32_16x16x32_bf16 v[88:91], v[140:143], v[212:215], v[88:91]
	v_mfma_f32_16x16x32_bf16 v[76:79], v[132:135], v[220:223], v[76:79]
	v_mfma_f32_16x16x32_bf16 v[72:75], v[140:143], v[220:223], v[72:75]
	v_mfma_f32_16x16x32_bf16 v[116:119], v[144:147], v[182:185], v[116:119]
	v_mfma_f32_16x16x32_bf16 v[112:115], v[174:177], v[182:185], v[112:115]
	v_mfma_f32_16x16x32_bf16 v[100:103], v[144:147], v[200:203], v[100:103]
	v_mfma_f32_16x16x32_bf16 v[96:99], v[174:177], v[200:203], v[96:99]
	v_mfma_f32_16x16x32_bf16 v[84:87], v[144:147], v[208:211], v[84:87]
	v_mfma_f32_16x16x32_bf16 v[80:83], v[174:177], v[208:211], v[80:83]
	v_mfma_f32_16x16x32_bf16 v[68:71], v[144:147], v[216:219], v[68:71]
	v_mfma_f32_16x16x32_bf16 v[64:67], v[174:177], v[216:219], v[64:67]
	v_mfma_f32_16x16x32_bf16 v[116:119], v[148:151], v[186:189], v[116:119]
	v_mfma_f32_16x16x32_bf16 v[112:115], v[178:181], v[186:189], v[112:115]
	v_mfma_f32_16x16x32_bf16 v[100:103], v[148:151], v[204:207], v[100:103]
	v_mfma_f32_16x16x32_bf16 v[96:99], v[178:181], v[204:207], v[96:99]
	v_mfma_f32_16x16x32_bf16 v[84:87], v[148:151], v[212:215], v[84:87]
	v_mfma_f32_16x16x32_bf16 v[80:83], v[178:181], v[212:215], v[80:83]
	v_mfma_f32_16x16x32_bf16 v[68:71], v[148:151], v[220:223], v[68:71]
	v_mfma_f32_16x16x32_bf16 v[64:67], v[178:181], v[220:223], v[64:67]
	s_barrier
	s_setprio 0
	s_add_i32 s57, 0, 0x18000
	s_add_i32 s58, 0, 0x1c000
	ds_read_b128 v[128:131], v246
	ds_read_b128 v[132:135], v246 offset:1024
	ds_read_b128 v[136:139], v246 offset:2048
	ds_read_b128 v[140:143], v246 offset:3072
	ds_read_b128 v[144:147], v248
	ds_read_b128 v[148:151], v248 offset:1024
	ds_read_b128 v[174:177], v248 offset:2048
	ds_read_b128 v[178:181], v248 offset:3072
	s_add_u32 s18, s24, 0x2b0000
	s_addc_u32 s19, s25, 0
	s_mov_b32 m0, s31
	ds_read_b128 v[182:185], v199 offset:32768
	ds_read_b128 v[186:189], v199 offset:33792
	ds_read_b128 v[200:203], v199 offset:34816
	ds_read_b128 v[204:207], v199 offset:35840
	ds_read_b128 v[208:211], v199 offset:36864
	ds_read_b128 v[212:215], v199 offset:37888
	ds_read_b128 v[216:219], v199 offset:38912
	ds_read_b128 v[220:223], v199 offset:39936
	global_load_lds_dwordx4 v152, s[18:19]
	s_mov_b32 m0, s34
	s_nop 0
	global_load_lds_dwordx4 v156, s[18:19]
	s_waitcnt vmcnt(8)
	s_waitcnt lgkmcnt(0)
	s_setprio 1
	s_barrier
; #define PG8_STAGE(bufoff, gbase, voff) do { _Pragma("unroll") for (int _i = 0; _i < 2; ++_i) \
;         __builtin_amdgcn_global_load_lds((const unsigned*)((const char*)(gbase) + (voff)[_i]), (PG8_LAS unsigned*)(lds + (bufoff) + ldsw + _i * 8192), 16, 0, 0); } while (0)
; #define PG8_LDA(dst, b, h) do { _Pragma("unroll") for (int m = 0; m < 4; ++m) _Pragma("unroll") for (int k = 0; k < 2; ++k) dst[m][k] = *(const PG8_LAS bf16x8*)(lds + PG8_SA(b, h) + aoff + m * 2048 + k * 1024); } while (0)
; #define PG8_MMA(ai, bj, At, Bt) do { __builtin_amdgcn_s_setprio(1); _Pragma("unroll") for (int m = 0; m < 4; ++m) _Pragma("unroll") for (int n = 0; n < 2; ++n) _Pragma("unroll") for (int k = 0; k < 2; ++k) \
;         acc[ai][bj][m][n] = __builtin_amdgcn_mfma_f32_16x16x32_bf16(Bt[n][k], At[m][k], acc[ai][bj][m][n], 0, 0, 0); __builtin_amdgcn_s_setprio(0); } while (0)
; #define PG8_WAIT_V(n) asm volatile("s_waitcnt vmcnt(" #n ")" ::: "memory")
; #define PG8_WAIT_L(n) asm volatile("s_waitcnt lgkmcnt(" #n ")" ::: "memory")
; #define PG8_BAR __builtin_amdgcn_s_barrier()
; #define PG8_SCHED __builtin_amdgcn_sched_barrier(0)
; template <class Epi, class Sched, bool ALIGN_EPI = false, bool SP2 = false>
; __device__ __forceinline__ void gemm_phase(PG8_LAS unsigned char* lds, const Gemm g, const Sched& S, const Epi& E, const int wid) {
;     ...
;         for (int t = 0; t < nt; t += 2) {
;     ...
;             PG8_WAIT_V(8); PG8_WAIT_L(0); PG8_BAR; PG8_MMA(0, 0, At, B0); PG8_MMA(0, 1, At, B1); PG8_BAR; PG8_SCHED;
;             PG8_LDA(At, 1, 1); PG8_STAGE(PG8_SB(1, 0), b3, voffB); PG8_STAGE(PG8_SB(1, 1), b3 + hstep, voffB); PG8_STAGE(PG8_SA(1, 0), a3, voffA);
;             PG8_WAIT_V(8); PG8_WAIT_L(0); PG8_BAR; PG8_MMA(1, 0, At, B0); PG8_MMA(1, 1, At, B1); PG8_BAR; PG8_SCHED;
	v_mfma_f32_16x16x32_bf16 v[60:63], v[128:131], v[182:185], v[60:63]
	v_mfma_f32_16x16x32_bf16 v[56:59], v[136:139], v[182:185], v[56:59]
	v_mfma_f32_16x16x32_bf16 v[44:47], v[128:131], v[200:203], v[44:47]
	v_mfma_f32_16x16x32_bf16 v[40:43], v[136:139], v[200:203], v[40:43]
	v_mfma_f32_16x16x32_bf16 v[28:31], v[128:131], v[208:211], v[28:31]
	v_mfma_f32_16x16x32_bf16 v[24:27], v[136:139], v[208:211], v[24:27]
	v_mfma_f32_16x16x32_bf16 v[12:15], v[128:131], v[216:219], v[12:15]
	v_mfma_f32_16x16x32_bf16 v[8:11], v[136:139], v[216:219], v[8:11]
	v_mfma_f32_16x16x32_bf16 v[60:63], v[132:135], v[186:189], v[60:63]
	v_mfma_f32_16x16x32_bf16 v[56:59], v[140:143], v[186:189], v[56:59]
	v_mfma_f32_16x16x32_bf16 v[44:47], v[132:135], v[204:207], v[44:47]
	v_mfma_f32_16x16x32_bf16 v[40:43], v[140:143], v[204:207], v[40:43]
	v_mfma_f32_16x16x32_bf16 v[28:31], v[132:135], v[212:215], v[28:31]
	v_mfma_f32_16x16x32_bf16 v[24:27], v[140:143], v[212:215], v[24:27]
	v_mfma_f32_16x16x32_bf16 v[12:15], v[132:135], v[220:223], v[12:15]
	v_mfma_f32_16x16x32_bf16 v[8:11], v[140:143], v[220:223], v[8:11]
	v_mfma_f32_16x16x32_bf16 v[52:55], v[144:147], v[182:185], v[52:55]
	v_mfma_f32_16x16x32_bf16 v[48:51], v[174:177], v[182:185], v[48:51]
	v_mfma_f32_16x16x32_bf16 v[36:39], v[144:147], v[200:203], v[36:39]
	v_mfma_f32_16x16x32_bf16 v[32:35], v[174:177], v[200:203], v[32:35]
	v_mfma_f32_16x16x32_bf16 v[20:23], v[144:147], v[208:211], v[20:23]
	v_mfma_f32_16x16x32_bf16 v[16:19], v[174:177], v[208:211], v[16:19]
	v_mfma_f32_16x16x32_bf16 v[4:7], v[144:147], v[216:219], v[4:7]
	v_mfma_f32_16x16x32_bf16 v[0:3], v[174:177], v[216:219], v[0:3]
	v_mfma_f32_16x16x32_bf16 v[52:55], v[148:151], v[186:189], v[52:55]
	v_mfma_f32_16x16x32_bf16 v[48:51], v[178:181], v[186:189], v[48:51]
	v_mfma_f32_16x16x32_bf16 v[36:39], v[148:151], v[204:207], v[36:39]
	v_mfma_f32_16x16x32_bf16 v[32:35], v[178:181], v[204:207], v[32:35]
	v_mfma_f32_16x16x32_bf16 v[20:23], v[148:151], v[212:215], v[20:23]
	v_mfma_f32_16x16x32_bf16 v[16:19], v[178:181], v[212:215], v[16:19]
	v_mfma_f32_16x16x32_bf16 v[4:7], v[148:151], v[220:223], v[4:7]
	v_mfma_f32_16x16x32_bf16 v[0:3], v[178:181], v[220:223], v[0:3]
	s_barrier
	s_setprio 0
	s_add_u32 s98, s22, 0x80
	s_addc_u32 s99, s23, 0
	s_add_u32 s100, s24, 0x80
	s_addc_u32 s101, s25, 0
	s_add_i32 s18, s57, s28
	s_mov_b32 m0, s18
	ds_read_b128 v[182:185], v199 offset:49152
	ds_read_b128 v[186:189], v199 offset:50176
	ds_read_b128 v[200:203], v199 offset:51200
	ds_read_b128 v[204:207], v199 offset:52224
	ds_read_b128 v[208:211], v199 offset:53248
	ds_read_b128 v[212:215], v199 offset:54272
	ds_read_b128 v[216:219], v199 offset:55296
	ds_read_b128 v[220:223], v199 offset:56320
	global_load_lds_dwordx4 v154, s[98:99]
	s_add_i32 m0, s18, 0x2000
	s_add_u32 s18, s22, 0x2b0080
	s_addc_u32 s19, s23, 0
	s_add_i32 s22, s58, s28
	global_load_lds_dwordx4 v158, s[98:99]
	s_mov_b32 m0, s22
	s_nop 0
	global_load_lds_dwordx4 v154, s[18:19]
	s_add_i32 m0, s22, 0x2000
	s_nop 0
	global_load_lds_dwordx4 v158, s[18:19]
	s_mov_b32 m0, s36
	s_nop 0
	global_load_lds_dwordx4 v152, s[100:101]
	s_mov_b32 m0, s37
	s_nop 0
	global_load_lds_dwordx4 v156, s[100:101]
	s_waitcnt vmcnt(8)
	s_waitcnt lgkmcnt(0)
	s_setprio 1
	s_barrier
	v_mfma_f32_16x16x32_bf16 v[124:127], v[128:131], v[182:185], v[124:127]
	v_mfma_f32_16x16x32_bf16 v[120:123], v[136:139], v[182:185], v[120:123]
	v_mfma_f32_16x16x32_bf16 v[108:111], v[128:131], v[200:203], v[108:111]
	v_mfma_f32_16x16x32_bf16 v[104:107], v[136:139], v[200:203], v[104:107]
	v_mfma_f32_16x16x32_bf16 v[92:95], v[128:131], v[208:211], v[92:95]
	v_mfma_f32_16x16x32_bf16 v[88:91], v[136:139], v[208:211], v[88:91]
	v_mfma_f32_16x16x32_bf16 v[76:79], v[128:131], v[216:219], v[76:79]
	v_mfma_f32_16x16x32_bf16 v[72:75], v[136:139], v[216:219], v[72:75]
	v_mfma_f32_16x16x32_bf16 v[124:127], v[132:135], v[186:189], v[124:127]
	v_mfma_f32_16x16x32_bf16 v[120:123], v[140:143], v[186:189], v[120:123]
	v_mfma_f32_16x16x32_bf16 v[108:111], v[132:135], v[204:207], v[108:111]
	v_mfma_f32_16x16x32_bf16 v[104:107], v[140:143], v[204:207], v[104:107]
	v_mfma_f32_16x16x32_bf16 v[92:95], v[132:135], v[212:215], v[92:95]
	v_mfma_f32_16x16x32_bf16 v[88:91], v[140:143], v[212:215], v[88:91]
	v_mfma_f32_16x16x32_bf16 v[76:79], v[132:135], v[220:223], v[76:79]
	v_mfma_f32_16x16x32_bf16 v[72:75], v[140:143], v[220:223], v[72:75]
	v_mfma_f32_16x16x32_bf16 v[116:119], v[144:147], v[182:185], v[116:119]
	v_mfma_f32_16x16x32_bf16 v[112:115], v[174:177], v[182:185], v[112:115]
	v_mfma_f32_16x16x32_bf16 v[100:103], v[144:147], v[200:203], v[100:103]
	v_mfma_f32_16x16x32_bf16 v[96:99], v[174:177], v[200:203], v[96:99]
	v_mfma_f32_16x16x32_bf16 v[84:87], v[144:147], v[208:211], v[84:87]
	v_mfma_f32_16x16x32_bf16 v[80:83], v[174:177], v[208:211], v[80:83]
	v_mfma_f32_16x16x32_bf16 v[68:71], v[144:147], v[216:219], v[68:71]
	v_mfma_f32_16x16x32_bf16 v[64:67], v[174:177], v[216:219], v[64:67]
	v_mfma_f32_16x16x32_bf16 v[116:119], v[148:151], v[186:189], v[116:119]
	v_mfma_f32_16x16x32_bf16 v[112:115], v[178:181], v[186:189], v[112:115]
	v_mfma_f32_16x16x32_bf16 v[100:103], v[148:151], v[204:207], v[100:103]
	v_mfma_f32_16x16x32_bf16 v[96:99], v[178:181], v[204:207], v[96:99]
	v_mfma_f32_16x16x32_bf16 v[84:87], v[148:151], v[212:215], v[84:87]
	v_mfma_f32_16x16x32_bf16 v[80:83], v[178:181], v[212:215], v[80:83]
	v_mfma_f32_16x16x32_bf16 v[68:71], v[148:151], v[220:223], v[68:71]
	v_mfma_f32_16x16x32_bf16 v[64:67], v[178:181], v[220:223], v[64:67]
	s_barrier
	s_setprio 0
	s_add_u32 s54, s54, 0x100
	s_addc_u32 s55, s55, 0
	s_cmp_ge_i32 s56, s53
	s_mov_b64 s[18:19], s[20:21]
	s_mov_b32 s22, s56
	s_cbranch_scc0 .LBB0_1138
	s_and_b64 vcc, exec, s[10:11]
	s_cbranch_vccz .LBB0_1141
	s_barrier

;     __device__ bool next(int i, Unit& u) const { const bool ok = StaticOrder::next(i, u); u.pm = 0; u.pn = 0; return ok; }
; #define PG8_STAGE(bufoff, gbase, voff) do { _Pragma("unroll") for (int _i = 0; _i < 2; ++_i) \
;         __builtin_amdgcn_global_load_lds((const unsigned*)((const char*)(gbase) + (voff)[_i]), (PG8_LAS unsigned*)(lds + (bufoff) + ldsw + _i * 8192), 16, 0, 0); } while (0)
; #define PG8_LDA(dst, b, h) do { _Pragma("unroll") for (int m = 0; m < 4; ++m) _Pragma("unroll") for (int k = 0; k < 2; ++k) dst[m][k] = *(const PG8_LAS bf16x8*)(lds + PG8_SA(b, h) + aoff + m * 2048 + k * 1024); } while (0)
; #define PG8_LDB(dst, b, h) do { _Pragma("unroll") for (int n = 0; n < 2; ++n) _Pragma("unroll") for (int k = 0; k < 2; ++k) dst[n][k] = *(const PG8_LAS bf16x8*)(lds + PG8_SB(b, h) + boff + n * 2048 + k * 1024); } while (0)
; #define PG8_SCHED __builtin_amdgcn_sched_barrier(0)
; template <class Epi, class Sched, bool ALIGN_EPI = false, bool SP2 = false>
; __device__ __forceinline__ void gemm_phase(PG8_LAS unsigned char* lds, const Gemm g, const Sched& S, const Epi& E, const int wid) {
;     ...
;         const bool has_next = S.next(ui + 1, nxt);
;         const char* nA = has_next ? (const char*)g.A + (size_t)nxt.pm * tstep + (size_t)nxt.kb * kstep : cA; const char* nB = has_next ? (const char*)g.Bt + (size_t)nxt.pn * tstep + (size_t)nxt.kb * kstep : cB;
;         for (int t = 0; t < nt; t += 2) {
;             const bool last = (t == nt - 2);
;             const char* a1 = cA + (size_t)(t + 1) * kstep;
;             const char* a2 = last ? nA : cA + (size_t)(t + 2) * kstep; const char* b2 = last ? nB : cB + (size_t)(t + 2) * kstep;
;             const char* a3 = a2 + kstep; const char* b3 = b2 + kstep;
;             if (last && has_next) S.a_ready(nxt);
;             if constexpr (SP2) {
;             PG8_LDB(B0, 0, 0); PG8_LDB(B1, 0, 1); PG8_SCHED; PG8_LDA(At, 0, 0); PG8_STAGE(PG8_SA(1, 1), a1 + hstep, voffA);
;     ...
; #pragma unroll
;         for (int a = 0; a < 2; ++a)
; #pragma unroll
;             for (int b = 0; b < 2; ++b)
; #pragma unroll
;                 for (int m = 0; m < 4; ++m)
; #pragma unroll
;                     for (int n = 0; n < 2; ++n) acc[a][b][m][n] = (f32x4){0.f, 0.f, 0.f, 0.f};
;         cur = nxt; cA = nA; cB = nB; ++ui; nt = cur.kn;
.LBB0_1249:
	v_lshl_add_u32 v254, s18, 8, v164
	v_ashrrev_i32_e32 v255, 31, v254
	v_lshl_add_u64 v[254:255], v[254:255], 3, s[4:5]
	global_load_dwordx2 v[238:239], v[254:255], off
	global_load_dwordx2 v[240:241], v[254:255], off offset:128
	global_load_dwordx2 v[242:243], v[254:255], off offset:256
	global_load_dwordx2 v[244:245], v[254:255], off offset:384
	global_load_dwordx2 v[248:249], v[254:255], off offset:1024
	global_load_dwordx2 v[250:251], v[254:255], off offset:1152
	global_load_dwordx2 v[252:253], v[254:255], off offset:1280
	global_load_dwordx2 v[254:255], v[254:255], off offset:1408
	s_ashr_i32 s13, s12, 31
	s_lshl_b64 s[14:15], s[12:13], 21
	s_add_u32 s14, s78, s14
	s_addc_u32 s15, s79, s15
	s_and_b64 s[16:17], s[0:1], exec
	s_cselect_b32 s13, s15, s21
	s_cselect_b32 s19, s14, s20
	s_ashr_i32 s11, s10, 31
	s_lshl_b64 s[16:17], s[10:11], 21
	s_add_u32 s16, s26, s16
	s_addc_u32 s17, s27, s17
	s_and_b64 s[24:25], s[0:1], exec
	s_cselect_b32 s11, s17, s23
	s_cselect_b32 s57, s16, s22
	s_add_u32 s20, s20, 0x100080
	s_addc_u32 s21, s21, 0
	s_add_u32 s58, s22, 0x100
	v_mov_b32_e32 v0, 0
	s_addc_u32 s59, s23, 0
	s_mov_b32 s60, -2
	v_mov_b32_e32 v1, v0
	v_mov_b32_e32 v2, v0
	v_mov_b32_e32 v3, v0
	v_mov_b32_e32 v8, v0
	v_mov_b32_e32 v9, v0
	v_mov_b32_e32 v10, v0
	v_mov_b32_e32 v11, v0
	v_mov_b32_e32 v16, v0
	v_mov_b32_e32 v17, v0
	v_mov_b32_e32 v18, v0
	v_mov_b32_e32 v19, v0
	v_mov_b32_e32 v24, v0
	v_mov_b32_e32 v25, v0
	v_mov_b32_e32 v26, v0
	v_mov_b32_e32 v27, v0
	v_mov_b32_e32 v32, v0
	v_mov_b32_e32 v33, v0
	v_mov_b32_e32 v34, v0
	v_mov_b32_e32 v35, v0
	v_mov_b32_e32 v40, v0
	v_mov_b32_e32 v41, v0
	v_mov_b32_e32 v42, v0
	v_mov_b32_e32 v43, v0
	v_mov_b32_e32 v48, v0
	v_mov_b32_e32 v49, v0
	v_mov_b32_e32 v50, v0
	v_mov_b32_e32 v51, v0
	v_mov_b32_e32 v56, v0
	v_mov_b32_e32 v57, v0
	v_mov_b32_e32 v58, v0
	v_mov_b32_e32 v59, v0
	v_mov_b32_e32 v4, v0
	v_mov_b32_e32 v5, v0
	v_mov_b32_e32 v6, v0
	v_mov_b32_e32 v7, v0
	v_mov_b32_e32 v12, v0
	v_mov_b32_e32 v13, v0
	v_mov_b32_e32 v14, v0
	v_mov_b32_e32 v15, v0
	v_mov_b32_e32 v20, v0
	v_mov_b32_e32 v21, v0
	v_mov_b32_e32 v22, v0
	v_mov_b32_e32 v23, v0
	v_mov_b32_e32 v28, v0
	v_mov_b32_e32 v29, v0
	v_mov_b32_e32 v30, v0
	v_mov_b32_e32 v31, v0
	v_mov_b32_e32 v36, v0
	v_mov_b32_e32 v37, v0
	v_mov_b32_e32 v38, v0
	v_mov_b32_e32 v39, v0
	v_mov_b32_e32 v44, v0
	v_mov_b32_e32 v45, v0
	v_mov_b32_e32 v46, v0
	v_mov_b32_e32 v47, v0
	v_mov_b32_e32 v52, v0
	v_mov_b32_e32 v53, v0
	v_mov_b32_e32 v54, v0
	v_mov_b32_e32 v55, v0
	v_mov_b32_e32 v60, v0
	v_mov_b32_e32 v61, v0
	v_mov_b32_e32 v62, v0
	v_mov_b32_e32 v63, v0
	v_mov_b32_e32 v64, v0
	v_mov_b32_e32 v65, v0
	v_mov_b32_e32 v66, v0
	v_mov_b32_e32 v67, v0
	v_mov_b32_e32 v72, v0
	v_mov_b32_e32 v73, v0
	v_mov_b32_e32 v74, v0
	v_mov_b32_e32 v75, v0
	v_mov_b32_e32 v80, v0
	v_mov_b32_e32 v81, v0
	v_mov_b32_e32 v82, v0
	v_mov_b32_e32 v83, v0
	v_mov_b32_e32 v88, v0
	v_mov_b32_e32 v89, v0
	v_mov_b32_e32 v90, v0
	v_mov_b32_e32 v91, v0
	v_mov_b32_e32 v96, v0
	v_mov_b32_e32 v97, v0
	v_mov_b32_e32 v98, v0
	v_mov_b32_e32 v99, v0
	v_mov_b32_e32 v104, v0
	v_mov_b32_e32 v105, v0
	v_mov_b32_e32 v106, v0
	v_mov_b32_e32 v107, v0
	v_mov_b32_e32 v112, v0
	v_mov_b32_e32 v113, v0
	v_mov_b32_e32 v114, v0
	v_mov_b32_e32 v115, v0
	v_mov_b32_e32 v120, v0
	v_mov_b32_e32 v121, v0
	v_mov_b32_e32 v122, v0
	v_mov_b32_e32 v123, v0
	v_mov_b32_e32 v68, v0
	v_mov_b32_e32 v69, v0
	v_mov_b32_e32 v70, v0
	v_mov_b32_e32 v71, v0
	v_mov_b32_e32 v76, v0
	v_mov_b32_e32 v77, v0
	v_mov_b32_e32 v78, v0
	v_mov_b32_e32 v79, v0
	v_mov_b32_e32 v84, v0
	v_mov_b32_e32 v85, v0
	v_mov_b32_e32 v86, v0
	v_mov_b32_e32 v87, v0
	v_mov_b32_e32 v92, v0
	v_mov_b32_e32 v93, v0
	v_mov_b32_e32 v94, v0
	v_mov_b32_e32 v95, v0
	v_mov_b32_e32 v100, v0
	v_mov_b32_e32 v101, v0
	v_mov_b32_e32 v102, v0
	v_mov_b32_e32 v103, v0
	v_mov_b32_e32 v108, v0
	v_mov_b32_e32 v109, v0
	v_mov_b32_e32 v110, v0
	v_mov_b32_e32 v111, v0
	v_mov_b32_e32 v116, v0
	v_mov_b32_e32 v117, v0
	v_mov_b32_e32 v118, v0
	v_mov_b32_e32 v119, v0
	v_mov_b32_e32 v124, v0
	v_mov_b32_e32 v125, v0
	v_mov_b32_e32 v126, v0
	v_mov_b32_e32 v127, v0
	v_add_u32_e32 v246, 0x18000, v165
.LBB0_1250:
	ds_read_b128 v[128:131], v175
	ds_read_b128 v[150:153], v175 offset:1024
	ds_read_b128 v[154:157], v175 offset:2048
	ds_read_b128 v[158:161], v175 offset:3072
	ds_read_b128 v[180:183], v176
	ds_read_b128 v[184:187], v176 offset:1024
	ds_read_b128 v[188:191], v176 offset:2048
	ds_read_b128 v[192:195], v176 offset:3072
	s_add_u32 s22, s20, 0xfff00080
	s_addc_u32 s23, s21, -1
	s_cmp_eq_u32 s60, 60
	s_cselect_b32 s25, s13, s23
	s_cselect_b32 s24, s19, s22
	s_cselect_b32 s23, s11, s59
	s_cselect_b32 s22, s57, s58
	s_add_i32 m0, s31, 0xc000
	ds_read_b128 v[196:199], v177
	ds_read_b128 v[200:203], v177 offset:1024
	ds_read_b128 v[204:207], v177 offset:2048
	ds_read_b128 v[208:211], v177 offset:3072
	ds_read_b128 v[212:215], v177 offset:4096
	ds_read_b128 v[216:219], v177 offset:5120
	ds_read_b128 v[220:223], v177 offset:6144
	ds_read_b128 v[224:227], v177 offset:7168
	global_load_lds_dwordx4 v142, s[20:21]
	s_add_i32 m0, s31, 0xe000
	s_nop 0
	global_load_lds_dwordx4 v144, s[20:21]
	s_waitcnt vmcnt(8)
	s_waitcnt lgkmcnt(0)
	s_setprio 1
	s_barrier
; #define PG8_STAGE(bufoff, gbase, voff) do { _Pragma("unroll") for (int _i = 0; _i < 2; ++_i) \
;         __builtin_amdgcn_global_load_lds((const unsigned*)((const char*)(gbase) + (voff)[_i]), (PG8_LAS unsigned*)(lds + (bufoff) + ldsw + _i * 8192), 16, 0, 0); } while (0)
; #define PG8_LDA(dst, b, h) do { _Pragma("unroll") for (int m = 0; m < 4; ++m) _Pragma("unroll") for (int k = 0; k < 2; ++k) dst[m][k] = *(const PG8_LAS bf16x8*)(lds + PG8_SA(b, h) + aoff + m * 2048 + k * 1024); } while (0)
; #define PG8_MMA(ai, bj, At, Bt) do { __builtin_amdgcn_s_setprio(1); _Pragma("unroll") for (int m = 0; m < 4; ++m) _Pragma("unroll") for (int n = 0; n < 2; ++n) _Pragma("unroll") for (int k = 0; k < 2; ++k) \
;         acc[ai][bj][m][n] = __builtin_amdgcn_mfma_f32_16x16x32_bf16(Bt[n][k], At[m][k], acc[ai][bj][m][n], 0, 0, 0); __builtin_amdgcn_s_setprio(0); } while (0)
; #define PG8_WAIT_V(n) asm volatile("s_waitcnt vmcnt(" #n ")" ::: "memory")
; #define PG8_WAIT_L(n) asm volatile("s_waitcnt lgkmcnt(" #n ")" ::: "memory")
; #define PG8_BAR __builtin_amdgcn_s_barrier()
; #define PG8_SCHED __builtin_amdgcn_sched_barrier(0)
; template <class Epi, class Sched, bool ALIGN_EPI = false, bool SP2 = false>
; __device__ __forceinline__ void gemm_phase(PG8_LAS unsigned char* lds, const Gemm g, const Sched& S, const Epi& E, const int wid) {
;     ...
;             PG8_WAIT_V(8); PG8_WAIT_L(0); PG8_BAR; PG8_MMA(0, 0, At, B0); PG8_MMA(0, 1, At, B1); PG8_BAR; PG8_SCHED;
;             PG8_LDA(At, 0, 1); PG8_STAGE(PG8_SB(0, 0), b2, voffB); PG8_STAGE(PG8_SB(0, 1), b2 + hstep, voffB); PG8_STAGE(PG8_SA(0, 0), a2, voffA);
;             PG8_WAIT_V(8); PG8_WAIT_L(0); PG8_BAR; PG8_MMA(1, 0, At, B0); PG8_MMA(1, 1, At, B1); PG8_BAR; PG8_SCHED;
	v_mfma_f32_16x16x32_bf16 v[124:127], v[128:131], v[196:199], v[124:127]
	v_mfma_f32_16x16x32_bf16 v[116:119], v[154:157], v[196:199], v[116:119]
	v_mfma_f32_16x16x32_bf16 v[108:111], v[128:131], v[204:207], v[108:111]
	v_mfma_f32_16x16x32_bf16 v[100:103], v[154:157], v[204:207], v[100:103]
	v_mfma_f32_16x16x32_bf16 v[92:95], v[128:131], v[212:215], v[92:95]
	v_mfma_f32_16x16x32_bf16 v[84:87], v[154:157], v[212:215], v[84:87]
	v_mfma_f32_16x16x32_bf16 v[76:79], v[128:131], v[220:223], v[76:79]
	v_mfma_f32_16x16x32_bf16 v[68:71], v[154:157], v[220:223], v[68:71]
	v_mfma_f32_16x16x32_bf16 v[124:127], v[150:153], v[200:203], v[124:127]
	v_mfma_f32_16x16x32_bf16 v[116:119], v[158:161], v[200:203], v[116:119]
	v_mfma_f32_16x16x32_bf16 v[108:111], v[150:153], v[208:211], v[108:111]
	v_mfma_f32_16x16x32_bf16 v[100:103], v[158:161], v[208:211], v[100:103]
	v_mfma_f32_16x16x32_bf16 v[92:95], v[150:153], v[216:219], v[92:95]
	v_mfma_f32_16x16x32_bf16 v[84:87], v[158:161], v[216:219], v[84:87]
	v_mfma_f32_16x16x32_bf16 v[76:79], v[150:153], v[224:227], v[76:79]
	v_mfma_f32_16x16x32_bf16 v[68:71], v[158:161], v[224:227], v[68:71]
	v_mfma_f32_16x16x32_bf16 v[120:123], v[180:183], v[196:199], v[120:123]
	v_mfma_f32_16x16x32_bf16 v[112:115], v[188:191], v[196:199], v[112:115]
	v_mfma_f32_16x16x32_bf16 v[104:107], v[180:183], v[204:207], v[104:107]
	v_mfma_f32_16x16x32_bf16 v[96:99], v[188:191], v[204:207], v[96:99]
	v_mfma_f32_16x16x32_bf16 v[88:91], v[180:183], v[212:215], v[88:91]
	v_mfma_f32_16x16x32_bf16 v[80:83], v[188:191], v[212:215], v[80:83]
	v_mfma_f32_16x16x32_bf16 v[72:75], v[180:183], v[220:223], v[72:75]
	v_mfma_f32_16x16x32_bf16 v[64:67], v[188:191], v[220:223], v[64:67]
	v_mfma_f32_16x16x32_bf16 v[120:123], v[184:187], v[200:203], v[120:123]
	v_mfma_f32_16x16x32_bf16 v[112:115], v[192:195], v[200:203], v[112:115]
	v_mfma_f32_16x16x32_bf16 v[104:107], v[184:187], v[208:211], v[104:107]
	v_mfma_f32_16x16x32_bf16 v[96:99], v[192:195], v[208:211], v[96:99]
	v_mfma_f32_16x16x32_bf16 v[88:91], v[184:187], v[216:219], v[88:91]
	v_mfma_f32_16x16x32_bf16 v[80:83], v[192:195], v[216:219], v[80:83]
	v_mfma_f32_16x16x32_bf16 v[72:75], v[184:187], v[224:227], v[72:75]
	v_mfma_f32_16x16x32_bf16 v[64:67], v[192:195], v[224:227], v[64:67]
	s_barrier
	s_setprio 0
	s_add_i32 s61, s42, s28
	s_mov_b32 m0, s61
	ds_read_b128 v[196:199], v177 offset:16384
	ds_read_b128 v[200:203], v177 offset:17408
	ds_read_b128 v[204:207], v177 offset:18432
	ds_read_b128 v[208:211], v177 offset:19456
	ds_read_b128 v[212:215], v177 offset:20480
	ds_read_b128 v[216:219], v177 offset:21504
	ds_read_b128 v[220:223], v177 offset:22528
	ds_read_b128 v[224:227], v177 offset:23552
	global_load_lds_dwordx4 v136, s[22:23]
	s_add_i32 m0, s61, 0x2000
	s_add_u32 s62, s22, 0x100000
	s_addc_u32 s63, s23, 0
	s_add_i32 s61, s43, s28
	global_load_lds_dwordx4 v132, s[22:23]
	s_mov_b32 m0, s61
	global_load_lds_dwordx4 v136, s[62:63]
	s_add_i32 m0, s61, 0x2000
	s_nop 0
	global_load_lds_dwordx4 v132, s[62:63]
	s_mov_b32 m0, s31
	s_nop 0
	global_load_lds_dwordx4 v138, s[24:25]
	s_mov_b32 m0, s34
	s_nop 0
	global_load_lds_dwordx4 v134, s[24:25]
	s_waitcnt vmcnt(8)
	s_waitcnt lgkmcnt(0)
	s_setprio 1
	s_barrier
	v_mfma_f32_16x16x32_bf16 v[60:63], v[128:131], v[196:199], v[60:63]
	v_mfma_f32_16x16x32_bf16 v[52:55], v[154:157], v[196:199], v[52:55]
	v_mfma_f32_16x16x32_bf16 v[44:47], v[128:131], v[204:207], v[44:47]
	v_mfma_f32_16x16x32_bf16 v[36:39], v[154:157], v[204:207], v[36:39]
	v_mfma_f32_16x16x32_bf16 v[28:31], v[128:131], v[212:215], v[28:31]
	v_mfma_f32_16x16x32_bf16 v[20:23], v[154:157], v[212:215], v[20:23]
	v_mfma_f32_16x16x32_bf16 v[12:15], v[128:131], v[220:223], v[12:15]
	v_mfma_f32_16x16x32_bf16 v[4:7], v[154:157], v[220:223], v[4:7]
	v_mfma_f32_16x16x32_bf16 v[60:63], v[150:153], v[200:203], v[60:63]
	v_mfma_f32_16x16x32_bf16 v[52:55], v[158:161], v[200:203], v[52:55]
	v_mfma_f32_16x16x32_bf16 v[44:47], v[150:153], v[208:211], v[44:47]
	v_mfma_f32_16x16x32_bf16 v[36:39], v[158:161], v[208:211], v[36:39]
	v_mfma_f32_16x16x32_bf16 v[28:31], v[150:153], v[216:219], v[28:31]
	v_mfma_f32_16x16x32_bf16 v[20:23], v[158:161], v[216:219], v[20:23]
	v_mfma_f32_16x16x32_bf16 v[12:15], v[150:153], v[224:227], v[12:15]
	v_mfma_f32_16x16x32_bf16 v[4:7], v[158:161], v[224:227], v[4:7]
	v_mfma_f32_16x16x32_bf16 v[56:59], v[180:183], v[196:199], v[56:59]
	v_mfma_f32_16x16x32_bf16 v[48:51], v[188:191], v[196:199], v[48:51]
	v_mfma_f32_16x16x32_bf16 v[40:43], v[180:183], v[204:207], v[40:43]
	v_mfma_f32_16x16x32_bf16 v[32:35], v[188:191], v[204:207], v[32:35]
	v_mfma_f32_16x16x32_bf16 v[24:27], v[180:183], v[212:215], v[24:27]
	v_mfma_f32_16x16x32_bf16 v[16:19], v[188:191], v[212:215], v[16:19]
	v_mfma_f32_16x16x32_bf16 v[8:11], v[180:183], v[220:223], v[8:11]
	v_mfma_f32_16x16x32_bf16 v[0:3], v[188:191], v[220:223], v[0:3]
	v_mfma_f32_16x16x32_bf16 v[56:59], v[184:187], v[200:203], v[56:59]
	v_mfma_f32_16x16x32_bf16 v[48:51], v[192:195], v[200:203], v[48:51]
	v_mfma_f32_16x16x32_bf16 v[40:43], v[184:187], v[208:211], v[40:43]
	v_mfma_f32_16x16x32_bf16 v[32:35], v[192:195], v[208:211], v[32:35]
	v_mfma_f32_16x16x32_bf16 v[24:27], v[184:187], v[216:219], v[24:27]
	v_mfma_f32_16x16x32_bf16 v[16:19], v[192:195], v[216:219], v[16:19]
	v_mfma_f32_16x16x32_bf16 v[8:11], v[184:187], v[224:227], v[8:11]
	v_mfma_f32_16x16x32_bf16 v[0:3], v[192:195], v[224:227], v[0:3]
	s_barrier
; #define PG8_STAGE(bufoff, gbase, voff) do { _Pragma("unroll") for (int _i = 0; _i < 2; ++_i) \
;         __builtin_amdgcn_global_load_lds((const unsigned*)((const char*)(gbase) + (voff)[_i]), (PG8_LAS unsigned*)(lds + (bufoff) + ldsw + _i * 8192), 16, 0, 0); } while (0)
; #define PG8_LDA(dst, b, h) do { _Pragma("unroll") for (int m = 0; m < 4; ++m) _Pragma("unroll") for (int k = 0; k < 2; ++k) dst[m][k] = *(const PG8_LAS bf16x8*)(lds + PG8_SA(b, h) + aoff + m * 2048 + k * 1024); } while (0)
; #define PG8_LDB(dst, b, h) do { _Pragma("unroll") for (int n = 0; n < 2; ++n) _Pragma("unroll") for (int k = 0; k < 2; ++k) dst[n][k] = *(const PG8_LAS bf16x8*)(lds + PG8_SB(b, h) + boff + n * 2048 + k * 1024); } while (0)
; #define PG8_MMA(ai, bj, At, Bt) do { __builtin_amdgcn_s_setprio(1); _Pragma("unroll") for (int m = 0; m < 4; ++m) _Pragma("unroll") for (int n = 0; n < 2; ++n) _Pragma("unroll") for (int k = 0; k < 2; ++k) \
;         acc[ai][bj][m][n] = __builtin_amdgcn_mfma_f32_16x16x32_bf16(Bt[n][k], At[m][k], acc[ai][bj][m][n], 0, 0, 0); __builtin_amdgcn_s_setprio(0); } while (0)
; #define PG8_WAIT_V(n) asm volatile("s_waitcnt vmcnt(" #n ")" ::: "memory")
; #define PG8_WAIT_L(n) asm volatile("s_waitcnt lgkmcnt(" #n ")" ::: "memory")
; #define PG8_BAR __builtin_amdgcn_s_barrier()
; #define PG8_SCHED __builtin_amdgcn_sched_barrier(0)
; template <class Epi, class Sched, bool ALIGN_EPI = false, bool SP2 = false>
; __device__ __forceinline__ void gemm_phase(PG8_LAS unsigned char* lds, const Gemm g, const Sched& S, const Epi& E, const int wid) {
;     ...
;         for (int t = 0; t < nt; t += 2) {
;     ...
;             PG8_LDB(B0, 1, 0); PG8_LDB(B1, 1, 1); PG8_SCHED; PG8_LDA(At, 1, 0); PG8_STAGE(PG8_SA(0, 1), a2 + hstep, voffA);
;             PG8_WAIT_V(8); PG8_WAIT_L(0); PG8_BAR; PG8_MMA(0, 0, At, B0); PG8_MMA(0, 1, At, B1); PG8_BAR; PG8_SCHED;
;             PG8_LDA(At, 1, 1); PG8_STAGE(PG8_SB(1, 0), b3, voffB); PG8_STAGE(PG8_SB(1, 1), b3 + hstep, voffB); PG8_STAGE(PG8_SA(1, 0), a3, voffA);
;             PG8_WAIT_V(8); PG8_WAIT_L(0); PG8_BAR; PG8_MMA(1, 0, At, B0); PG8_MMA(1, 1, At, B1); PG8_BAR; PG8_SCHED;
	s_setprio 0
	s_add_i32 s61, 0, 0x18000
	s_add_i32 s62, 0, 0x1c000
	ds_read_b128 v[128:131], v246
	ds_read_b128 v[150:153], v246 offset:1024
	ds_read_b128 v[154:157], v246 offset:2048
	ds_read_b128 v[158:161], v246 offset:3072
	v_add_u32_e32 v140, s62, v165
	ds_read_b128 v[180:183], v140
	ds_read_b128 v[184:187], v140 offset:1024
	ds_read_b128 v[188:191], v140 offset:2048
	ds_read_b128 v[192:195], v140 offset:3072
	s_add_u32 s24, s24, 0x100000
	s_addc_u32 s25, s25, 0
	s_mov_b32 m0, s35
	ds_read_b128 v[196:199], v177 offset:32768
	ds_read_b128 v[200:203], v177 offset:33792
	ds_read_b128 v[204:207], v177 offset:34816
	ds_read_b128 v[208:211], v177 offset:35840
	ds_read_b128 v[212:215], v177 offset:36864
	ds_read_b128 v[216:219], v177 offset:37888
	ds_read_b128 v[220:223], v177 offset:38912
	ds_read_b128 v[224:227], v177 offset:39936
	global_load_lds_dwordx4 v138, s[24:25]
	s_mov_b32 m0, s36
	s_nop 0
	global_load_lds_dwordx4 v134, s[24:25]
	s_waitcnt vmcnt(8)
	s_waitcnt lgkmcnt(0)
	s_setprio 1
	s_barrier
	v_mfma_f32_16x16x32_bf16 v[124:127], v[128:131], v[196:199], v[124:127]
	v_mfma_f32_16x16x32_bf16 v[116:119], v[154:157], v[196:199], v[116:119]
	v_mfma_f32_16x16x32_bf16 v[108:111], v[128:131], v[204:207], v[108:111]
	v_mfma_f32_16x16x32_bf16 v[100:103], v[154:157], v[204:207], v[100:103]
	v_mfma_f32_16x16x32_bf16 v[92:95], v[128:131], v[212:215], v[92:95]
	v_mfma_f32_16x16x32_bf16 v[84:87], v[154:157], v[212:215], v[84:87]
	v_mfma_f32_16x16x32_bf16 v[76:79], v[128:131], v[220:223], v[76:79]
	v_mfma_f32_16x16x32_bf16 v[68:71], v[154:157], v[220:223], v[68:71]
	v_mfma_f32_16x16x32_bf16 v[124:127], v[150:153], v[200:203], v[124:127]
	v_mfma_f32_16x16x32_bf16 v[116:119], v[158:161], v[200:203], v[116:119]
	v_mfma_f32_16x16x32_bf16 v[108:111], v[150:153], v[208:211], v[108:111]
	v_mfma_f32_16x16x32_bf16 v[100:103], v[158:161], v[208:211], v[100:103]
	v_mfma_f32_16x16x32_bf16 v[92:95], v[150:153], v[216:219], v[92:95]
	v_mfma_f32_16x16x32_bf16 v[84:87], v[158:161], v[216:219], v[84:87]
	v_mfma_f32_16x16x32_bf16 v[76:79], v[150:153], v[224:227], v[76:79]
	v_mfma_f32_16x16x32_bf16 v[68:71], v[158:161], v[224:227], v[68:71]
	v_mfma_f32_16x16x32_bf16 v[120:123], v[180:183], v[196:199], v[120:123]
	v_mfma_f32_16x16x32_bf16 v[112:115], v[188:191], v[196:199], v[112:115]
	v_mfma_f32_16x16x32_bf16 v[104:107], v[180:183], v[204:207], v[104:107]
	v_mfma_f32_16x16x32_bf16 v[96:99], v[188:191], v[204:207], v[96:99]
	v_mfma_f32_16x16x32_bf16 v[88:91], v[180:183], v[212:215], v[88:91]
	v_mfma_f32_16x16x32_bf16 v[80:83], v[188:191], v[212:215], v[80:83]
	v_mfma_f32_16x16x32_bf16 v[72:75], v[180:183], v[220:223], v[72:75]
	v_mfma_f32_16x16x32_bf16 v[64:67], v[188:191], v[220:223], v[64:67]
	v_mfma_f32_16x16x32_bf16 v[120:123], v[184:187], v[200:203], v[120:123]
	v_mfma_f32_16x16x32_bf16 v[112:115], v[192:195], v[200:203], v[112:115]
	v_mfma_f32_16x16x32_bf16 v[104:107], v[184:187], v[208:211], v[104:107]
	v_mfma_f32_16x16x32_bf16 v[96:99], v[192:195], v[208:211], v[96:99]
	v_mfma_f32_16x16x32_bf16 v[88:91], v[184:187], v[216:219], v[88:91]
	v_mfma_f32_16x16x32_bf16 v[80:83], v[192:195], v[216:219], v[80:83]
	v_mfma_f32_16x16x32_bf16 v[72:75], v[184:187], v[224:227], v[72:75]
	v_mfma_f32_16x16x32_bf16 v[64:67], v[192:195], v[224:227], v[64:67]
	s_barrier
	s_setprio 0
	s_add_u32 s98, s22, 0x80
	s_addc_u32 s99, s23, 0
	s_add_u32 s100, s24, 0xfff00080
	s_addc_u32 s101, s25, -1
	s_add_i32 s24, s61, s28
	s_mov_b32 m0, s24
	ds_read_b128 v[196:199], v177 offset:49152
	ds_read_b128 v[200:203], v177 offset:50176
	ds_read_b128 v[204:207], v177 offset:51200
	ds_read_b128 v[208:211], v177 offset:52224
	ds_read_b128 v[212:215], v177 offset:53248
	ds_read_b128 v[216:219], v177 offset:54272
	ds_read_b128 v[220:223], v177 offset:55296
	ds_read_b128 v[224:227], v177 offset:56320
	global_load_lds_dwordx4 v136, s[98:99]
	s_add_i32 m0, s24, 0x2000
	s_add_u32 s22, s22, 0x100080
	s_addc_u32 s23, s23, 0
	s_add_i32 s24, s62, s28
	global_load_lds_dwordx4 v132, s[98:99]
	s_mov_b32 m0, s24
	s_nop 0
	global_load_lds_dwordx4 v136, s[22:23]
	s_add_i32 m0, s24, 0x2000
	s_nop 0
	global_load_lds_dwordx4 v132, s[22:23]
	s_mov_b32 m0, s38
	s_nop 0
	global_load_lds_dwordx4 v138, s[100:101]
	s_mov_b32 m0, s39
	s_nop 0
	global_load_lds_dwordx4 v134, s[100:101]
	s_waitcnt vmcnt(8)
	s_waitcnt lgkmcnt(0)
	s_setprio 1
	s_barrier
	v_mfma_f32_16x16x32_bf16 v[60:63], v[128:131], v[196:199], v[60:63]
	v_mfma_f32_16x16x32_bf16 v[52:55], v[154:157], v[196:199], v[52:55]
	v_mfma_f32_16x16x32_bf16 v[44:47], v[128:131], v[204:207], v[44:47]
	v_mfma_f32_16x16x32_bf16 v[36:39], v[154:157], v[204:207], v[36:39]
	v_mfma_f32_16x16x32_bf16 v[28:31], v[128:131], v[212:215], v[28:31]
	v_mfma_f32_16x16x32_bf16 v[20:23], v[154:157], v[212:215], v[20:23]
	v_mfma_f32_16x16x32_bf16 v[12:15], v[128:131], v[220:223], v[12:15]
	v_mfma_f32_16x16x32_bf16 v[4:7], v[154:157], v[220:223], v[4:7]
	v_mfma_f32_16x16x32_bf16 v[60:63], v[150:153], v[200:203], v[60:63]
	v_mfma_f32_16x16x32_bf16 v[52:55], v[158:161], v[200:203], v[52:55]
	v_mfma_f32_16x16x32_bf16 v[44:47], v[150:153], v[208:211], v[44:47]
	v_mfma_f32_16x16x32_bf16 v[36:39], v[158:161], v[208:211], v[36:39]
	v_mfma_f32_16x16x32_bf16 v[28:31], v[150:153], v[216:219], v[28:31]
	v_mfma_f32_16x16x32_bf16 v[20:23], v[158:161], v[216:219], v[20:23]
	v_mfma_f32_16x16x32_bf16 v[12:15], v[150:153], v[224:227], v[12:15]
	v_mfma_f32_16x16x32_bf16 v[4:7], v[158:161], v[224:227], v[4:7]
	v_mfma_f32_16x16x32_bf16 v[56:59], v[180:183], v[196:199], v[56:59]
	v_mfma_f32_16x16x32_bf16 v[48:51], v[188:191], v[196:199], v[48:51]
	v_mfma_f32_16x16x32_bf16 v[40:43], v[180:183], v[204:207], v[40:43]
	v_mfma_f32_16x16x32_bf16 v[32:35], v[188:191], v[204:207], v[32:35]
	v_mfma_f32_16x16x32_bf16 v[24:27], v[180:183], v[212:215], v[24:27]
	v_mfma_f32_16x16x32_bf16 v[16:19], v[188:191], v[212:215], v[16:19]
	v_mfma_f32_16x16x32_bf16 v[8:11], v[180:183], v[220:223], v[8:11]
	v_mfma_f32_16x16x32_bf16 v[0:3], v[188:191], v[220:223], v[0:3]
	v_mfma_f32_16x16x32_bf16 v[56:59], v[184:187], v[200:203], v[56:59]
	v_mfma_f32_16x16x32_bf16 v[48:51], v[192:195], v[200:203], v[48:51]
	v_mfma_f32_16x16x32_bf16 v[40:43], v[184:187], v[208:211], v[40:43]
	v_mfma_f32_16x16x32_bf16 v[32:35], v[192:195], v[208:211], v[32:35]
	v_mfma_f32_16x16x32_bf16 v[24:27], v[184:187], v[216:219], v[24:27]
	v_mfma_f32_16x16x32_bf16 v[16:19], v[192:195], v[216:219], v[16:19]
	v_mfma_f32_16x16x32_bf16 v[8:11], v[184:187], v[224:227], v[8:11]
	v_mfma_f32_16x16x32_bf16 v[0:3], v[192:195], v[224:227], v[0:3]
	s_barrier
	s_setprio 0
	s_add_i32 s60, s60, 2
	s_add_u32 s20, s20, 0x100
	s_addc_u32 s21, s21, 0
	s_add_u32 s58, s58, 0x100
	s_addc_u32 s59, s59, 0
	s_cmp_gt_u32 s60, 61
	s_cbranch_scc0 .LBB0_1250
	s_and_b64 vcc, exec, s[8:9]
	s_cbranch_vccz .LBB0_1253
	s_barrier

;     __device__ bool next(int i, Unit& u) const { const bool ok = StaticOrder::next(i, u); u.pm = 0; u.pn = 0; return ok; }
; #define PG8_STAGE(bufoff, gbase, voff) do { _Pragma("unroll") for (int _i = 0; _i < 2; ++_i) \
;         __builtin_amdgcn_global_load_lds((const unsigned*)((const char*)(gbase) + (voff)[_i]), (PG8_LAS unsigned*)(lds + (bufoff) + ldsw + _i * 8192), 16, 0, 0); } while (0)
; #define PG8_LDA(dst, b, h) do { _Pragma("unroll") for (int m = 0; m < 4; ++m) _Pragma("unroll") for (int k = 0; k < 2; ++k) dst[m][k] = *(const PG8_LAS bf16x8*)(lds + PG8_SA(b, h) + aoff + m * 2048 + k * 1024); } while (0)
; #define PG8_LDB(dst, b, h) do { _Pragma("unroll") for (int n = 0; n < 2; ++n) _Pragma("unroll") for (int k = 0; k < 2; ++k) dst[n][k] = *(const PG8_LAS bf16x8*)(lds + PG8_SB(b, h) + boff + n * 2048 + k * 1024); } while (0)
; #define PG8_SCHED __builtin_amdgcn_sched_barrier(0)
; template <class Epi, class Sched, bool ALIGN_EPI = false, bool SP2 = false>
; __device__ __forceinline__ void gemm_phase(PG8_LAS unsigned char* lds, const Gemm g, const Sched& S, const Epi& E, const int wid) {
;     ...
;         const bool has_next = S.next(ui + 1, nxt);
;         const char* nA = has_next ? (const char*)g.A + (size_t)nxt.pm * tstep + (size_t)nxt.kb * kstep : cA; const char* nB = has_next ? (const char*)g.Bt + (size_t)nxt.pn * tstep + (size_t)nxt.kb * kstep : cB;
;         for (int t = 0; t < nt; t += 2) {
;             const bool last = (t == nt - 2);
;             const char* a1 = cA + (size_t)(t + 1) * kstep;
;             const char* a2 = last ? nA : cA + (size_t)(t + 2) * kstep; const char* b2 = last ? nB : cB + (size_t)(t + 2) * kstep;
;             const char* a3 = a2 + kstep; const char* b3 = b2 + kstep;
;             if (last && has_next) S.a_ready(nxt);
;             if constexpr (SP2) {
;             PG8_LDB(B0, 0, 0); PG8_LDB(B1, 0, 1); PG8_SCHED; PG8_LDA(At, 0, 0); PG8_STAGE(PG8_SA(1, 1), a1 + hstep, voffA);
;     ...
; #pragma unroll
;         for (int a = 0; a < 2; ++a)
; #pragma unroll
;             for (int b = 0; b < 2; ++b)
; #pragma unroll
;                 for (int m = 0; m < 4; ++m)
; #pragma unroll
;                     for (int n = 0; n < 2; ++n) acc[a][b][m][n] = (f32x4){0.f, 0.f, 0.f, 0.f};
;         cur = nxt; cA = nA; cB = nB; ++ui; nt = cur.kn;
.LBB0_1670:
	s_ashr_i32 s15, s14, 31
	s_lshl_b64 s[16:17], s[14:15], 22
	s_add_u32 s16, s82, s16
	s_addc_u32 s17, s83, s17
	s_and_b64 s[18:19], s[2:3], exec
	s_cselect_b32 s15, s17, s25
	s_cselect_b32 s21, s16, s24
	s_ashr_i32 s13, s12, 31
	s_lshl_b64 s[18:19], s[12:13], 22
	s_add_u32 s18, s30, s18
	s_addc_u32 s19, s31, s19
	s_and_b64 s[28:29], s[2:3], exec
	s_cselect_b32 s13, s19, s27
	s_cselect_b32 s23, s18, s26
	s_add_u32 s24, s24, 0x200080
	s_addc_u32 s25, s25, 0
	s_add_u32 s48, s26, 0x100
	s_waitcnt vmcnt(0)
	v_mov_b32_e32 v64, 0
	s_addc_u32 s49, s27, 0
	s_mov_b32 s50, -2
	v_mov_b32_e32 v65, v64
	v_mov_b32_e32 v66, v64
	v_mov_b32_e32 v67, v64
	v_mov_b32_e32 v68, v64
	v_mov_b32_e32 v69, v64
	v_mov_b32_e32 v70, v64
	v_mov_b32_e32 v71, v64
	v_mov_b32_e32 v80, v64
	v_mov_b32_e32 v81, v64
	v_mov_b32_e32 v82, v64
	v_mov_b32_e32 v83, v64
	v_mov_b32_e32 v84, v64
	v_mov_b32_e32 v85, v64
	v_mov_b32_e32 v86, v64
	v_mov_b32_e32 v87, v64
	v_mov_b32_e32 v96, v64
	v_mov_b32_e32 v97, v64
	v_mov_b32_e32 v98, v64
	v_mov_b32_e32 v99, v64
	v_mov_b32_e32 v100, v64
	v_mov_b32_e32 v101, v64
	v_mov_b32_e32 v102, v64
	v_mov_b32_e32 v103, v64
	v_mov_b32_e32 v112, v64
	v_mov_b32_e32 v113, v64
	v_mov_b32_e32 v114, v64
	v_mov_b32_e32 v115, v64
	v_mov_b32_e32 v116, v64
	v_mov_b32_e32 v117, v64
	v_mov_b32_e32 v118, v64
	v_mov_b32_e32 v119, v64
	v_mov_b32_e32 v72, v64
	v_mov_b32_e32 v73, v64
	v_mov_b32_e32 v74, v64
	v_mov_b32_e32 v75, v64
	v_mov_b32_e32 v76, v64
	v_mov_b32_e32 v77, v64
	v_mov_b32_e32 v78, v64
	v_mov_b32_e32 v79, v64
	v_mov_b32_e32 v88, v64
	v_mov_b32_e32 v89, v64
	v_mov_b32_e32 v90, v64
	v_mov_b32_e32 v91, v64
	v_mov_b32_e32 v92, v64
	v_mov_b32_e32 v93, v64
	v_mov_b32_e32 v94, v64
	v_mov_b32_e32 v95, v64
	v_mov_b32_e32 v104, v64
	v_mov_b32_e32 v105, v64
	v_mov_b32_e32 v106, v64
	v_mov_b32_e32 v107, v64
	v_mov_b32_e32 v108, v64
	v_mov_b32_e32 v109, v64
	v_mov_b32_e32 v110, v64
	v_mov_b32_e32 v111, v64
	v_mov_b32_e32 v120, v64
	v_mov_b32_e32 v121, v64
	v_mov_b32_e32 v122, v64
	v_mov_b32_e32 v123, v64
	v_mov_b32_e32 v124, v64
	v_mov_b32_e32 v125, v64
	v_mov_b32_e32 v126, v64
	v_mov_b32_e32 v127, v64
	v_mov_b32_e32 v0, v64
	v_mov_b32_e32 v1, v64
	v_mov_b32_e32 v2, v64
	v_mov_b32_e32 v3, v64
	v_mov_b32_e32 v4, v64
	v_mov_b32_e32 v5, v64
	v_mov_b32_e32 v6, v64
	v_mov_b32_e32 v7, v64
	v_mov_b32_e32 v16, v64
	v_mov_b32_e32 v17, v64
	v_mov_b32_e32 v18, v64
	v_mov_b32_e32 v19, v64
	v_mov_b32_e32 v20, v64
	v_mov_b32_e32 v21, v64
	v_mov_b32_e32 v22, v64
	v_mov_b32_e32 v23, v64
	v_mov_b32_e32 v32, v64
	v_mov_b32_e32 v33, v64
	v_mov_b32_e32 v34, v64
	v_mov_b32_e32 v35, v64
	v_mov_b32_e32 v36, v64
	v_mov_b32_e32 v37, v64
	v_mov_b32_e32 v38, v64
	v_mov_b32_e32 v39, v64
	v_mov_b32_e32 v48, v64
	v_mov_b32_e32 v49, v64
	v_mov_b32_e32 v50, v64
	v_mov_b32_e32 v51, v64
	v_mov_b32_e32 v52, v64
	v_mov_b32_e32 v53, v64
	v_mov_b32_e32 v54, v64
	v_mov_b32_e32 v55, v64
	v_mov_b32_e32 v8, v64
	v_mov_b32_e32 v9, v64
	v_mov_b32_e32 v10, v64
	v_mov_b32_e32 v11, v64
	v_mov_b32_e32 v12, v64
	v_mov_b32_e32 v13, v64
	v_mov_b32_e32 v14, v64
	v_mov_b32_e32 v15, v64
	v_mov_b32_e32 v24, v64
	v_mov_b32_e32 v25, v64
	v_mov_b32_e32 v26, v64
	v_mov_b32_e32 v27, v64
	v_mov_b32_e32 v28, v64
	v_mov_b32_e32 v29, v64
	v_mov_b32_e32 v30, v64
	v_mov_b32_e32 v31, v64
	v_mov_b32_e32 v40, v64
	v_mov_b32_e32 v41, v64
	v_mov_b32_e32 v42, v64
	v_mov_b32_e32 v43, v64
	v_mov_b32_e32 v44, v64
	v_mov_b32_e32 v45, v64
	v_mov_b32_e32 v46, v64
	v_mov_b32_e32 v47, v64
	v_mov_b32_e32 v56, v64
	v_mov_b32_e32 v57, v64
	v_mov_b32_e32 v58, v64
	v_mov_b32_e32 v59, v64
	v_mov_b32_e32 v60, v64
	v_mov_b32_e32 v61, v64
	v_mov_b32_e32 v62, v64
	v_mov_b32_e32 v63, v64
	v_add_u32_e32 v246, 0x18000, v195
	v_add_u32_e32 v248, 0x1c000, v195
.LBB0_1671:
	ds_read_b128 v[128:131], v197
	ds_read_b128 v[132:135], v197 offset:1024
	ds_read_b128 v[136:139], v197 offset:2048
	ds_read_b128 v[140:143], v197 offset:3072
	ds_read_b128 v[144:147], v198
	ds_read_b128 v[148:151], v198 offset:1024
	ds_read_b128 v[176:179], v198 offset:2048
	ds_read_b128 v[180:183], v198 offset:3072
	s_add_u32 s26, s24, 0xffe00080
	s_addc_u32 s27, s25, -1
	s_cmpk_eq_i32 s50, 0x7c
	s_cselect_b32 s29, s15, s27
	s_cselect_b32 s28, s21, s26
	s_cselect_b32 s27, s13, s49
	s_cselect_b32 s26, s23, s48
	s_add_i32 m0, s35, 0xc000
	ds_read_b128 v[184:187], v199
	ds_read_b128 v[188:191], v199 offset:1024
	ds_read_b128 v[200:203], v199 offset:2048
	ds_read_b128 v[204:207], v199 offset:3072
	ds_read_b128 v[208:211], v199 offset:4096
	ds_read_b128 v[212:215], v199 offset:5120
	ds_read_b128 v[216:219], v199 offset:6144
	ds_read_b128 v[220:223], v199 offset:7168
	global_load_lds_dwordx4 v168, s[24:25]
	s_add_i32 m0, s35, 0xe000
	s_nop 0
	global_load_lds_dwordx4 v170, s[24:25]
	s_waitcnt vmcnt(8)
	s_waitcnt lgkmcnt(0)
	s_setprio 1
	s_barrier
; #define PG8_STAGE(bufoff, gbase, voff) do { _Pragma("unroll") for (int _i = 0; _i < 2; ++_i) \
;         __builtin_amdgcn_global_load_lds((const unsigned*)((const char*)(gbase) + (voff)[_i]), (PG8_LAS unsigned*)(lds + (bufoff) + ldsw + _i * 8192), 16, 0, 0); } while (0)
; #define PG8_LDA(dst, b, h) do { _Pragma("unroll") for (int m = 0; m < 4; ++m) _Pragma("unroll") for (int k = 0; k < 2; ++k) dst[m][k] = *(const PG8_LAS bf16x8*)(lds + PG8_SA(b, h) + aoff + m * 2048 + k * 1024); } while (0)
; #define PG8_MMA(ai, bj, At, Bt) do { __builtin_amdgcn_s_setprio(1); _Pragma("unroll") for (int m = 0; m < 4; ++m) _Pragma("unroll") for (int n = 0; n < 2; ++n) _Pragma("unroll") for (int k = 0; k < 2; ++k) \
;         acc[ai][bj][m][n] = __builtin_amdgcn_mfma_f32_16x16x32_bf16(Bt[n][k], At[m][k], acc[ai][bj][m][n], 0, 0, 0); __builtin_amdgcn_s_setprio(0); } while (0)
; #define PG8_WAIT_V(n) asm volatile("s_waitcnt vmcnt(" #n ")" ::: "memory")
; #define PG8_WAIT_L(n) asm volatile("s_waitcnt lgkmcnt(" #n ")" ::: "memory")
; #define PG8_BAR __builtin_amdgcn_s_barrier()
; #define PG8_SCHED __builtin_amdgcn_sched_barrier(0)
; template <class Epi, class Sched, bool ALIGN_EPI = false, bool SP2 = false>
; __device__ __forceinline__ void gemm_phase(PG8_LAS unsigned char* lds, const Gemm g, const Sched& S, const Epi& E, const int wid) {
;     ...
;             PG8_WAIT_V(8); PG8_WAIT_L(0); PG8_BAR; PG8_MMA(0, 0, At, B0); PG8_MMA(0, 1, At, B1); PG8_BAR; PG8_SCHED;
;             PG8_LDA(At, 0, 1); PG8_STAGE(PG8_SB(0, 0), b2, voffB); PG8_STAGE(PG8_SB(0, 1), b2 + hstep, voffB); PG8_STAGE(PG8_SA(0, 0), a2, voffA);
;             PG8_WAIT_V(8); PG8_WAIT_L(0); PG8_BAR; PG8_MMA(1, 0, At, B0); PG8_MMA(1, 1, At, B1); PG8_BAR; PG8_SCHED;
	v_mfma_f32_16x16x32_bf16 v[60:63], v[128:131], v[184:187], v[60:63]
	v_mfma_f32_16x16x32_bf16 v[56:59], v[136:139], v[184:187], v[56:59]
	v_mfma_f32_16x16x32_bf16 v[44:47], v[128:131], v[200:203], v[44:47]
	v_mfma_f32_16x16x32_bf16 v[40:43], v[136:139], v[200:203], v[40:43]
	v_mfma_f32_16x16x32_bf16 v[28:31], v[128:131], v[208:211], v[28:31]
	v_mfma_f32_16x16x32_bf16 v[24:27], v[136:139], v[208:211], v[24:27]
	v_mfma_f32_16x16x32_bf16 v[12:15], v[128:131], v[216:219], v[12:15]
	v_mfma_f32_16x16x32_bf16 v[8:11], v[136:139], v[216:219], v[8:11]
	v_mfma_f32_16x16x32_bf16 v[60:63], v[132:135], v[188:191], v[60:63]
	v_mfma_f32_16x16x32_bf16 v[56:59], v[140:143], v[188:191], v[56:59]
	v_mfma_f32_16x16x32_bf16 v[44:47], v[132:135], v[204:207], v[44:47]
	v_mfma_f32_16x16x32_bf16 v[40:43], v[140:143], v[204:207], v[40:43]
	v_mfma_f32_16x16x32_bf16 v[28:31], v[132:135], v[212:215], v[28:31]
	v_mfma_f32_16x16x32_bf16 v[24:27], v[140:143], v[212:215], v[24:27]
	v_mfma_f32_16x16x32_bf16 v[12:15], v[132:135], v[220:223], v[12:15]
	v_mfma_f32_16x16x32_bf16 v[8:11], v[140:143], v[220:223], v[8:11]
	v_mfma_f32_16x16x32_bf16 v[52:55], v[144:147], v[184:187], v[52:55]
	v_mfma_f32_16x16x32_bf16 v[48:51], v[176:179], v[184:187], v[48:51]
	v_mfma_f32_16x16x32_bf16 v[36:39], v[144:147], v[200:203], v[36:39]
	v_mfma_f32_16x16x32_bf16 v[32:35], v[176:179], v[200:203], v[32:35]
	v_mfma_f32_16x16x32_bf16 v[20:23], v[144:147], v[208:211], v[20:23]
	v_mfma_f32_16x16x32_bf16 v[16:19], v[176:179], v[208:211], v[16:19]
	v_mfma_f32_16x16x32_bf16 v[4:7], v[144:147], v[216:219], v[4:7]
	v_mfma_f32_16x16x32_bf16 v[0:3], v[176:179], v[216:219], v[0:3]
	v_mfma_f32_16x16x32_bf16 v[52:55], v[148:151], v[188:191], v[52:55]
	v_mfma_f32_16x16x32_bf16 v[48:51], v[180:183], v[188:191], v[48:51]
	v_mfma_f32_16x16x32_bf16 v[36:39], v[148:151], v[204:207], v[36:39]
	v_mfma_f32_16x16x32_bf16 v[32:35], v[180:183], v[204:207], v[32:35]
	v_mfma_f32_16x16x32_bf16 v[20:23], v[148:151], v[212:215], v[20:23]
	v_mfma_f32_16x16x32_bf16 v[16:19], v[180:183], v[212:215], v[16:19]
	v_mfma_f32_16x16x32_bf16 v[4:7], v[148:151], v[220:223], v[4:7]
	v_mfma_f32_16x16x32_bf16 v[0:3], v[180:183], v[220:223], v[0:3]
	s_barrier
	s_setprio 0
	s_add_i32 s51, s44, s34
	s_mov_b32 m0, s51
	ds_read_b128 v[184:187], v199 offset:16384
	ds_read_b128 v[188:191], v199 offset:17408
	ds_read_b128 v[200:203], v199 offset:18432
	ds_read_b128 v[204:207], v199 offset:19456
	ds_read_b128 v[208:211], v199 offset:20480
	ds_read_b128 v[212:215], v199 offset:21504
	ds_read_b128 v[216:219], v199 offset:22528
	ds_read_b128 v[220:223], v199 offset:23552
	global_load_lds_dwordx4 v154, s[26:27]
	s_add_i32 m0, s51, 0x2000
	s_add_u32 s52, s26, 0x200000
	s_addc_u32 s53, s27, 0
	s_add_i32 s51, s45, s34
	global_load_lds_dwordx4 v158, s[26:27]
	s_mov_b32 m0, s51
	global_load_lds_dwordx4 v154, s[52:53]
	s_add_i32 m0, s51, 0x2000
	s_nop 0
	global_load_lds_dwordx4 v158, s[52:53]
	s_mov_b32 m0, s35
	s_nop 0
	global_load_lds_dwordx4 v152, s[28:29]
	s_mov_b32 m0, s36
	s_nop 0
	global_load_lds_dwordx4 v156, s[28:29]
	s_waitcnt vmcnt(8)
	s_waitcnt lgkmcnt(0)
	s_setprio 1
	s_barrier
	v_mfma_f32_16x16x32_bf16 v[124:127], v[128:131], v[184:187], v[124:127]
	v_mfma_f32_16x16x32_bf16 v[120:123], v[136:139], v[184:187], v[120:123]
	v_mfma_f32_16x16x32_bf16 v[108:111], v[128:131], v[200:203], v[108:111]
	v_mfma_f32_16x16x32_bf16 v[104:107], v[136:139], v[200:203], v[104:107]
	v_mfma_f32_16x16x32_bf16 v[92:95], v[128:131], v[208:211], v[92:95]
	v_mfma_f32_16x16x32_bf16 v[88:91], v[136:139], v[208:211], v[88:91]
	v_mfma_f32_16x16x32_bf16 v[76:79], v[128:131], v[216:219], v[76:79]
	v_mfma_f32_16x16x32_bf16 v[72:75], v[136:139], v[216:219], v[72:75]
	v_mfma_f32_16x16x32_bf16 v[124:127], v[132:135], v[188:191], v[124:127]
	v_mfma_f32_16x16x32_bf16 v[120:123], v[140:143], v[188:191], v[120:123]
	v_mfma_f32_16x16x32_bf16 v[108:111], v[132:135], v[204:207], v[108:111]
	v_mfma_f32_16x16x32_bf16 v[104:107], v[140:143], v[204:207], v[104:107]
	v_mfma_f32_16x16x32_bf16 v[92:95], v[132:135], v[212:215], v[92:95]
	v_mfma_f32_16x16x32_bf16 v[88:91], v[140:143], v[212:215], v[88:91]
	v_mfma_f32_16x16x32_bf16 v[76:79], v[132:135], v[220:223], v[76:79]
	v_mfma_f32_16x16x32_bf16 v[72:75], v[140:143], v[220:223], v[72:75]
	v_mfma_f32_16x16x32_bf16 v[116:119], v[144:147], v[184:187], v[116:119]
	v_mfma_f32_16x16x32_bf16 v[112:115], v[176:179], v[184:187], v[112:115]
	v_mfma_f32_16x16x32_bf16 v[100:103], v[144:147], v[200:203], v[100:103]
	v_mfma_f32_16x16x32_bf16 v[96:99], v[176:179], v[200:203], v[96:99]
	v_mfma_f32_16x16x32_bf16 v[84:87], v[144:147], v[208:211], v[84:87]
	v_mfma_f32_16x16x32_bf16 v[80:83], v[176:179], v[208:211], v[80:83]
	v_mfma_f32_16x16x32_bf16 v[68:71], v[144:147], v[216:219], v[68:71]
	v_mfma_f32_16x16x32_bf16 v[64:67], v[176:179], v[216:219], v[64:67]
	v_mfma_f32_16x16x32_bf16 v[116:119], v[148:151], v[188:191], v[116:119]
	v_mfma_f32_16x16x32_bf16 v[112:115], v[180:183], v[188:191], v[112:115]
	v_mfma_f32_16x16x32_bf16 v[100:103], v[148:151], v[204:207], v[100:103]
	v_mfma_f32_16x16x32_bf16 v[96:99], v[180:183], v[204:207], v[96:99]
	v_mfma_f32_16x16x32_bf16 v[84:87], v[148:151], v[212:215], v[84:87]
	v_mfma_f32_16x16x32_bf16 v[80:83], v[180:183], v[212:215], v[80:83]
	v_mfma_f32_16x16x32_bf16 v[68:71], v[148:151], v[220:223], v[68:71]
	v_mfma_f32_16x16x32_bf16 v[64:67], v[180:183], v[220:223], v[64:67]
	s_barrier
; #define PG8_STAGE(bufoff, gbase, voff) do { _Pragma("unroll") for (int _i = 0; _i < 2; ++_i) \
;         __builtin_amdgcn_global_load_lds((const unsigned*)((const char*)(gbase) + (voff)[_i]), (PG8_LAS unsigned*)(lds + (bufoff) + ldsw + _i * 8192), 16, 0, 0); } while (0)
; #define PG8_LDA(dst, b, h) do { _Pragma("unroll") for (int m = 0; m < 4; ++m) _Pragma("unroll") for (int k = 0; k < 2; ++k) dst[m][k] = *(const PG8_LAS bf16x8*)(lds + PG8_SA(b, h) + aoff + m * 2048 + k * 1024); } while (0)
; #define PG8_LDB(dst, b, h) do { _Pragma("unroll") for (int n = 0; n < 2; ++n) _Pragma("unroll") for (int k = 0; k < 2; ++k) dst[n][k] = *(const PG8_LAS bf16x8*)(lds + PG8_SB(b, h) + boff + n * 2048 + k * 1024); } while (0)
; #define PG8_MMA(ai, bj, At, Bt) do { __builtin_amdgcn_s_setprio(1); _Pragma("unroll") for (int m = 0; m < 4; ++m) _Pragma("unroll") for (int n = 0; n < 2; ++n) _Pragma("unroll") for (int k = 0; k < 2; ++k) \
;         acc[ai][bj][m][n] = __builtin_amdgcn_mfma_f32_16x16x32_bf16(Bt[n][k], At[m][k], acc[ai][bj][m][n], 0, 0, 0); __builtin_amdgcn_s_setprio(0); } while (0)
; #define PG8_WAIT_V(n) asm volatile("s_waitcnt vmcnt(" #n ")" ::: "memory")
; #define PG8_WAIT_L(n) asm volatile("s_waitcnt lgkmcnt(" #n ")" ::: "memory")
; #define PG8_BAR __builtin_amdgcn_s_barrier()
; #define PG8_SCHED __builtin_amdgcn_sched_barrier(0)
;     __device__ __forceinline__ void operator()(const f32x4 (&acc)[2][2][4][2], const Unit& u, int wr, int wc, int fr, int fq) const {
;     ...
;         if (u.pm == MTOK / BM) {
; template <class Epi, class Sched, bool ALIGN_EPI = false, bool SP2 = false>
; __device__ __forceinline__ void gemm_phase(PG8_LAS unsigned char* lds, const Gemm g, const Sched& S, const Epi& E, const int wid) {
;     ...
;         for (int t = 0; t < nt; t += 2) {
;             const bool last = (t == nt - 2);
;     ...
;             PG8_LDB(B0, 1, 0); PG8_LDB(B1, 1, 1); PG8_SCHED; PG8_LDA(At, 1, 0); PG8_STAGE(PG8_SA(0, 1), a2 + hstep, voffA);
;             PG8_WAIT_V(8); PG8_WAIT_L(0); PG8_BAR; PG8_MMA(0, 0, At, B0); PG8_MMA(0, 1, At, B1); PG8_BAR; PG8_SCHED;
;             PG8_LDA(At, 1, 1); PG8_STAGE(PG8_SB(1, 0), b3, voffB); PG8_STAGE(PG8_SB(1, 1), b3 + hstep, voffB); PG8_STAGE(PG8_SA(1, 0), a3, voffA);
;             PG8_WAIT_V(8); PG8_WAIT_L(0); PG8_BAR; PG8_MMA(1, 0, At, B0); PG8_MMA(1, 1, At, B1); PG8_BAR; PG8_SCHED;
	s_setprio 0
	s_add_i32 s51, 0, 0x18000
	s_add_i32 s52, 0, 0x1c000
	ds_read_b128 v[128:131], v246
	ds_read_b128 v[132:135], v246 offset:1024
	ds_read_b128 v[136:139], v246 offset:2048
	ds_read_b128 v[140:143], v246 offset:3072
	ds_read_b128 v[144:147], v248
	ds_read_b128 v[148:151], v248 offset:1024
	ds_read_b128 v[176:179], v248 offset:2048
	ds_read_b128 v[180:183], v248 offset:3072
	s_add_u32 s28, s28, 0x200000
	s_addc_u32 s29, s29, 0
	s_mov_b32 m0, s37
	ds_read_b128 v[184:187], v199 offset:32768
	ds_read_b128 v[188:191], v199 offset:33792
	ds_read_b128 v[200:203], v199 offset:34816
	ds_read_b128 v[204:207], v199 offset:35840
	ds_read_b128 v[208:211], v199 offset:36864
	ds_read_b128 v[212:215], v199 offset:37888
	ds_read_b128 v[216:219], v199 offset:38912
	ds_read_b128 v[220:223], v199 offset:39936
	global_load_lds_dwordx4 v152, s[28:29]
	s_mov_b32 m0, s38
	s_nop 0
	global_load_lds_dwordx4 v156, s[28:29]
	s_waitcnt vmcnt(8)
	s_waitcnt lgkmcnt(0)
	s_setprio 1
	s_barrier
	v_mfma_f32_16x16x32_bf16 v[60:63], v[128:131], v[184:187], v[60:63]
	v_mfma_f32_16x16x32_bf16 v[56:59], v[136:139], v[184:187], v[56:59]
	v_mfma_f32_16x16x32_bf16 v[44:47], v[128:131], v[200:203], v[44:47]
	v_mfma_f32_16x16x32_bf16 v[40:43], v[136:139], v[200:203], v[40:43]
	v_mfma_f32_16x16x32_bf16 v[28:31], v[128:131], v[208:211], v[28:31]
	v_mfma_f32_16x16x32_bf16 v[24:27], v[136:139], v[208:211], v[24:27]
	v_mfma_f32_16x16x32_bf16 v[12:15], v[128:131], v[216:219], v[12:15]
	v_mfma_f32_16x16x32_bf16 v[8:11], v[136:139], v[216:219], v[8:11]
	v_mfma_f32_16x16x32_bf16 v[60:63], v[132:135], v[188:191], v[60:63]
	v_mfma_f32_16x16x32_bf16 v[56:59], v[140:143], v[188:191], v[56:59]
	v_mfma_f32_16x16x32_bf16 v[44:47], v[132:135], v[204:207], v[44:47]
	v_mfma_f32_16x16x32_bf16 v[40:43], v[140:143], v[204:207], v[40:43]
	v_mfma_f32_16x16x32_bf16 v[28:31], v[132:135], v[212:215], v[28:31]
	v_mfma_f32_16x16x32_bf16 v[24:27], v[140:143], v[212:215], v[24:27]
	v_mfma_f32_16x16x32_bf16 v[12:15], v[132:135], v[220:223], v[12:15]
	v_mfma_f32_16x16x32_bf16 v[8:11], v[140:143], v[220:223], v[8:11]
	v_mfma_f32_16x16x32_bf16 v[52:55], v[144:147], v[184:187], v[52:55]
	v_mfma_f32_16x16x32_bf16 v[48:51], v[176:179], v[184:187], v[48:51]
	v_mfma_f32_16x16x32_bf16 v[36:39], v[144:147], v[200:203], v[36:39]
	v_mfma_f32_16x16x32_bf16 v[32:35], v[176:179], v[200:203], v[32:35]
	v_mfma_f32_16x16x32_bf16 v[20:23], v[144:147], v[208:211], v[20:23]
	v_mfma_f32_16x16x32_bf16 v[16:19], v[176:179], v[208:211], v[16:19]
	v_mfma_f32_16x16x32_bf16 v[4:7], v[144:147], v[216:219], v[4:7]
	v_mfma_f32_16x16x32_bf16 v[0:3], v[176:179], v[216:219], v[0:3]
	v_mfma_f32_16x16x32_bf16 v[52:55], v[148:151], v[188:191], v[52:55]
	v_mfma_f32_16x16x32_bf16 v[48:51], v[180:183], v[188:191], v[48:51]
	v_mfma_f32_16x16x32_bf16 v[36:39], v[148:151], v[204:207], v[36:39]
	v_mfma_f32_16x16x32_bf16 v[32:35], v[180:183], v[204:207], v[32:35]
	v_mfma_f32_16x16x32_bf16 v[20:23], v[148:151], v[212:215], v[20:23]
	v_mfma_f32_16x16x32_bf16 v[16:19], v[180:183], v[212:215], v[16:19]
	v_mfma_f32_16x16x32_bf16 v[4:7], v[148:151], v[220:223], v[4:7]
	v_mfma_f32_16x16x32_bf16 v[0:3], v[180:183], v[220:223], v[0:3]
	s_barrier
	s_setprio 0
	s_add_u32 s98, s26, 0x80
	s_addc_u32 s99, s27, 0
	s_add_u32 s100, s28, 0xffe00080
	s_addc_u32 s101, s29, -1
	s_add_i32 s28, s51, s34
	s_mov_b32 m0, s28
	ds_read_b128 v[184:187], v199 offset:49152
	ds_read_b128 v[188:191], v199 offset:50176
	ds_read_b128 v[200:203], v199 offset:51200
	ds_read_b128 v[204:207], v199 offset:52224
	ds_read_b128 v[208:211], v199 offset:53248
	ds_read_b128 v[212:215], v199 offset:54272
	ds_read_b128 v[216:219], v199 offset:55296
	ds_read_b128 v[220:223], v199 offset:56320
	global_load_lds_dwordx4 v154, s[98:99]
	s_add_i32 m0, s28, 0x2000
	s_add_u32 s26, s26, 0x200080
	s_addc_u32 s27, s27, 0
	s_add_i32 s28, s52, s34
	global_load_lds_dwordx4 v158, s[98:99]
	s_mov_b32 m0, s28
	s_nop 0
	global_load_lds_dwordx4 v154, s[26:27]
	s_add_i32 m0, s28, 0x2000
	s_nop 0
	global_load_lds_dwordx4 v158, s[26:27]
	s_mov_b32 m0, s40
	s_nop 0
	global_load_lds_dwordx4 v152, s[100:101]
	s_mov_b32 m0, s41
	s_nop 0
	global_load_lds_dwordx4 v156, s[100:101]
	s_waitcnt vmcnt(8)
	s_waitcnt lgkmcnt(0)
	s_setprio 1
	s_barrier
	v_mfma_f32_16x16x32_bf16 v[124:127], v[128:131], v[184:187], v[124:127]
	v_mfma_f32_16x16x32_bf16 v[120:123], v[136:139], v[184:187], v[120:123]
	v_mfma_f32_16x16x32_bf16 v[108:111], v[128:131], v[200:203], v[108:111]
	v_mfma_f32_16x16x32_bf16 v[104:107], v[136:139], v[200:203], v[104:107]
	v_mfma_f32_16x16x32_bf16 v[92:95], v[128:131], v[208:211], v[92:95]
	v_mfma_f32_16x16x32_bf16 v[88:91], v[136:139], v[208:211], v[88:91]
	v_mfma_f32_16x16x32_bf16 v[76:79], v[128:131], v[216:219], v[76:79]
	v_mfma_f32_16x16x32_bf16 v[72:75], v[136:139], v[216:219], v[72:75]
	v_mfma_f32_16x16x32_bf16 v[124:127], v[132:135], v[188:191], v[124:127]
	v_mfma_f32_16x16x32_bf16 v[120:123], v[140:143], v[188:191], v[120:123]
	v_mfma_f32_16x16x32_bf16 v[108:111], v[132:135], v[204:207], v[108:111]
	v_mfma_f32_16x16x32_bf16 v[104:107], v[140:143], v[204:207], v[104:107]
	v_mfma_f32_16x16x32_bf16 v[92:95], v[132:135], v[212:215], v[92:95]
	v_mfma_f32_16x16x32_bf16 v[88:91], v[140:143], v[212:215], v[88:91]
	v_mfma_f32_16x16x32_bf16 v[76:79], v[132:135], v[220:223], v[76:79]
	v_mfma_f32_16x16x32_bf16 v[72:75], v[140:143], v[220:223], v[72:75]
	v_mfma_f32_16x16x32_bf16 v[116:119], v[144:147], v[184:187], v[116:119]
	v_mfma_f32_16x16x32_bf16 v[112:115], v[176:179], v[184:187], v[112:115]
	v_mfma_f32_16x16x32_bf16 v[100:103], v[144:147], v[200:203], v[100:103]
	v_mfma_f32_16x16x32_bf16 v[96:99], v[176:179], v[200:203], v[96:99]
	v_mfma_f32_16x16x32_bf16 v[84:87], v[144:147], v[208:211], v[84:87]
	v_mfma_f32_16x16x32_bf16 v[80:83], v[176:179], v[208:211], v[80:83]
	v_mfma_f32_16x16x32_bf16 v[68:71], v[144:147], v[216:219], v[68:71]
	v_mfma_f32_16x16x32_bf16 v[64:67], v[176:179], v[216:219], v[64:67]
	v_mfma_f32_16x16x32_bf16 v[116:119], v[148:151], v[188:191], v[116:119]
	v_mfma_f32_16x16x32_bf16 v[112:115], v[180:183], v[188:191], v[112:115]
	v_mfma_f32_16x16x32_bf16 v[100:103], v[148:151], v[204:207], v[100:103]
	v_mfma_f32_16x16x32_bf16 v[96:99], v[180:183], v[204:207], v[96:99]
	v_mfma_f32_16x16x32_bf16 v[84:87], v[148:151], v[212:215], v[84:87]
	v_mfma_f32_16x16x32_bf16 v[80:83], v[180:183], v[212:215], v[80:83]
	v_mfma_f32_16x16x32_bf16 v[68:71], v[148:151], v[220:223], v[68:71]
	v_mfma_f32_16x16x32_bf16 v[64:67], v[180:183], v[220:223], v[64:67]
	s_barrier
	s_setprio 0
	s_add_i32 s50, s50, 2
	s_add_u32 s24, s24, 0x100
	s_addc_u32 s25, s25, 0
	s_add_u32 s48, s48, 0x100
	s_addc_u32 s49, s49, 0
	s_cmpk_gt_u32 s50, 0x7d
	s_cbranch_scc0 .LBB0_1671
	s_and_b64 vcc, exec, s[10:11]
	s_cbranch_vccnz .LBB0_1675
	v_lshl_add_u32 v176, s22, 8, v196
	s_cmp_eq_u32 s20, 64
	s_mov_b64 s[22:23], -1
	s_cbranch_scc0 .LBB0_1676

;     __device__ bool next(int i, Unit& u) const { const bool ok = StaticOrder::next(i, u); u.pm = 0; u.pn = 0; return ok; }
; #define PG8_STAGE(bufoff, gbase, voff) do { _Pragma("unroll") for (int _i = 0; _i < 2; ++_i) \
;         __builtin_amdgcn_global_load_lds((const unsigned*)((const char*)(gbase) + (voff)[_i]), (PG8_LAS unsigned*)(lds + (bufoff) + ldsw + _i * 8192), 16, 0, 0); } while (0)
; #define PG8_LDA(dst, b, h) do { _Pragma("unroll") for (int m = 0; m < 4; ++m) _Pragma("unroll") for (int k = 0; k < 2; ++k) dst[m][k] = *(const PG8_LAS bf16x8*)(lds + PG8_SA(b, h) + aoff + m * 2048 + k * 1024); } while (0)
; #define PG8_LDB(dst, b, h) do { _Pragma("unroll") for (int n = 0; n < 2; ++n) _Pragma("unroll") for (int k = 0; k < 2; ++k) dst[n][k] = *(const PG8_LAS bf16x8*)(lds + PG8_SB(b, h) + boff + n * 2048 + k * 1024); } while (0)
; #define PG8_SCHED __builtin_amdgcn_sched_barrier(0)
; template <class Epi, class Sched, bool ALIGN_EPI = false, bool SP2 = false>
; __device__ __forceinline__ void gemm_phase(PG8_LAS unsigned char* lds, const Gemm g, const Sched& S, const Epi& E, const int wid) {
;     ...
;         const bool has_next = S.next(ui + 1, nxt);
;         const char* nA = has_next ? (const char*)g.A + (size_t)nxt.pm * tstep + (size_t)nxt.kb * kstep : cA; const char* nB = has_next ? (const char*)g.Bt + (size_t)nxt.pn * tstep + (size_t)nxt.kb * kstep : cB;
;         for (int t = 0; t < nt; t += 2) {
;             const bool last = (t == nt - 2);
;             const char* a1 = cA + (size_t)(t + 1) * kstep;
;             const char* a2 = last ? nA : cA + (size_t)(t + 2) * kstep; const char* b2 = last ? nB : cB + (size_t)(t + 2) * kstep;
;             const char* a3 = a2 + kstep; const char* b3 = b2 + kstep;
;             if (last && has_next) S.a_ready(nxt);
;             if constexpr (SP2) {
;             PG8_LDB(B0, 0, 0); PG8_LDB(B1, 0, 1); PG8_SCHED; PG8_LDA(At, 0, 0); PG8_STAGE(PG8_SA(1, 1), a1 + hstep, voffA);
;     ...
; #pragma unroll
;         for (int a = 0; a < 2; ++a)
; #pragma unroll
;             for (int b = 0; b < 2; ++b)
; #pragma unroll
;                 for (int m = 0; m < 4; ++m)
; #pragma unroll
;                     for (int n = 0; n < 2; ++n) acc[a][b][m][n] = (f32x4){0.f, 0.f, 0.f, 0.f};
;         cur = nxt; cA = nA; cB = nB; ++ui; nt = cur.kn;
.LBB0_1763:
	v_lshl_add_u32 v244, s20, 8, v151
	v_ashrrev_i32_e32 v245, 31, v244
	v_lshl_add_u64 v[244:245], v[244:245], 3, s[4:5]
	global_load_dwordx2 v[228:229], v[244:245], off
	global_load_dwordx2 v[230:231], v[244:245], off offset:128
	global_load_dwordx2 v[232:233], v[244:245], off offset:256
	global_load_dwordx2 v[234:235], v[244:245], off offset:384
	global_load_dwordx2 v[236:237], v[244:245], off offset:1024
	global_load_dwordx2 v[238:239], v[244:245], off offset:1152
	global_load_dwordx2 v[240:241], v[244:245], off offset:1280
	global_load_dwordx2 v[242:243], v[244:245], off offset:1408
	s_ashr_i32 s15, s14, 31
	s_lshl_b64 s[16:17], s[14:15], 21
	s_add_u32 s16, s78, s16
	s_addc_u32 s17, s79, s17
	s_and_b64 s[18:19], s[0:1], exec
	s_cselect_b32 s15, s17, s23
	s_cselect_b32 s47, s16, s22
	s_ashr_i32 s13, s12, 31
	s_lshl_b64 s[18:19], s[12:13], 21
	s_add_u32 s18, s38, s18
	s_addc_u32 s19, s39, s19
	s_and_b64 s[26:27], s[0:1], exec
	s_cselect_b32 s13, s19, s25
	s_cselect_b32 s48, s18, s24
	s_add_u32 s22, s22, 0x100080
	s_addc_u32 s23, s23, 0
	s_add_u32 s49, s24, 0x100
	v_mov_b32_e32 v0, 0
	s_addc_u32 s50, s25, 0
	s_mov_b32 s51, -2
	v_mov_b32_e32 v1, v0
	v_mov_b32_e32 v2, v0
	v_mov_b32_e32 v3, v0
	v_mov_b32_e32 v4, v0
	v_mov_b32_e32 v5, v0
	v_mov_b32_e32 v6, v0
	v_mov_b32_e32 v7, v0
	v_mov_b32_e32 v16, v0
	v_mov_b32_e32 v17, v0
	v_mov_b32_e32 v18, v0
	v_mov_b32_e32 v19, v0
	v_mov_b32_e32 v20, v0
	v_mov_b32_e32 v21, v0
	v_mov_b32_e32 v22, v0
	v_mov_b32_e32 v23, v0
	v_mov_b32_e32 v32, v0
	v_mov_b32_e32 v33, v0
	v_mov_b32_e32 v34, v0
	v_mov_b32_e32 v35, v0
	v_mov_b32_e32 v36, v0
	v_mov_b32_e32 v37, v0
	v_mov_b32_e32 v38, v0
	v_mov_b32_e32 v39, v0
	v_mov_b32_e32 v48, v0
	v_mov_b32_e32 v49, v0
	v_mov_b32_e32 v50, v0
	v_mov_b32_e32 v51, v0
	v_mov_b32_e32 v52, v0
	v_mov_b32_e32 v53, v0
	v_mov_b32_e32 v54, v0
	v_mov_b32_e32 v55, v0
	v_mov_b32_e32 v8, v0
	v_mov_b32_e32 v9, v0
	v_mov_b32_e32 v10, v0
	v_mov_b32_e32 v11, v0
	v_mov_b32_e32 v12, v0
	v_mov_b32_e32 v13, v0
	v_mov_b32_e32 v14, v0
	v_mov_b32_e32 v15, v0
	v_mov_b32_e32 v24, v0
	v_mov_b32_e32 v25, v0
	v_mov_b32_e32 v26, v0
	v_mov_b32_e32 v27, v0
	v_mov_b32_e32 v28, v0
	v_mov_b32_e32 v29, v0
	v_mov_b32_e32 v30, v0
	v_mov_b32_e32 v31, v0
	v_mov_b32_e32 v40, v0
	v_mov_b32_e32 v41, v0
	v_mov_b32_e32 v42, v0
	v_mov_b32_e32 v43, v0
	v_mov_b32_e32 v44, v0
	v_mov_b32_e32 v45, v0
	v_mov_b32_e32 v46, v0
	v_mov_b32_e32 v47, v0
	v_mov_b32_e32 v56, v0
	v_mov_b32_e32 v57, v0
	v_mov_b32_e32 v58, v0
	v_mov_b32_e32 v59, v0
	v_mov_b32_e32 v60, v0
	v_mov_b32_e32 v61, v0
	v_mov_b32_e32 v62, v0
	v_mov_b32_e32 v63, v0
	v_mov_b32_e32 v64, v0
	v_mov_b32_e32 v65, v0
	v_mov_b32_e32 v66, v0
	v_mov_b32_e32 v67, v0
	v_mov_b32_e32 v68, v0
	v_mov_b32_e32 v69, v0
	v_mov_b32_e32 v70, v0
	v_mov_b32_e32 v71, v0
	v_mov_b32_e32 v80, v0
	v_mov_b32_e32 v81, v0
	v_mov_b32_e32 v82, v0
	v_mov_b32_e32 v83, v0
	v_mov_b32_e32 v84, v0
	v_mov_b32_e32 v85, v0
	v_mov_b32_e32 v86, v0
	v_mov_b32_e32 v87, v0
	v_mov_b32_e32 v96, v0
	v_mov_b32_e32 v97, v0
	v_mov_b32_e32 v98, v0
	v_mov_b32_e32 v99, v0
	v_mov_b32_e32 v100, v0
	v_mov_b32_e32 v101, v0
	v_mov_b32_e32 v102, v0
	v_mov_b32_e32 v103, v0
	v_mov_b32_e32 v112, v0
	v_mov_b32_e32 v113, v0
	v_mov_b32_e32 v114, v0
	v_mov_b32_e32 v115, v0
	v_mov_b32_e32 v116, v0
	v_mov_b32_e32 v117, v0
	v_mov_b32_e32 v118, v0
	v_mov_b32_e32 v119, v0
	v_mov_b32_e32 v72, v0
	v_mov_b32_e32 v73, v0
	v_mov_b32_e32 v74, v0
	v_mov_b32_e32 v75, v0
	v_mov_b32_e32 v76, v0
	v_mov_b32_e32 v77, v0
	v_mov_b32_e32 v78, v0
	v_mov_b32_e32 v79, v0
	v_mov_b32_e32 v88, v0
	v_mov_b32_e32 v89, v0
	v_mov_b32_e32 v90, v0
	v_mov_b32_e32 v91, v0
	v_mov_b32_e32 v92, v0
	v_mov_b32_e32 v93, v0
	v_mov_b32_e32 v94, v0
	v_mov_b32_e32 v95, v0
	v_mov_b32_e32 v104, v0
	v_mov_b32_e32 v105, v0
	v_mov_b32_e32 v106, v0
	v_mov_b32_e32 v107, v0
	v_mov_b32_e32 v108, v0
	v_mov_b32_e32 v109, v0
	v_mov_b32_e32 v110, v0
	v_mov_b32_e32 v111, v0
	v_mov_b32_e32 v120, v0
	v_mov_b32_e32 v121, v0
	v_mov_b32_e32 v122, v0
	v_mov_b32_e32 v123, v0
	v_mov_b32_e32 v124, v0
	v_mov_b32_e32 v125, v0
	v_mov_b32_e32 v126, v0
	v_mov_b32_e32 v127, v0
	v_add_u32_e32 v246, 0x18000, v152
	v_add_u32_e32 v248, 0x1c000, v152
.LBB0_1764:
	ds_read_b128 v[146:149], v154
	ds_read_b128 v[158:161], v154 offset:1024
	ds_read_b128 v[162:165], v154 offset:2048
	ds_read_b128 v[166:169], v154 offset:3072
	ds_read_b128 v[170:173], v155
	ds_read_b128 v[174:177], v155 offset:1024
	ds_read_b128 v[178:181], v155 offset:2048
	ds_read_b128 v[182:185], v155 offset:3072
	s_add_u32 s24, s22, 0xfff00080
	s_addc_u32 s25, s23, -1
	s_cmp_eq_u32 s51, 60
	s_cselect_b32 s27, s15, s25
	s_cselect_b32 s26, s47, s24
	s_cselect_b32 s25, s13, s50
	s_cselect_b32 s24, s48, s49
	s_add_i32 m0, s21, 0xc000
	ds_read_b128 v[186:189], v156
	ds_read_b128 v[190:193], v156 offset:1024
	ds_read_b128 v[194:197], v156 offset:2048
	ds_read_b128 v[198:201], v156 offset:3072
	ds_read_b128 v[202:205], v156 offset:4096
	ds_read_b128 v[206:209], v156 offset:5120
	ds_read_b128 v[210:213], v156 offset:6144
	ds_read_b128 v[214:217], v156 offset:7168
	global_load_lds_dwordx4 v138, s[22:23]
	s_add_i32 m0, s21, 0xe000
	s_nop 0
	global_load_lds_dwordx4 v140, s[22:23]
	s_waitcnt vmcnt(8)
	s_waitcnt lgkmcnt(0)
	s_setprio 1
	s_barrier
; #define PG8_STAGE(bufoff, gbase, voff) do { _Pragma("unroll") for (int _i = 0; _i < 2; ++_i) \
;         __builtin_amdgcn_global_load_lds((const unsigned*)((const char*)(gbase) + (voff)[_i]), (PG8_LAS unsigned*)(lds + (bufoff) + ldsw + _i * 8192), 16, 0, 0); } while (0)
; #define PG8_LDA(dst, b, h) do { _Pragma("unroll") for (int m = 0; m < 4; ++m) _Pragma("unroll") for (int k = 0; k < 2; ++k) dst[m][k] = *(const PG8_LAS bf16x8*)(lds + PG8_SA(b, h) + aoff + m * 2048 + k * 1024); } while (0)
; #define PG8_MMA(ai, bj, At, Bt) do { __builtin_amdgcn_s_setprio(1); _Pragma("unroll") for (int m = 0; m < 4; ++m) _Pragma("unroll") for (int n = 0; n < 2; ++n) _Pragma("unroll") for (int k = 0; k < 2; ++k) \
;         acc[ai][bj][m][n] = __builtin_amdgcn_mfma_f32_16x16x32_bf16(Bt[n][k], At[m][k], acc[ai][bj][m][n], 0, 0, 0); __builtin_amdgcn_s_setprio(0); } while (0)
; #define PG8_WAIT_V(n) asm volatile("s_waitcnt vmcnt(" #n ")" ::: "memory")
; #define PG8_WAIT_L(n) asm volatile("s_waitcnt lgkmcnt(" #n ")" ::: "memory")
; #define PG8_BAR __builtin_amdgcn_s_barrier()
; #define PG8_SCHED __builtin_amdgcn_sched_barrier(0)
; template <class Epi, class Sched, bool ALIGN_EPI = false, bool SP2 = false>
; __device__ __forceinline__ void gemm_phase(PG8_LAS unsigned char* lds, const Gemm g, const Sched& S, const Epi& E, const int wid) {
;     ...
;             PG8_WAIT_V(8); PG8_WAIT_L(0); PG8_BAR; PG8_MMA(0, 0, At, B0); PG8_MMA(0, 1, At, B1); PG8_BAR; PG8_SCHED;
;             PG8_LDA(At, 0, 1); PG8_STAGE(PG8_SB(0, 0), b2, voffB); PG8_STAGE(PG8_SB(0, 1), b2 + hstep, voffB); PG8_STAGE(PG8_SA(0, 0), a2, voffA);
;             PG8_WAIT_V(8); PG8_WAIT_L(0); PG8_BAR; PG8_MMA(1, 0, At, B0); PG8_MMA(1, 1, At, B1); PG8_BAR; PG8_SCHED;
	v_mfma_f32_16x16x32_bf16 v[124:127], v[146:149], v[186:189], v[124:127]
	v_mfma_f32_16x16x32_bf16 v[120:123], v[162:165], v[186:189], v[120:123]
	v_mfma_f32_16x16x32_bf16 v[108:111], v[146:149], v[194:197], v[108:111]
	v_mfma_f32_16x16x32_bf16 v[104:107], v[162:165], v[194:197], v[104:107]
	v_mfma_f32_16x16x32_bf16 v[92:95], v[146:149], v[202:205], v[92:95]
	v_mfma_f32_16x16x32_bf16 v[88:91], v[162:165], v[202:205], v[88:91]
	v_mfma_f32_16x16x32_bf16 v[76:79], v[146:149], v[210:213], v[76:79]
	v_mfma_f32_16x16x32_bf16 v[72:75], v[162:165], v[210:213], v[72:75]
	v_mfma_f32_16x16x32_bf16 v[124:127], v[158:161], v[190:193], v[124:127]
	v_mfma_f32_16x16x32_bf16 v[120:123], v[166:169], v[190:193], v[120:123]
	v_mfma_f32_16x16x32_bf16 v[108:111], v[158:161], v[198:201], v[108:111]
	v_mfma_f32_16x16x32_bf16 v[104:107], v[166:169], v[198:201], v[104:107]
	v_mfma_f32_16x16x32_bf16 v[92:95], v[158:161], v[206:209], v[92:95]
	v_mfma_f32_16x16x32_bf16 v[88:91], v[166:169], v[206:209], v[88:91]
	v_mfma_f32_16x16x32_bf16 v[76:79], v[158:161], v[214:217], v[76:79]
	v_mfma_f32_16x16x32_bf16 v[72:75], v[166:169], v[214:217], v[72:75]
	v_mfma_f32_16x16x32_bf16 v[116:119], v[170:173], v[186:189], v[116:119]
	v_mfma_f32_16x16x32_bf16 v[112:115], v[178:181], v[186:189], v[112:115]
	v_mfma_f32_16x16x32_bf16 v[100:103], v[170:173], v[194:197], v[100:103]
	v_mfma_f32_16x16x32_bf16 v[96:99], v[178:181], v[194:197], v[96:99]
	v_mfma_f32_16x16x32_bf16 v[84:87], v[170:173], v[202:205], v[84:87]
	v_mfma_f32_16x16x32_bf16 v[80:83], v[178:181], v[202:205], v[80:83]
	v_mfma_f32_16x16x32_bf16 v[68:71], v[170:173], v[210:213], v[68:71]
	v_mfma_f32_16x16x32_bf16 v[64:67], v[178:181], v[210:213], v[64:67]
	v_mfma_f32_16x16x32_bf16 v[116:119], v[174:177], v[190:193], v[116:119]
	v_mfma_f32_16x16x32_bf16 v[112:115], v[182:185], v[190:193], v[112:115]
	v_mfma_f32_16x16x32_bf16 v[100:103], v[174:177], v[198:201], v[100:103]
	v_mfma_f32_16x16x32_bf16 v[96:99], v[182:185], v[198:201], v[96:99]
	v_mfma_f32_16x16x32_bf16 v[84:87], v[174:177], v[206:209], v[84:87]
	v_mfma_f32_16x16x32_bf16 v[80:83], v[182:185], v[206:209], v[80:83]
	v_mfma_f32_16x16x32_bf16 v[68:71], v[174:177], v[214:217], v[68:71]
	v_mfma_f32_16x16x32_bf16 v[64:67], v[182:185], v[214:217], v[64:67]
	s_barrier
	s_setprio 0
	s_add_i32 s52, s42, s28
	s_mov_b32 m0, s52
	ds_read_b128 v[186:189], v156 offset:16384
	ds_read_b128 v[190:193], v156 offset:17408
	ds_read_b128 v[194:197], v156 offset:18432
	ds_read_b128 v[198:201], v156 offset:19456
	ds_read_b128 v[202:205], v156 offset:20480
	ds_read_b128 v[206:209], v156 offset:21504
	ds_read_b128 v[210:213], v156 offset:22528
	ds_read_b128 v[214:217], v156 offset:23552
	global_load_lds_dwordx4 v132, s[24:25]
	s_add_i32 m0, s52, 0x2000
	s_add_u32 s52, s24, 0x100000
	s_addc_u32 s53, s25, 0
	s_add_i32 s54, s43, s28
	global_load_lds_dwordx4 v128, s[24:25]
	s_mov_b32 m0, s54
	global_load_lds_dwordx4 v132, s[52:53]
	s_add_i32 m0, s54, 0x2000
	s_nop 0
	global_load_lds_dwordx4 v128, s[52:53]
	s_mov_b32 m0, s21
	s_nop 0
	global_load_lds_dwordx4 v134, s[26:27]
	s_mov_b32 m0, s31
	s_nop 0
	global_load_lds_dwordx4 v130, s[26:27]
	s_waitcnt vmcnt(8)
	s_waitcnt lgkmcnt(0)
	s_setprio 1
	s_barrier
	v_mfma_f32_16x16x32_bf16 v[60:63], v[146:149], v[186:189], v[60:63]
	v_mfma_f32_16x16x32_bf16 v[56:59], v[162:165], v[186:189], v[56:59]
	v_mfma_f32_16x16x32_bf16 v[44:47], v[146:149], v[194:197], v[44:47]
	v_mfma_f32_16x16x32_bf16 v[40:43], v[162:165], v[194:197], v[40:43]
	v_mfma_f32_16x16x32_bf16 v[28:31], v[146:149], v[202:205], v[28:31]
	v_mfma_f32_16x16x32_bf16 v[24:27], v[162:165], v[202:205], v[24:27]
	v_mfma_f32_16x16x32_bf16 v[12:15], v[146:149], v[210:213], v[12:15]
	v_mfma_f32_16x16x32_bf16 v[8:11], v[162:165], v[210:213], v[8:11]
	v_mfma_f32_16x16x32_bf16 v[60:63], v[158:161], v[190:193], v[60:63]
	v_mfma_f32_16x16x32_bf16 v[56:59], v[166:169], v[190:193], v[56:59]
	v_mfma_f32_16x16x32_bf16 v[44:47], v[158:161], v[198:201], v[44:47]
	v_mfma_f32_16x16x32_bf16 v[40:43], v[166:169], v[198:201], v[40:43]
	v_mfma_f32_16x16x32_bf16 v[28:31], v[158:161], v[206:209], v[28:31]
	v_mfma_f32_16x16x32_bf16 v[24:27], v[166:169], v[206:209], v[24:27]
	v_mfma_f32_16x16x32_bf16 v[12:15], v[158:161], v[214:217], v[12:15]
	v_mfma_f32_16x16x32_bf16 v[8:11], v[166:169], v[214:217], v[8:11]
	v_mfma_f32_16x16x32_bf16 v[52:55], v[170:173], v[186:189], v[52:55]
	v_mfma_f32_16x16x32_bf16 v[48:51], v[178:181], v[186:189], v[48:51]
	v_mfma_f32_16x16x32_bf16 v[36:39], v[170:173], v[194:197], v[36:39]
	v_mfma_f32_16x16x32_bf16 v[32:35], v[178:181], v[194:197], v[32:35]
	v_mfma_f32_16x16x32_bf16 v[20:23], v[170:173], v[202:205], v[20:23]
	v_mfma_f32_16x16x32_bf16 v[16:19], v[178:181], v[202:205], v[16:19]
	v_mfma_f32_16x16x32_bf16 v[4:7], v[170:173], v[210:213], v[4:7]
	v_mfma_f32_16x16x32_bf16 v[0:3], v[178:181], v[210:213], v[0:3]
	v_mfma_f32_16x16x32_bf16 v[52:55], v[174:177], v[190:193], v[52:55]
	v_mfma_f32_16x16x32_bf16 v[48:51], v[182:185], v[190:193], v[48:51]
	v_mfma_f32_16x16x32_bf16 v[36:39], v[174:177], v[198:201], v[36:39]
	v_mfma_f32_16x16x32_bf16 v[32:35], v[182:185], v[198:201], v[32:35]
	v_mfma_f32_16x16x32_bf16 v[20:23], v[174:177], v[206:209], v[20:23]
	v_mfma_f32_16x16x32_bf16 v[16:19], v[182:185], v[206:209], v[16:19]
	v_mfma_f32_16x16x32_bf16 v[4:7], v[174:177], v[214:217], v[4:7]
	v_mfma_f32_16x16x32_bf16 v[0:3], v[182:185], v[214:217], v[0:3]
	s_barrier
; #define PG8_STAGE(bufoff, gbase, voff) do { _Pragma("unroll") for (int _i = 0; _i < 2; ++_i) \
;         __builtin_amdgcn_global_load_lds((const unsigned*)((const char*)(gbase) + (voff)[_i]), (PG8_LAS unsigned*)(lds + (bufoff) + ldsw + _i * 8192), 16, 0, 0); } while (0)
; #define PG8_LDA(dst, b, h) do { _Pragma("unroll") for (int m = 0; m < 4; ++m) _Pragma("unroll") for (int k = 0; k < 2; ++k) dst[m][k] = *(const PG8_LAS bf16x8*)(lds + PG8_SA(b, h) + aoff + m * 2048 + k * 1024); } while (0)
; #define PG8_LDB(dst, b, h) do { _Pragma("unroll") for (int n = 0; n < 2; ++n) _Pragma("unroll") for (int k = 0; k < 2; ++k) dst[n][k] = *(const PG8_LAS bf16x8*)(lds + PG8_SB(b, h) + boff + n * 2048 + k * 1024); } while (0)
; #define PG8_MMA(ai, bj, At, Bt) do { __builtin_amdgcn_s_setprio(1); _Pragma("unroll") for (int m = 0; m < 4; ++m) _Pragma("unroll") for (int n = 0; n < 2; ++n) _Pragma("unroll") for (int k = 0; k < 2; ++k) \
;         acc[ai][bj][m][n] = __builtin_amdgcn_mfma_f32_16x16x32_bf16(Bt[n][k], At[m][k], acc[ai][bj][m][n], 0, 0, 0); __builtin_amdgcn_s_setprio(0); } while (0)
; #define PG8_WAIT_V(n) asm volatile("s_waitcnt vmcnt(" #n ")" ::: "memory")
; #define PG8_WAIT_L(n) asm volatile("s_waitcnt lgkmcnt(" #n ")" ::: "memory")
; #define PG8_BAR __builtin_amdgcn_s_barrier()
; #define PG8_SCHED __builtin_amdgcn_sched_barrier(0)
; template <class Epi, class Sched, bool ALIGN_EPI = false, bool SP2 = false>
; __device__ __forceinline__ void gemm_phase(PG8_LAS unsigned char* lds, const Gemm g, const Sched& S, const Epi& E, const int wid) {
;     ...
;         for (int t = 0; t < nt; t += 2) {
;     ...
;             PG8_WAIT_V(8); PG8_WAIT_L(0); PG8_BAR; PG8_MMA(1, 0, At, B0); PG8_MMA(1, 1, At, B1); PG8_BAR; PG8_SCHED;
;             PG8_LDB(B0, 1, 0); PG8_LDB(B1, 1, 1); PG8_SCHED; PG8_LDA(At, 1, 0); PG8_STAGE(PG8_SA(0, 1), a2 + hstep, voffA);
;             PG8_WAIT_V(8); PG8_WAIT_L(0); PG8_BAR; PG8_MMA(0, 0, At, B0); PG8_MMA(0, 1, At, B1); PG8_BAR; PG8_SCHED;
;             PG8_LDA(At, 1, 1); PG8_STAGE(PG8_SB(1, 0), b3, voffB); PG8_STAGE(PG8_SB(1, 1), b3 + hstep, voffB); PG8_STAGE(PG8_SA(1, 0), a3, voffA);
;             PG8_WAIT_V(8); PG8_WAIT_L(0); PG8_BAR; PG8_MMA(1, 0, At, B0); PG8_MMA(1, 1, At, B1); PG8_BAR; PG8_SCHED;
	s_setprio 0
	s_add_i32 s52, 0, 0x18000
	s_add_i32 s53, 0, 0x1c000
	ds_read_b128 v[146:149], v246
	ds_read_b128 v[158:161], v246 offset:1024
	ds_read_b128 v[162:165], v246 offset:2048
	ds_read_b128 v[166:169], v246 offset:3072
	ds_read_b128 v[170:173], v248
	ds_read_b128 v[174:177], v248 offset:1024
	ds_read_b128 v[178:181], v248 offset:2048
	ds_read_b128 v[182:185], v248 offset:3072
	s_add_u32 s26, s26, 0x100000
	s_addc_u32 s27, s27, 0
	s_mov_b32 m0, s34
	ds_read_b128 v[186:189], v156 offset:32768
	ds_read_b128 v[190:193], v156 offset:33792
	ds_read_b128 v[194:197], v156 offset:34816
	ds_read_b128 v[198:201], v156 offset:35840
	ds_read_b128 v[202:205], v156 offset:36864
	ds_read_b128 v[206:209], v156 offset:37888
	ds_read_b128 v[210:213], v156 offset:38912
	ds_read_b128 v[214:217], v156 offset:39936
	global_load_lds_dwordx4 v134, s[26:27]
	s_mov_b32 m0, s35
	s_nop 0
	global_load_lds_dwordx4 v130, s[26:27]
	s_waitcnt vmcnt(8)
	s_waitcnt lgkmcnt(0)
	s_setprio 1
	s_barrier
	v_mfma_f32_16x16x32_bf16 v[124:127], v[146:149], v[186:189], v[124:127]
	v_mfma_f32_16x16x32_bf16 v[120:123], v[162:165], v[186:189], v[120:123]
	v_mfma_f32_16x16x32_bf16 v[108:111], v[146:149], v[194:197], v[108:111]
	v_mfma_f32_16x16x32_bf16 v[104:107], v[162:165], v[194:197], v[104:107]
	v_mfma_f32_16x16x32_bf16 v[92:95], v[146:149], v[202:205], v[92:95]
	v_mfma_f32_16x16x32_bf16 v[88:91], v[162:165], v[202:205], v[88:91]
	v_mfma_f32_16x16x32_bf16 v[76:79], v[146:149], v[210:213], v[76:79]
	v_mfma_f32_16x16x32_bf16 v[72:75], v[162:165], v[210:213], v[72:75]
	v_mfma_f32_16x16x32_bf16 v[124:127], v[158:161], v[190:193], v[124:127]
	v_mfma_f32_16x16x32_bf16 v[120:123], v[166:169], v[190:193], v[120:123]
	v_mfma_f32_16x16x32_bf16 v[108:111], v[158:161], v[198:201], v[108:111]
	v_mfma_f32_16x16x32_bf16 v[104:107], v[166:169], v[198:201], v[104:107]
	v_mfma_f32_16x16x32_bf16 v[92:95], v[158:161], v[206:209], v[92:95]
	v_mfma_f32_16x16x32_bf16 v[88:91], v[166:169], v[206:209], v[88:91]
	v_mfma_f32_16x16x32_bf16 v[76:79], v[158:161], v[214:217], v[76:79]
	v_mfma_f32_16x16x32_bf16 v[72:75], v[166:169], v[214:217], v[72:75]
	v_mfma_f32_16x16x32_bf16 v[116:119], v[170:173], v[186:189], v[116:119]
	v_mfma_f32_16x16x32_bf16 v[112:115], v[178:181], v[186:189], v[112:115]
	v_mfma_f32_16x16x32_bf16 v[100:103], v[170:173], v[194:197], v[100:103]
	v_mfma_f32_16x16x32_bf16 v[96:99], v[178:181], v[194:197], v[96:99]
	v_mfma_f32_16x16x32_bf16 v[84:87], v[170:173], v[202:205], v[84:87]
	v_mfma_f32_16x16x32_bf16 v[80:83], v[178:181], v[202:205], v[80:83]
	v_mfma_f32_16x16x32_bf16 v[68:71], v[170:173], v[210:213], v[68:71]
	v_mfma_f32_16x16x32_bf16 v[64:67], v[178:181], v[210:213], v[64:67]
	v_mfma_f32_16x16x32_bf16 v[116:119], v[174:177], v[190:193], v[116:119]
	v_mfma_f32_16x16x32_bf16 v[112:115], v[182:185], v[190:193], v[112:115]
	v_mfma_f32_16x16x32_bf16 v[100:103], v[174:177], v[198:201], v[100:103]
	v_mfma_f32_16x16x32_bf16 v[96:99], v[182:185], v[198:201], v[96:99]
	v_mfma_f32_16x16x32_bf16 v[84:87], v[174:177], v[206:209], v[84:87]
	v_mfma_f32_16x16x32_bf16 v[80:83], v[182:185], v[206:209], v[80:83]
	v_mfma_f32_16x16x32_bf16 v[68:71], v[174:177], v[214:217], v[68:71]
	v_mfma_f32_16x16x32_bf16 v[64:67], v[182:185], v[214:217], v[64:67]
	s_barrier
	s_setprio 0
	s_add_u32 s98, s24, 0x80
	s_addc_u32 s99, s25, 0
	s_add_u32 s100, s26, 0xfff00080
	s_addc_u32 s101, s27, -1
	s_add_i32 s26, s52, s28
	s_mov_b32 m0, s26
	ds_read_b128 v[186:189], v156 offset:49152
	ds_read_b128 v[190:193], v156 offset:50176
	ds_read_b128 v[194:197], v156 offset:51200
	ds_read_b128 v[198:201], v156 offset:52224
	ds_read_b128 v[202:205], v156 offset:53248
	ds_read_b128 v[206:209], v156 offset:54272
	ds_read_b128 v[210:213], v156 offset:55296
	ds_read_b128 v[214:217], v156 offset:56320
	global_load_lds_dwordx4 v132, s[98:99]
	s_add_i32 m0, s26, 0x2000
	s_add_u32 s24, s24, 0x100080
	s_addc_u32 s25, s25, 0
	s_add_i32 s26, s53, s28
	global_load_lds_dwordx4 v128, s[98:99]
	s_mov_b32 m0, s26
	s_nop 0
	global_load_lds_dwordx4 v132, s[24:25]
	s_add_i32 m0, s26, 0x2000
	s_nop 0
	global_load_lds_dwordx4 v128, s[24:25]
	s_mov_b32 m0, s37
	s_nop 0
	global_load_lds_dwordx4 v134, s[100:101]
	s_mov_b32 m0, s40
	s_nop 0
	global_load_lds_dwordx4 v130, s[100:101]
	s_waitcnt vmcnt(8)
	s_waitcnt lgkmcnt(0)
	s_setprio 1
	s_barrier
	v_mfma_f32_16x16x32_bf16 v[60:63], v[146:149], v[186:189], v[60:63]
	v_mfma_f32_16x16x32_bf16 v[56:59], v[162:165], v[186:189], v[56:59]
	v_mfma_f32_16x16x32_bf16 v[44:47], v[146:149], v[194:197], v[44:47]
	v_mfma_f32_16x16x32_bf16 v[40:43], v[162:165], v[194:197], v[40:43]
	v_mfma_f32_16x16x32_bf16 v[28:31], v[146:149], v[202:205], v[28:31]
	v_mfma_f32_16x16x32_bf16 v[24:27], v[162:165], v[202:205], v[24:27]
	v_mfma_f32_16x16x32_bf16 v[12:15], v[146:149], v[210:213], v[12:15]
	v_mfma_f32_16x16x32_bf16 v[8:11], v[162:165], v[210:213], v[8:11]
	v_mfma_f32_16x16x32_bf16 v[60:63], v[158:161], v[190:193], v[60:63]
	v_mfma_f32_16x16x32_bf16 v[56:59], v[166:169], v[190:193], v[56:59]
	v_mfma_f32_16x16x32_bf16 v[44:47], v[158:161], v[198:201], v[44:47]
	v_mfma_f32_16x16x32_bf16 v[40:43], v[166:169], v[198:201], v[40:43]
	v_mfma_f32_16x16x32_bf16 v[28:31], v[158:161], v[206:209], v[28:31]
	v_mfma_f32_16x16x32_bf16 v[24:27], v[166:169], v[206:209], v[24:27]
	v_mfma_f32_16x16x32_bf16 v[12:15], v[158:161], v[214:217], v[12:15]
	v_mfma_f32_16x16x32_bf16 v[8:11], v[166:169], v[214:217], v[8:11]
	v_mfma_f32_16x16x32_bf16 v[52:55], v[170:173], v[186:189], v[52:55]
	v_mfma_f32_16x16x32_bf16 v[48:51], v[178:181], v[186:189], v[48:51]
	v_mfma_f32_16x16x32_bf16 v[36:39], v[170:173], v[194:197], v[36:39]
	v_mfma_f32_16x16x32_bf16 v[32:35], v[178:181], v[194:197], v[32:35]
	v_mfma_f32_16x16x32_bf16 v[20:23], v[170:173], v[202:205], v[20:23]
	v_mfma_f32_16x16x32_bf16 v[16:19], v[178:181], v[202:205], v[16:19]
	v_mfma_f32_16x16x32_bf16 v[4:7], v[170:173], v[210:213], v[4:7]
	v_mfma_f32_16x16x32_bf16 v[0:3], v[178:181], v[210:213], v[0:3]
	v_mfma_f32_16x16x32_bf16 v[52:55], v[174:177], v[190:193], v[52:55]
	v_mfma_f32_16x16x32_bf16 v[48:51], v[182:185], v[190:193], v[48:51]
	v_mfma_f32_16x16x32_bf16 v[36:39], v[174:177], v[198:201], v[36:39]
	v_mfma_f32_16x16x32_bf16 v[32:35], v[182:185], v[198:201], v[32:35]
	v_mfma_f32_16x16x32_bf16 v[20:23], v[174:177], v[206:209], v[20:23]
	v_mfma_f32_16x16x32_bf16 v[16:19], v[182:185], v[206:209], v[16:19]
	v_mfma_f32_16x16x32_bf16 v[4:7], v[174:177], v[214:217], v[4:7]
	v_mfma_f32_16x16x32_bf16 v[0:3], v[182:185], v[214:217], v[0:3]
	s_barrier
	s_setprio 0
	s_add_i32 s51, s51, 2
	s_add_u32 s22, s22, 0x100
	s_addc_u32 s23, s23, 0
	s_add_u32 s49, s49, 0x100
	s_addc_u32 s50, s50, 0
	s_cmp_gt_u32 s51, 61
	s_cbranch_scc0 .LBB0_1764
	s_and_b64 vcc, exec, s[10:11]
	s_cbranch_vccz .LBB0_1767
	s_barrier

; #define PG8_STAGE(bufoff, gbase, voff) do { _Pragma("unroll") for (int _i = 0; _i < 2; ++_i) \
;         __builtin_amdgcn_global_load_lds((const unsigned*)((const char*)(gbase) + (voff)[_i]), (PG8_LAS unsigned*)(lds + (bufoff) + ldsw + _i * 8192), 16, 0, 0); } while (0)
; #define PG8_LDA(dst, b, h) do { _Pragma("unroll") for (int m = 0; m < 4; ++m) _Pragma("unroll") for (int k = 0; k < 2; ++k) dst[m][k] = *(const PG8_LAS bf16x8*)(lds + PG8_SA(b, h) + aoff + m * 2048 + k * 1024); } while (0)
; #define PG8_LDB(dst, b, h) do { _Pragma("unroll") for (int n = 0; n < 2; ++n) _Pragma("unroll") for (int k = 0; k < 2; ++k) dst[n][k] = *(const PG8_LAS bf16x8*)(lds + PG8_SB(b, h) + boff + n * 2048 + k * 1024); } while (0)
; #define PG8_MMA(ai, bj, At, Bt) do { __builtin_amdgcn_s_setprio(1); _Pragma("unroll") for (int m = 0; m < 4; ++m) _Pragma("unroll") for (int n = 0; n < 2; ++n) _Pragma("unroll") for (int k = 0; k < 2; ++k) \
;         acc[ai][bj][m][n] = __builtin_amdgcn_mfma_f32_16x16x32_bf16(Bt[n][k], At[m][k], acc[ai][bj][m][n], 0, 0, 0); __builtin_amdgcn_s_setprio(0); } while (0)
; #define PG8_WAIT_V(n) asm volatile("s_waitcnt vmcnt(" #n ")" ::: "memory")
; #define PG8_WAIT_L(n) asm volatile("s_waitcnt lgkmcnt(" #n ")" ::: "memory")
; #define PG8_BAR __builtin_amdgcn_s_barrier()
; #define PG8_SCHED __builtin_amdgcn_sched_barrier(0)
; template <class Epi, class Sched, bool ALIGN_EPI = false, bool SP2 = false>
; __device__ __forceinline__ void gemm_phase(PG8_LAS unsigned char* lds, const Gemm g, const Sched& S, const Epi& E, const int wid) {
;     ...
;             PG8_LDB(B0, 0, 0); PG8_LDB(B1, 0, 1); PG8_SCHED; PG8_LDA(At, 0, 0); PG8_STAGE(PG8_SA(1, 1), a1 + hstep, voffA);
;             PG8_WAIT_V(8); PG8_WAIT_L(0); PG8_BAR; PG8_MMA(0, 0, At, B0); PG8_MMA(0, 1, At, B1); PG8_BAR; PG8_SCHED;
;     ...
; #pragma unroll
;         for (int a = 0; a < 2; ++a)
; #pragma unroll
;             for (int b = 0; b < 2; ++b)
; #pragma unroll
;                 for (int m = 0; m < 4; ++m)
; #pragma unroll
;                     for (int n = 0; n < 2; ++n) acc[a][b][m][n] = (f32x4){0.f, 0.f, 0.f, 0.f};
;         cur = nxt; cA = nA; cB = nB; ++ui; nt = cur.kn;
.LBB0_2054:
	s_add_u32 s40, s14, 0x100
	v_mov_b32_e32 v0, 0
	s_addc_u32 s41, s15, 0
	s_mov_b32 s42, -2
	v_mov_b32_e32 v1, v0
	v_mov_b32_e32 v2, v0
	v_mov_b32_e32 v3, v0
	v_mov_b32_e32 v4, v0
	v_mov_b32_e32 v5, v0
	v_mov_b32_e32 v6, v0
	v_mov_b32_e32 v7, v0
	v_mov_b32_e32 v12, v0
	v_mov_b32_e32 v13, v0
	v_mov_b32_e32 v14, v0
	v_mov_b32_e32 v15, v0
	v_mov_b32_e32 v20, v0
	v_mov_b32_e32 v21, v0
	v_mov_b32_e32 v22, v0
	v_mov_b32_e32 v23, v0
	v_mov_b32_e32 v28, v0
	v_mov_b32_e32 v29, v0
	v_mov_b32_e32 v30, v0
	v_mov_b32_e32 v31, v0
	v_mov_b32_e32 v36, v0
	v_mov_b32_e32 v37, v0
	v_mov_b32_e32 v38, v0
	v_mov_b32_e32 v39, v0
	v_mov_b32_e32 v44, v0
	v_mov_b32_e32 v45, v0
	v_mov_b32_e32 v46, v0
	v_mov_b32_e32 v47, v0
	v_mov_b32_e32 v52, v0
	v_mov_b32_e32 v53, v0
	v_mov_b32_e32 v54, v0
	v_mov_b32_e32 v55, v0
	v_mov_b32_e32 v8, v0
	v_mov_b32_e32 v9, v0
	v_mov_b32_e32 v10, v0
	v_mov_b32_e32 v11, v0
	v_mov_b32_e32 v16, v0
	v_mov_b32_e32 v17, v0
	v_mov_b32_e32 v18, v0
	v_mov_b32_e32 v19, v0
	v_mov_b32_e32 v24, v0
	v_mov_b32_e32 v25, v0
	v_mov_b32_e32 v26, v0
	v_mov_b32_e32 v27, v0
	v_mov_b32_e32 v32, v0
	v_mov_b32_e32 v33, v0
	v_mov_b32_e32 v34, v0
	v_mov_b32_e32 v35, v0
	v_mov_b32_e32 v40, v0
	v_mov_b32_e32 v41, v0
	v_mov_b32_e32 v42, v0
	v_mov_b32_e32 v43, v0
	v_mov_b32_e32 v48, v0
	v_mov_b32_e32 v49, v0
	v_mov_b32_e32 v50, v0
	v_mov_b32_e32 v51, v0
	v_mov_b32_e32 v56, v0
	v_mov_b32_e32 v57, v0
	v_mov_b32_e32 v58, v0
	v_mov_b32_e32 v59, v0
	v_mov_b32_e32 v60, v0
	v_mov_b32_e32 v61, v0
	v_mov_b32_e32 v62, v0
	v_mov_b32_e32 v63, v0
	v_mov_b32_e32 v64, v0
	v_mov_b32_e32 v65, v0
	v_mov_b32_e32 v66, v0
	v_mov_b32_e32 v67, v0
	v_mov_b32_e32 v68, v0
	v_mov_b32_e32 v69, v0
	v_mov_b32_e32 v70, v0
	v_mov_b32_e32 v71, v0
	v_mov_b32_e32 v76, v0
	v_mov_b32_e32 v77, v0
	v_mov_b32_e32 v78, v0
	v_mov_b32_e32 v79, v0
	v_mov_b32_e32 v84, v0
	v_mov_b32_e32 v85, v0
	v_mov_b32_e32 v86, v0
	v_mov_b32_e32 v87, v0
	v_mov_b32_e32 v92, v0
	v_mov_b32_e32 v93, v0
	v_mov_b32_e32 v94, v0
	v_mov_b32_e32 v95, v0
	v_mov_b32_e32 v100, v0
	v_mov_b32_e32 v101, v0
	v_mov_b32_e32 v102, v0
	v_mov_b32_e32 v103, v0
	v_mov_b32_e32 v112, v0
	v_mov_b32_e32 v113, v0
	v_mov_b32_e32 v114, v0
	v_mov_b32_e32 v115, v0
	v_mov_b32_e32 v116, v0
	v_mov_b32_e32 v117, v0
	v_mov_b32_e32 v118, v0
	v_mov_b32_e32 v119, v0
	v_mov_b32_e32 v72, v0
	v_mov_b32_e32 v73, v0
	v_mov_b32_e32 v74, v0
	v_mov_b32_e32 v75, v0
	v_mov_b32_e32 v80, v0
	v_mov_b32_e32 v81, v0
	v_mov_b32_e32 v82, v0
	v_mov_b32_e32 v83, v0
	v_mov_b32_e32 v88, v0
	v_mov_b32_e32 v89, v0
	v_mov_b32_e32 v90, v0
	v_mov_b32_e32 v91, v0
	v_mov_b32_e32 v96, v0
	v_mov_b32_e32 v97, v0
	v_mov_b32_e32 v98, v0
	v_mov_b32_e32 v99, v0
	v_mov_b32_e32 v104, v0
	v_mov_b32_e32 v105, v0
	v_mov_b32_e32 v106, v0
	v_mov_b32_e32 v107, v0
	v_mov_b32_e32 v108, v0
	v_mov_b32_e32 v109, v0
	v_mov_b32_e32 v110, v0
	v_mov_b32_e32 v111, v0
	v_mov_b32_e32 v120, v0
	v_mov_b32_e32 v121, v0
	v_mov_b32_e32 v122, v0
	v_mov_b32_e32 v123, v0
	v_mov_b32_e32 v124, v0
	v_mov_b32_e32 v125, v0
	v_mov_b32_e32 v126, v0
	v_mov_b32_e32 v127, v0
	v_add_u32_e32 v246, 0x18000, v153
	v_add_u32_e32 v248, 0x1c000, v153
.LBB0_2055:
	ds_read_b128 v[144:147], v155
	ds_read_b128 v[148:151], v155 offset:1024
	ds_read_b128 v[158:161], v155 offset:2048
	ds_read_b128 v[162:165], v155 offset:3072
	ds_read_b128 v[166:169], v156
	ds_read_b128 v[170:173], v156 offset:1024
	ds_read_b128 v[174:177], v156 offset:2048
	ds_read_b128 v[178:181], v156 offset:3072
	s_add_u32 s14, s12, 0x100
	s_addc_u32 s15, s13, 0
	s_cmpk_eq_i32 s42, 0xa8
	s_cselect_b32 s19, s3, s15
	s_cselect_b32 s18, s2, s14
	s_cselect_b32 s17, s11, s41
	s_cselect_b32 s16, s10, s40
	s_add_i32 m0, s24, 0xc000
	ds_read_b128 v[182:185], v157
	ds_read_b128 v[186:189], v157 offset:1024
	ds_read_b128 v[190:193], v157 offset:2048
	ds_read_b128 v[194:197], v157 offset:3072
	ds_read_b128 v[198:201], v157 offset:4096
	ds_read_b128 v[202:205], v157 offset:5120
	ds_read_b128 v[206:209], v157 offset:6144
	ds_read_b128 v[210:213], v157 offset:7168
	global_load_lds_dwordx4 v136, s[12:13]
	s_add_i32 m0, s24, 0xe000
	s_nop 0
	global_load_lds_dwordx4 v138, s[12:13]
	s_waitcnt vmcnt(8)
	s_waitcnt lgkmcnt(0)
	s_setprio 1
	s_barrier
	v_mfma_f32_16x16x32_bf16 v[124:127], v[144:147], v[182:185], v[124:127]
	v_mfma_f32_16x16x32_bf16 v[120:123], v[158:161], v[182:185], v[120:123]
	v_mfma_f32_16x16x32_bf16 v[108:111], v[144:147], v[190:193], v[108:111]
	v_mfma_f32_16x16x32_bf16 v[104:107], v[158:161], v[190:193], v[104:107]
	v_mfma_f32_16x16x32_bf16 v[96:99], v[144:147], v[198:201], v[96:99]
	v_mfma_f32_16x16x32_bf16 v[88:91], v[158:161], v[198:201], v[88:91]
	v_mfma_f32_16x16x32_bf16 v[80:83], v[144:147], v[206:209], v[80:83]
	v_mfma_f32_16x16x32_bf16 v[72:75], v[158:161], v[206:209], v[72:75]
	v_mfma_f32_16x16x32_bf16 v[124:127], v[148:151], v[186:189], v[124:127]
	v_mfma_f32_16x16x32_bf16 v[120:123], v[162:165], v[186:189], v[120:123]
	v_mfma_f32_16x16x32_bf16 v[108:111], v[148:151], v[194:197], v[108:111]
	v_mfma_f32_16x16x32_bf16 v[104:107], v[162:165], v[194:197], v[104:107]
	v_mfma_f32_16x16x32_bf16 v[96:99], v[148:151], v[202:205], v[96:99]
	v_mfma_f32_16x16x32_bf16 v[88:91], v[162:165], v[202:205], v[88:91]
	v_mfma_f32_16x16x32_bf16 v[80:83], v[148:151], v[210:213], v[80:83]
	v_mfma_f32_16x16x32_bf16 v[72:75], v[162:165], v[210:213], v[72:75]
	v_mfma_f32_16x16x32_bf16 v[116:119], v[166:169], v[182:185], v[116:119]
	v_mfma_f32_16x16x32_bf16 v[112:115], v[174:177], v[182:185], v[112:115]
	v_mfma_f32_16x16x32_bf16 v[100:103], v[166:169], v[190:193], v[100:103]
	v_mfma_f32_16x16x32_bf16 v[92:95], v[174:177], v[190:193], v[92:95]
	v_mfma_f32_16x16x32_bf16 v[84:87], v[166:169], v[198:201], v[84:87]
	v_mfma_f32_16x16x32_bf16 v[76:79], v[174:177], v[198:201], v[76:79]
	v_mfma_f32_16x16x32_bf16 v[68:71], v[166:169], v[206:209], v[68:71]
	v_mfma_f32_16x16x32_bf16 v[64:67], v[174:177], v[206:209], v[64:67]
	v_mfma_f32_16x16x32_bf16 v[116:119], v[170:173], v[186:189], v[116:119]
	v_mfma_f32_16x16x32_bf16 v[112:115], v[178:181], v[186:189], v[112:115]
	v_mfma_f32_16x16x32_bf16 v[100:103], v[170:173], v[194:197], v[100:103]
	v_mfma_f32_16x16x32_bf16 v[92:95], v[178:181], v[194:197], v[92:95]
	v_mfma_f32_16x16x32_bf16 v[84:87], v[170:173], v[202:205], v[84:87]
	v_mfma_f32_16x16x32_bf16 v[76:79], v[178:181], v[202:205], v[76:79]
	v_mfma_f32_16x16x32_bf16 v[68:71], v[170:173], v[210:213], v[68:71]
	v_mfma_f32_16x16x32_bf16 v[64:67], v[178:181], v[210:213], v[64:67]
	s_barrier
; #define PG8_STAGE(bufoff, gbase, voff) do { _Pragma("unroll") for (int _i = 0; _i < 2; ++_i) \
;         __builtin_amdgcn_global_load_lds((const unsigned*)((const char*)(gbase) + (voff)[_i]), (PG8_LAS unsigned*)(lds + (bufoff) + ldsw + _i * 8192), 16, 0, 0); } while (0)
; #define PG8_LDA(dst, b, h) do { _Pragma("unroll") for (int m = 0; m < 4; ++m) _Pragma("unroll") for (int k = 0; k < 2; ++k) dst[m][k] = *(const PG8_LAS bf16x8*)(lds + PG8_SA(b, h) + aoff + m * 2048 + k * 1024); } while (0)
; #define PG8_LDB(dst, b, h) do { _Pragma("unroll") for (int n = 0; n < 2; ++n) _Pragma("unroll") for (int k = 0; k < 2; ++k) dst[n][k] = *(const PG8_LAS bf16x8*)(lds + PG8_SB(b, h) + boff + n * 2048 + k * 1024); } while (0)
; #define PG8_MMA(ai, bj, At, Bt) do { __builtin_amdgcn_s_setprio(1); _Pragma("unroll") for (int m = 0; m < 4; ++m) _Pragma("unroll") for (int n = 0; n < 2; ++n) _Pragma("unroll") for (int k = 0; k < 2; ++k) \
;         acc[ai][bj][m][n] = __builtin_amdgcn_mfma_f32_16x16x32_bf16(Bt[n][k], At[m][k], acc[ai][bj][m][n], 0, 0, 0); __builtin_amdgcn_s_setprio(0); } while (0)
; #define PG8_WAIT_V(n) asm volatile("s_waitcnt vmcnt(" #n ")" ::: "memory")
; #define PG8_WAIT_L(n) asm volatile("s_waitcnt lgkmcnt(" #n ")" ::: "memory")
; #define PG8_BAR __builtin_amdgcn_s_barrier()
; #define PG8_SCHED __builtin_amdgcn_sched_barrier(0)
; template <class Epi, class Sched, bool ALIGN_EPI = false, bool SP2 = false>
; __device__ __forceinline__ void gemm_phase(PG8_LAS unsigned char* lds, const Gemm g, const Sched& S, const Epi& E, const int wid) {
;     ...
;             PG8_WAIT_V(8); PG8_WAIT_L(0); PG8_BAR; PG8_MMA(0, 0, At, B0); PG8_MMA(0, 1, At, B1); PG8_BAR; PG8_SCHED;
;             PG8_LDA(At, 0, 1); PG8_STAGE(PG8_SB(0, 0), b2, voffB); PG8_STAGE(PG8_SB(0, 1), b2 + hstep, voffB); PG8_STAGE(PG8_SA(0, 0), a2, voffA);
;             PG8_WAIT_V(8); PG8_WAIT_L(0); PG8_BAR; PG8_MMA(1, 0, At, B0); PG8_MMA(1, 1, At, B1); PG8_BAR; PG8_SCHED;
;             PG8_LDB(B0, 1, 0); PG8_LDB(B1, 1, 1); PG8_SCHED; PG8_LDA(At, 1, 0); PG8_STAGE(PG8_SA(0, 1), a2 + hstep, voffA);
;             PG8_WAIT_V(8); PG8_WAIT_L(0); PG8_BAR; PG8_MMA(0, 0, At, B0); PG8_MMA(0, 1, At, B1); PG8_BAR; PG8_SCHED;
	s_setprio 0
	s_add_i32 s12, s34, s23
	s_mov_b32 m0, s12
	ds_read_b128 v[182:185], v157 offset:16384
	ds_read_b128 v[186:189], v157 offset:17408
	ds_read_b128 v[190:193], v157 offset:18432
	ds_read_b128 v[194:197], v157 offset:19456
	ds_read_b128 v[198:201], v157 offset:20480
	ds_read_b128 v[202:205], v157 offset:21504
	ds_read_b128 v[206:209], v157 offset:22528
	ds_read_b128 v[210:213], v157 offset:23552
	global_load_lds_dwordx4 v130, s[16:17]
	s_add_i32 m0, s12, 0x2000
	s_add_u32 s12, s16, 0x2b0000
	s_addc_u32 s13, s17, 0
	s_add_i32 s43, s35, s23
	global_load_lds_dwordx4 v134, s[16:17]
	s_mov_b32 m0, s43
	global_load_lds_dwordx4 v130, s[12:13]
	s_add_i32 m0, s43, 0x2000
	s_nop 0
	global_load_lds_dwordx4 v134, s[12:13]
	s_mov_b32 m0, s24
	s_nop 0
	global_load_lds_dwordx4 v128, s[18:19]
	s_mov_b32 m0, s25
	s_nop 0
	global_load_lds_dwordx4 v132, s[18:19]
	s_waitcnt vmcnt(8)
	s_waitcnt lgkmcnt(0)
	s_setprio 1
	s_barrier
	v_mfma_f32_16x16x32_bf16 v[60:63], v[144:147], v[182:185], v[60:63]
	v_mfma_f32_16x16x32_bf16 v[56:59], v[158:161], v[182:185], v[56:59]
	v_mfma_f32_16x16x32_bf16 v[48:51], v[144:147], v[190:193], v[48:51]
	v_mfma_f32_16x16x32_bf16 v[40:43], v[158:161], v[190:193], v[40:43]
	v_mfma_f32_16x16x32_bf16 v[32:35], v[144:147], v[198:201], v[32:35]
	v_mfma_f32_16x16x32_bf16 v[24:27], v[158:161], v[198:201], v[24:27]
	v_mfma_f32_16x16x32_bf16 v[16:19], v[144:147], v[206:209], v[16:19]
	v_mfma_f32_16x16x32_bf16 v[8:11], v[158:161], v[206:209], v[8:11]
	v_mfma_f32_16x16x32_bf16 v[60:63], v[148:151], v[186:189], v[60:63]
	v_mfma_f32_16x16x32_bf16 v[56:59], v[162:165], v[186:189], v[56:59]
	v_mfma_f32_16x16x32_bf16 v[48:51], v[148:151], v[194:197], v[48:51]
	v_mfma_f32_16x16x32_bf16 v[40:43], v[162:165], v[194:197], v[40:43]
	v_mfma_f32_16x16x32_bf16 v[32:35], v[148:151], v[202:205], v[32:35]
	v_mfma_f32_16x16x32_bf16 v[24:27], v[162:165], v[202:205], v[24:27]
	v_mfma_f32_16x16x32_bf16 v[16:19], v[148:151], v[210:213], v[16:19]
	v_mfma_f32_16x16x32_bf16 v[8:11], v[162:165], v[210:213], v[8:11]
	v_mfma_f32_16x16x32_bf16 v[52:55], v[166:169], v[182:185], v[52:55]
	v_mfma_f32_16x16x32_bf16 v[44:47], v[174:177], v[182:185], v[44:47]
	v_mfma_f32_16x16x32_bf16 v[36:39], v[166:169], v[190:193], v[36:39]
	v_mfma_f32_16x16x32_bf16 v[28:31], v[174:177], v[190:193], v[28:31]
	v_mfma_f32_16x16x32_bf16 v[20:23], v[166:169], v[198:201], v[20:23]
	v_mfma_f32_16x16x32_bf16 v[12:15], v[174:177], v[198:201], v[12:15]
	v_mfma_f32_16x16x32_bf16 v[4:7], v[166:169], v[206:209], v[4:7]
	v_mfma_f32_16x16x32_bf16 v[0:3], v[174:177], v[206:209], v[0:3]
	v_mfma_f32_16x16x32_bf16 v[52:55], v[170:173], v[186:189], v[52:55]
	v_mfma_f32_16x16x32_bf16 v[44:47], v[178:181], v[186:189], v[44:47]
	v_mfma_f32_16x16x32_bf16 v[36:39], v[170:173], v[194:197], v[36:39]
	v_mfma_f32_16x16x32_bf16 v[28:31], v[178:181], v[194:197], v[28:31]
	v_mfma_f32_16x16x32_bf16 v[20:23], v[170:173], v[202:205], v[20:23]
	v_mfma_f32_16x16x32_bf16 v[12:15], v[178:181], v[202:205], v[12:15]
	v_mfma_f32_16x16x32_bf16 v[4:7], v[170:173], v[210:213], v[4:7]
	v_mfma_f32_16x16x32_bf16 v[0:3], v[178:181], v[210:213], v[0:3]
	s_barrier
	s_setprio 0
	s_add_i32 s43, 0, 0x18000
	s_add_i32 s44, 0, 0x1c000
	ds_read_b128 v[144:147], v246
	ds_read_b128 v[148:151], v246 offset:1024
	ds_read_b128 v[158:161], v246 offset:2048
	ds_read_b128 v[162:165], v246 offset:3072
	ds_read_b128 v[166:169], v248
	ds_read_b128 v[170:173], v248 offset:1024
	ds_read_b128 v[174:177], v248 offset:2048
	ds_read_b128 v[178:181], v248 offset:3072
	s_add_u32 s12, s18, 0x2b0000
	s_addc_u32 s13, s19, 0
	s_mov_b32 m0, s26
	ds_read_b128 v[182:185], v157 offset:32768
	ds_read_b128 v[186:189], v157 offset:33792
	ds_read_b128 v[190:193], v157 offset:34816
	ds_read_b128 v[194:197], v157 offset:35840
	ds_read_b128 v[198:201], v157 offset:36864
	ds_read_b128 v[202:205], v157 offset:37888
	ds_read_b128 v[206:209], v157 offset:38912
	ds_read_b128 v[210:213], v157 offset:39936
	global_load_lds_dwordx4 v128, s[12:13]
	s_mov_b32 m0, s27
	s_nop 0
	global_load_lds_dwordx4 v132, s[12:13]
	s_waitcnt vmcnt(8)
	s_waitcnt lgkmcnt(0)
	s_setprio 1
	s_barrier
; #define PG8_STAGE(bufoff, gbase, voff) do { _Pragma("unroll") for (int _i = 0; _i < 2; ++_i) \
;         __builtin_amdgcn_global_load_lds((const unsigned*)((const char*)(gbase) + (voff)[_i]), (PG8_LAS unsigned*)(lds + (bufoff) + ldsw + _i * 8192), 16, 0, 0); } while (0)
; #define PG8_LDA(dst, b, h) do { _Pragma("unroll") for (int m = 0; m < 4; ++m) _Pragma("unroll") for (int k = 0; k < 2; ++k) dst[m][k] = *(const PG8_LAS bf16x8*)(lds + PG8_SA(b, h) + aoff + m * 2048 + k * 1024); } while (0)
; #define PG8_MMA(ai, bj, At, Bt) do { __builtin_amdgcn_s_setprio(1); _Pragma("unroll") for (int m = 0; m < 4; ++m) _Pragma("unroll") for (int n = 0; n < 2; ++n) _Pragma("unroll") for (int k = 0; k < 2; ++k) \
;         acc[ai][bj][m][n] = __builtin_amdgcn_mfma_f32_16x16x32_bf16(Bt[n][k], At[m][k], acc[ai][bj][m][n], 0, 0, 0); __builtin_amdgcn_s_setprio(0); } while (0)
; #define PG8_WAIT_V(n) asm volatile("s_waitcnt vmcnt(" #n ")" ::: "memory")
; #define PG8_WAIT_L(n) asm volatile("s_waitcnt lgkmcnt(" #n ")" ::: "memory")
; #define PG8_BAR __builtin_amdgcn_s_barrier()
; #define PG8_SCHED __builtin_amdgcn_sched_barrier(0)
; template <class Epi, class Sched, bool ALIGN_EPI = false, bool SP2 = false>
; __device__ __forceinline__ void gemm_phase(PG8_LAS unsigned char* lds, const Gemm g, const Sched& S, const Epi& E, const int wid) {
;     ...
;         for (int t = 0; t < nt; t += 2) {
;     ...
;             PG8_WAIT_V(8); PG8_WAIT_L(0); PG8_BAR; PG8_MMA(0, 0, At, B0); PG8_MMA(0, 1, At, B1); PG8_BAR; PG8_SCHED;
;             PG8_LDA(At, 1, 1); PG8_STAGE(PG8_SB(1, 0), b3, voffB); PG8_STAGE(PG8_SB(1, 1), b3 + hstep, voffB); PG8_STAGE(PG8_SA(1, 0), a3, voffA);
;             PG8_WAIT_V(8); PG8_WAIT_L(0); PG8_BAR; PG8_MMA(1, 0, At, B0); PG8_MMA(1, 1, At, B1); PG8_BAR; PG8_SCHED;
	v_mfma_f32_16x16x32_bf16 v[124:127], v[144:147], v[182:185], v[124:127]
	v_mfma_f32_16x16x32_bf16 v[120:123], v[158:161], v[182:185], v[120:123]
	v_mfma_f32_16x16x32_bf16 v[108:111], v[144:147], v[190:193], v[108:111]
	v_mfma_f32_16x16x32_bf16 v[104:107], v[158:161], v[190:193], v[104:107]
	v_mfma_f32_16x16x32_bf16 v[96:99], v[144:147], v[198:201], v[96:99]
	v_mfma_f32_16x16x32_bf16 v[88:91], v[158:161], v[198:201], v[88:91]
	v_mfma_f32_16x16x32_bf16 v[80:83], v[144:147], v[206:209], v[80:83]
	v_mfma_f32_16x16x32_bf16 v[72:75], v[158:161], v[206:209], v[72:75]
	v_mfma_f32_16x16x32_bf16 v[124:127], v[148:151], v[186:189], v[124:127]
	v_mfma_f32_16x16x32_bf16 v[120:123], v[162:165], v[186:189], v[120:123]
	v_mfma_f32_16x16x32_bf16 v[108:111], v[148:151], v[194:197], v[108:111]
	v_mfma_f32_16x16x32_bf16 v[104:107], v[162:165], v[194:197], v[104:107]
	v_mfma_f32_16x16x32_bf16 v[96:99], v[148:151], v[202:205], v[96:99]
	v_mfma_f32_16x16x32_bf16 v[88:91], v[162:165], v[202:205], v[88:91]
	v_mfma_f32_16x16x32_bf16 v[80:83], v[148:151], v[210:213], v[80:83]
	v_mfma_f32_16x16x32_bf16 v[72:75], v[162:165], v[210:213], v[72:75]
	v_mfma_f32_16x16x32_bf16 v[116:119], v[166:169], v[182:185], v[116:119]
	v_mfma_f32_16x16x32_bf16 v[112:115], v[174:177], v[182:185], v[112:115]
	v_mfma_f32_16x16x32_bf16 v[100:103], v[166:169], v[190:193], v[100:103]
	v_mfma_f32_16x16x32_bf16 v[92:95], v[174:177], v[190:193], v[92:95]
	v_mfma_f32_16x16x32_bf16 v[84:87], v[166:169], v[198:201], v[84:87]
	v_mfma_f32_16x16x32_bf16 v[76:79], v[174:177], v[198:201], v[76:79]
	v_mfma_f32_16x16x32_bf16 v[68:71], v[166:169], v[206:209], v[68:71]
	v_mfma_f32_16x16x32_bf16 v[64:67], v[174:177], v[206:209], v[64:67]
	v_mfma_f32_16x16x32_bf16 v[116:119], v[170:173], v[186:189], v[116:119]
	v_mfma_f32_16x16x32_bf16 v[112:115], v[178:181], v[186:189], v[112:115]
	v_mfma_f32_16x16x32_bf16 v[100:103], v[170:173], v[194:197], v[100:103]
	v_mfma_f32_16x16x32_bf16 v[92:95], v[178:181], v[194:197], v[92:95]
	v_mfma_f32_16x16x32_bf16 v[84:87], v[170:173], v[202:205], v[84:87]
	v_mfma_f32_16x16x32_bf16 v[76:79], v[178:181], v[202:205], v[76:79]
	v_mfma_f32_16x16x32_bf16 v[68:71], v[170:173], v[210:213], v[68:71]
	v_mfma_f32_16x16x32_bf16 v[64:67], v[178:181], v[210:213], v[64:67]
	s_barrier
	s_setprio 0
	s_add_u32 s98, s16, 0x80
	s_addc_u32 s99, s17, 0
	s_add_u32 s100, s18, 0x80
	s_addc_u32 s101, s19, 0
	s_add_i32 s12, s43, s23
	s_mov_b32 m0, s12
	ds_read_b128 v[182:185], v157 offset:49152
	ds_read_b128 v[186:189], v157 offset:50176
	ds_read_b128 v[190:193], v157 offset:51200
	ds_read_b128 v[194:197], v157 offset:52224
	ds_read_b128 v[198:201], v157 offset:53248
	ds_read_b128 v[202:205], v157 offset:54272
	ds_read_b128 v[206:209], v157 offset:55296
	ds_read_b128 v[210:213], v157 offset:56320
	global_load_lds_dwordx4 v130, s[98:99]
	s_add_i32 m0, s12, 0x2000
	s_add_u32 s12, s16, 0x2b0080
	s_addc_u32 s13, s17, 0
	s_add_i32 s16, s44, s23
	global_load_lds_dwordx4 v134, s[98:99]
	s_mov_b32 m0, s16
	s_nop 0
	global_load_lds_dwordx4 v130, s[12:13]
	s_add_i32 m0, s16, 0x2000
	s_nop 0
	global_load_lds_dwordx4 v134, s[12:13]
	s_mov_b32 m0, s29
	s_nop 0
	global_load_lds_dwordx4 v128, s[100:101]
	s_mov_b32 m0, s30
	s_nop 0
	global_load_lds_dwordx4 v132, s[100:101]
	s_waitcnt vmcnt(8)
	s_waitcnt lgkmcnt(0)
	s_setprio 1
	s_barrier
	v_mfma_f32_16x16x32_bf16 v[60:63], v[144:147], v[182:185], v[60:63]
	v_mfma_f32_16x16x32_bf16 v[56:59], v[158:161], v[182:185], v[56:59]
	v_mfma_f32_16x16x32_bf16 v[48:51], v[144:147], v[190:193], v[48:51]
	v_mfma_f32_16x16x32_bf16 v[40:43], v[158:161], v[190:193], v[40:43]
	v_mfma_f32_16x16x32_bf16 v[32:35], v[144:147], v[198:201], v[32:35]
	v_mfma_f32_16x16x32_bf16 v[24:27], v[158:161], v[198:201], v[24:27]
	v_mfma_f32_16x16x32_bf16 v[16:19], v[144:147], v[206:209], v[16:19]
	v_mfma_f32_16x16x32_bf16 v[8:11], v[158:161], v[206:209], v[8:11]
	v_mfma_f32_16x16x32_bf16 v[60:63], v[148:151], v[186:189], v[60:63]
	v_mfma_f32_16x16x32_bf16 v[56:59], v[162:165], v[186:189], v[56:59]
	v_mfma_f32_16x16x32_bf16 v[48:51], v[148:151], v[194:197], v[48:51]
	v_mfma_f32_16x16x32_bf16 v[40:43], v[162:165], v[194:197], v[40:43]
	v_mfma_f32_16x16x32_bf16 v[32:35], v[148:151], v[202:205], v[32:35]
	v_mfma_f32_16x16x32_bf16 v[24:27], v[162:165], v[202:205], v[24:27]
	v_mfma_f32_16x16x32_bf16 v[16:19], v[148:151], v[210:213], v[16:19]
	v_mfma_f32_16x16x32_bf16 v[8:11], v[162:165], v[210:213], v[8:11]
	v_mfma_f32_16x16x32_bf16 v[52:55], v[166:169], v[182:185], v[52:55]
	v_mfma_f32_16x16x32_bf16 v[44:47], v[174:177], v[182:185], v[44:47]
	v_mfma_f32_16x16x32_bf16 v[36:39], v[166:169], v[190:193], v[36:39]
	v_mfma_f32_16x16x32_bf16 v[28:31], v[174:177], v[190:193], v[28:31]
	v_mfma_f32_16x16x32_bf16 v[20:23], v[166:169], v[198:201], v[20:23]
	v_mfma_f32_16x16x32_bf16 v[12:15], v[174:177], v[198:201], v[12:15]
	v_mfma_f32_16x16x32_bf16 v[4:7], v[166:169], v[206:209], v[4:7]
	v_mfma_f32_16x16x32_bf16 v[0:3], v[174:177], v[206:209], v[0:3]
	v_mfma_f32_16x16x32_bf16 v[52:55], v[170:173], v[186:189], v[52:55]
	v_mfma_f32_16x16x32_bf16 v[44:47], v[178:181], v[186:189], v[44:47]
	v_mfma_f32_16x16x32_bf16 v[36:39], v[170:173], v[194:197], v[36:39]
	v_mfma_f32_16x16x32_bf16 v[28:31], v[178:181], v[194:197], v[28:31]
	v_mfma_f32_16x16x32_bf16 v[20:23], v[170:173], v[202:205], v[20:23]
	v_mfma_f32_16x16x32_bf16 v[12:15], v[178:181], v[202:205], v[12:15]
	v_mfma_f32_16x16x32_bf16 v[4:7], v[170:173], v[210:213], v[4:7]
	v_mfma_f32_16x16x32_bf16 v[0:3], v[178:181], v[210:213], v[0:3]
	s_barrier
	s_setprio 0
	s_add_i32 s42, s42, 2
	s_add_u32 s40, s40, 0x100
	s_addc_u32 s41, s41, 0
	s_cmpk_gt_u32 s42, 0xa9
	s_mov_b64 s[12:13], s[14:15]
	s_cbranch_scc0 .LBB0_2055
	s_and_b64 vcc, exec, s[8:9]
	s_cbranch_vccz .LBB0_2058
	s_barrier

; __global__ void __launch_bounds__(NTHREADS, 2) hybrid_fwd(Args args) {
;     extern __shared__ __attribute__((aligned(16))) unsigned char lds_raw[];
	.amdhsa_kernel _Z10hybrid_fwd4Args
		.amdhsa_group_segment_fixed_size 0
		.amdhsa_private_segment_fixed_size 0
		.amdhsa_kernarg_size 464
		.amdhsa_user_sgpr_count 2
		.amdhsa_user_sgpr_dispatch_ptr 0
		.amdhsa_user_sgpr_queue_ptr 0
		.amdhsa_user_sgpr_kernarg_segment_ptr 1
		.amdhsa_user_sgpr_dispatch_id 0
		.amdhsa_user_sgpr_kernarg_preload_length 0
		.amdhsa_user_sgpr_kernarg_preload_offset 0
		.amdhsa_user_sgpr_private_segment_size 0
		.amdhsa_uses_dynamic_stack 0
		.amdhsa_enable_private_segment 0
		.amdhsa_system_sgpr_workgroup_id_x 1
		.amdhsa_system_sgpr_workgroup_id_y 0
		.amdhsa_system_sgpr_workgroup_id_z 0
		.amdhsa_system_sgpr_workgroup_info 0
		.amdhsa_system_vgpr_workitem_id 0
		.amdhsa_next_free_vgpr 256
		.amdhsa_next_free_sgpr 102
		.amdhsa_accum_offset 256
		.amdhsa_reserve_vcc 1
		.amdhsa_float_round_mode_32 0
		.amdhsa_float_round_mode_16_64 0
		.amdhsa_float_denorm_mode_32 3
		.amdhsa_float_denorm_mode_16_64 3
		.amdhsa_dx10_clamp 1
		.amdhsa_ieee_mode 1
		.amdhsa_fp16_overflow 0
		.amdhsa_tg_split 0
		.amdhsa_exception_fp_ieee_invalid_op 0
		.amdhsa_exception_fp_denorm_src 0
		.amdhsa_exception_fp_ieee_div_zero 0
		.amdhsa_exception_fp_ieee_overflow 0
		.amdhsa_exception_fp_ieee_underflow 0
		.amdhsa_exception_fp_ieee_inexact 0
		.amdhsa_exception_int_div_zero 0
	.end_amdhsa_kernel

; __global__ void __launch_bounds__(NTHREADS, 2) hybrid_fwd(Args args) {
;     extern __shared__ __attribute__((aligned(16))) unsigned char lds_raw[];
amdhsa.kernels:
  - .agpr_count:     0
    .args:
      - .offset:         0
        .size:           208
        .value_kind:     by_value
      - .offset:         208
        .size:           4
        .value_kind:     hidden_block_count_x
      - .offset:         212
        .size:           4
        .value_kind:     hidden_block_count_y
      - .offset:         216
        .size:           4
        .value_kind:     hidden_block_count_z
      - .offset:         220
        .size:           2
        .value_kind:     hidden_group_size_x
      - .offset:         222
        .size:           2
        .value_kind:     hidden_group_size_y
      - .offset:         224
        .size:           2
        .value_kind:     hidden_group_size_z
      - .offset:         226
        .size:           2
        .value_kind:     hidden_remainder_x
      - .offset:         228
        .size:           2
        .value_kind:     hidden_remainder_y
      - .offset:         230
        .size:           2
        .value_kind:     hidden_remainder_z
      - .offset:         248
        .size:           8
        .value_kind:     hidden_global_offset_x
      - .offset:         256
        .size:           8
        .value_kind:     hidden_global_offset_y
      - .offset:         264
        .size:           8
        .value_kind:     hidden_global_offset_z
      - .offset:         272
        .size:           2
        .value_kind:     hidden_grid_dims
      - .offset:         328
        .size:           4
        .value_kind:     hidden_dynamic_lds_size
    .group_segment_fixed_size: 0
    .kernarg_segment_align: 8
    .kernarg_segment_size: 464
    .language:       OpenCL C
    .language_version:
      - 2
      - 0
    .max_flat_workgroup_size: 512
    .name:           _Z10hybrid_fwd4Args
    .private_segment_fixed_size: 0
    .sgpr_count:     108
    .sgpr_spill_count: 94
    .symbol:         _Z10hybrid_fwd4Args.kd
    .uniform_work_group_size: 1
    .uses_dynamic_stack: false
    .vgpr_count:     256
    .vgpr_spill_count: 0
    .wavefront_size: 64
